# v82 + operand-sharing MFMA order recomputed across the merged 32-MFMA blocks (dependent pairs kept 6 apart)
# baseline (speedup 1.0000x reference)
; #define PG8_STAGE(bufoff, gbase, voff) do { _Pragma("unroll") for (int _i = 0; _i < 2; ++_i) \
;         __builtin_amdgcn_global_load_lds((const unsigned*)((const char*)(gbase) + (voff)[_i]), (PG8_LAS unsigned*)(lds + (bufoff) + ldsw + _i * 8192), 16, 0, 0); } while (0)
; #define PG8_LDA(dst, b, h) do { _Pragma("unroll") for (int m = 0; m < 4; ++m) _Pragma("unroll") for (int k = 0; k < 2; ++k) dst[m][k] = *(const PG8_LAS bf16x8*)(lds + PG8_SA(b, h) + aoff + m * 2048 + k * 1024); } while (0)
; #define PG8_LDB(dst, b, h) do { _Pragma("unroll") for (int n = 0; n < 2; ++n) _Pragma("unroll") for (int k = 0; k < 2; ++k) dst[n][k] = *(const PG8_LAS bf16x8*)(lds + PG8_SB(b, h) + boff + n * 2048 + k * 1024); } while (0)
; #define PG8_MMA(ai, bj, At, Bt) do { __builtin_amdgcn_s_setprio(1); _Pragma("unroll") for (int m = 0; m < 4; ++m) _Pragma("unroll") for (int n = 0; n < 2; ++n) _Pragma("unroll") for (int k = 0; k < 2; ++k) \
;         acc[ai][bj][m][n] = mma16<Epi::I8>(Bt[n][k], At[m][k], acc[ai][bj][m][n]); __builtin_amdgcn_s_setprio(0); } while (0)
; #define PG8_WAIT_V(n) asm volatile("s_waitcnt vmcnt(" #n ")" ::: "memory")
; #define PG8_WAIT_L(n) asm volatile("s_waitcnt lgkmcnt(" #n ")" ::: "memory")
; #define PG8_BAR __builtin_amdgcn_s_barrier()
; #define PG8_SCHED __builtin_amdgcn_sched_barrier(0)
; template <class Epi, class Sched, bool ALIGN_EPI = false, bool SP2 = false>
; __device__ __forceinline__ void gemm_phase(PG8_LAS unsigned char* lds, const Gemm g, const Sched& S, const Epi& E) {
;     ...
;             PG8_LDB(B0, 0, 0); PG8_LDB(B1, 0, 1); PG8_SCHED; PG8_LDA(At, 0, 0); PG8_STAGE(PG8_SA(1, 1), a1 + hstep, voffA);
;             PG8_WAIT_V(8); PG8_WAIT_L(0); PG8_BAR; PG8_MMA(0, 0, At, B0); PG8_MMA(0, 1, At, B1); PG8_BAR; PG8_SCHED;
;             PG8_LDA(At, 0, 1); PG8_STAGE(PG8_SB(0, 0), b2, voffB); PG8_STAGE(PG8_SB(0, 1), b2 + hstep, voffB); PG8_STAGE(PG8_SA(0, 0), a2, voffA);
;             PG8_WAIT_V(8); PG8_WAIT_L(0); PG8_BAR; PG8_MMA(1, 0, At, B0); PG8_MMA(1, 1, At, B1); PG8_BAR; PG8_SCHED;
.Lpeel80:
	s_add_u32 s8, s0, 0x100
	s_addc_u32 s9, s1, 0
	s_add_i32 vcc_hi, 0, 0x10000
	s_cmp_eq_u32 vcc_lo, 12
	s_cselect_b32 s13, s66, s9
	s_cselect_b32 s12, s67, s8
	s_cselect_b32 s7, s82, s97
	s_cselect_b32 s6, s83, s96
	s_add_i32 s4, 0, 0x14000
	v_add_u32_e32 v38, vcc_hi, v242
	v_add_u32_e32 v158, s4, v242
	ds_read_b128 v[18:21], v38
	ds_read_b128 v[22:25], v38 offset:1024
	ds_read_b128 v[34:37], v38 offset:2048
	ds_read_b128 v[38:41], v38 offset:3072
	ds_read_b128 v[130:133], v158
	ds_read_b128 v[134:137], v158 offset:1024
	ds_read_b128 v[154:157], v158 offset:2048
	ds_read_b128 v[158:161], v158 offset:3072
	s_add_i32 m0, s11, 0xc000
	ds_read_b128 v[162:165], v243
	ds_read_b128 v[166:169], v243 offset:1024
	ds_read_b128 v[170:173], v243 offset:2048
	ds_read_b128 v[174:177], v243 offset:3072
	ds_read_b128 v[178:181], v243 offset:4096
	ds_read_b128 v[182:185], v243 offset:5120
	ds_read_b128 v[186:189], v243 offset:6144
	ds_read_b128 v[190:193], v243 offset:7168
	global_load_lds_dwordx4 v216, s[0:1]
	s_add_i32 m0, s11, 0xe000
	s_nop 0
	global_load_lds_dwordx4 v218, s[0:1]
	s_waitcnt vmcnt(8)
	s_waitcnt lgkmcnt(0)
	s_barrier
	s_waitcnt lgkmcnt(0)
	v_mfma_i32_16x16x64_i8 v[150:153], v[18:21], v[162:165], 0
	v_mfma_i32_16x16x64_i8 v[146:149], v[34:37], v[162:165], 0
	v_mfma_i32_16x16x64_i8 v[110:113], v[34:37], v[170:173], 0
	v_mfma_i32_16x16x64_i8 v[118:121], v[18:21], v[170:173], 0
	v_mfma_i32_16x16x64_i8 v[54:57], v[18:21], v[178:181], 0
	v_mfma_i32_16x16x64_i8 v[30:33], v[34:37], v[178:181], 0
	v_mfma_i32_16x16x64_i8 v[58:61], v[34:37], v[186:189], 0
	v_mfma_i32_16x16x64_i8 v[94:97], v[18:21], v[186:189], 0
	v_mfma_i32_16x16x64_i8 v[62:65], v[154:157], v[186:189], 0
	v_mfma_i32_16x16x64_i8 v[138:141], v[154:157], v[162:165], 0
	v_mfma_i32_16x16x64_i8 v[142:145], v[130:133], v[162:165], 0
	v_mfma_i32_16x16x64_i8 v[102:105], v[130:133], v[170:173], 0
	v_mfma_i32_16x16x64_i8 v[98:101], v[154:157], v[170:173], 0
	v_mfma_i32_16x16x64_i8 v[26:29], v[154:157], v[178:181], 0
	v_mfma_i32_16x16x64_i8 v[42:45], v[130:133], v[178:181], 0
	v_mfma_i32_16x16x64_i8 v[78:81], v[130:133], v[186:189], 0
	v_mfma_i32_16x16x64_i8 v[150:153], v[22:25], v[166:169], v[150:153]
	v_mfma_i32_16x16x64_i8 v[146:149], v[38:41], v[166:169], v[146:149]
	v_mfma_i32_16x16x64_i8 v[110:113], v[38:41], v[174:177], v[110:113]
	v_mfma_i32_16x16x64_i8 v[118:121], v[22:25], v[174:177], v[118:121]
	v_mfma_i32_16x16x64_i8 v[54:57], v[22:25], v[182:185], v[54:57]
	v_mfma_i32_16x16x64_i8 v[30:33], v[38:41], v[182:185], v[30:33]
	v_mfma_i32_16x16x64_i8 v[58:61], v[38:41], v[190:193], v[58:61]
	v_mfma_i32_16x16x64_i8 v[94:97], v[22:25], v[190:193], v[94:97]
	v_mfma_i32_16x16x64_i8 v[62:65], v[158:161], v[190:193], v[62:65]
	v_mfma_i32_16x16x64_i8 v[138:141], v[158:161], v[166:169], v[138:141]
	v_mfma_i32_16x16x64_i8 v[142:145], v[134:137], v[166:169], v[142:145]
	v_mfma_i32_16x16x64_i8 v[102:105], v[134:137], v[174:177], v[102:105]
	v_mfma_i32_16x16x64_i8 v[98:101], v[158:161], v[174:177], v[98:101]
	v_mfma_i32_16x16x64_i8 v[26:29], v[158:161], v[182:185], v[26:29]
	v_mfma_i32_16x16x64_i8 v[42:45], v[134:137], v[182:185], v[42:45]
	v_mfma_i32_16x16x64_i8 v[78:81], v[134:137], v[190:193], v[78:81]
	s_barrier
	s_add_i32 s0, vcc_hi, s69
	v_lshl_add_u64 v[198:199], s[6:7], 0, v[0:1]
	s_mov_b32 m0, s0
	ds_read_b128 v[162:165], v243 offset:16384
	ds_read_b128 v[166:169], v243 offset:17408
	ds_read_b128 v[170:173], v243 offset:18432
	ds_read_b128 v[174:177], v243 offset:19456
	ds_read_b128 v[178:181], v243 offset:20480
	ds_read_b128 v[182:185], v243 offset:21504
	ds_read_b128 v[186:189], v243 offset:22528
	ds_read_b128 v[190:193], v243 offset:23552
	global_load_lds_dwordx4 v[198:199], off
	s_add_i32 m0, s0, 0x2000
	s_add_u32 s0, s6, 0x40000
	v_lshl_add_u64 v[200:201], s[6:7], 0, v[214:215]
	s_addc_u32 s1, s7, 0
	s_add_i32 s4, s4, s69
	global_load_lds_dwordx4 v[200:201], off
	s_mov_b32 m0, s4
	v_lshl_add_u64 v[206:207], s[12:13], 0, v[210:211]
	global_load_lds_dwordx4 v0, s[0:1]
	s_add_i32 m0, s4, 0x2000
	v_lshl_add_u64 v[220:221], s[12:13], 0, v[212:213]
	global_load_lds_dwordx4 v214, s[0:1]
	s_mov_b32 m0, s11
	s_nop 0
	global_load_lds_dwordx4 v[206:207], off
	s_mov_b32 m0, s71
	s_nop 0
	global_load_lds_dwordx4 v[220:221], off
	s_waitcnt vmcnt(8)
	s_waitcnt lgkmcnt(0)
	s_barrier
	s_waitcnt lgkmcnt(0)
	v_mfma_i32_16x16x64_i8 v[106:109], v[18:21], v[162:165], 0
	v_mfma_i32_16x16x64_i8 v[46:49], v[34:37], v[162:165], 0
	v_mfma_i32_16x16x64_i8 v[6:9], v[34:37], v[170:173], 0
	v_mfma_i32_16x16x64_i8 v[14:17], v[18:21], v[170:173], 0
	v_mfma_i32_16x16x64_i8 v[90:93], v[18:21], v[178:181], 0
	v_mfma_i32_16x16x64_i8 v[86:89], v[34:37], v[178:181], 0
	v_mfma_i32_16x16x64_i8 v[50:53], v[130:133], v[178:181], 0
	v_mfma_i32_16x16x64_i8 v[10:13], v[130:133], v[170:173], 0
	v_mfma_i32_16x16x64_i8 v[2:5], v[154:157], v[170:173], 0
	v_mfma_i32_16x16x64_i8 v[18:21], v[18:21], v[186:189], 0
	v_mfma_i32_16x16x64_i8 v[106:109], v[22:25], v[166:169], v[106:109]
	v_mfma_i32_16x16x64_i8 v[46:49], v[38:41], v[166:169], v[46:49]
	v_mfma_i32_16x16x64_i8 v[6:9], v[38:41], v[174:177], v[6:9]
	v_mfma_i32_16x16x64_i8 v[14:17], v[22:25], v[174:177], v[14:17]
	v_mfma_i32_16x16x64_i8 v[90:93], v[22:25], v[182:185], v[90:93]
	v_mfma_i32_16x16x64_i8 v[86:89], v[38:41], v[182:185], v[86:89]
	v_mfma_i32_16x16x64_i8 v[82:85], v[134:137], v[182:185], v[50:53]
	v_mfma_i32_16x16x64_i8 v[10:13], v[134:137], v[174:177], v[10:13]
	v_mfma_i32_16x16x64_i8 v[2:5], v[158:161], v[174:177], v[2:5]
	v_mfma_i32_16x16x64_i8 v[18:21], v[22:25], v[190:193], v[18:21]
	v_mfma_i32_16x16x64_i8 v[22:25], v[34:37], v[186:189], 0
	v_mfma_i32_16x16x64_i8 v[34:37], v[130:133], v[162:165], 0
	v_mfma_i32_16x16x64_i8 v[50:53], v[154:157], v[178:181], 0
	v_mfma_i32_16x16x64_i8 v[22:25], v[38:41], v[190:193], v[22:25]
	v_mfma_i32_16x16x64_i8 v[38:41], v[154:157], v[162:165], 0
	v_mfma_i32_16x16x64_i8 v[38:41], v[158:161], v[166:169], v[38:41]
	v_mfma_i32_16x16x64_i8 v[34:37], v[134:137], v[166:169], v[34:37]
	v_mfma_i32_16x16x64_i8 v[74:77], v[158:161], v[182:185], v[50:53]
	v_mfma_i32_16x16x64_i8 v[50:53], v[130:133], v[186:189], 0
	v_mfma_i32_16x16x64_i8 v[122:125], v[134:137], v[190:193], v[50:53]
	v_mfma_i32_16x16x64_i8 v[50:53], v[154:157], v[186:189], 0
	v_mfma_i32_16x16x64_i8 v[70:73], v[158:161], v[190:193], v[50:53]
	s_barrier
; #define PG8_STAGE(bufoff, gbase, voff) do { _Pragma("unroll") for (int _i = 0; _i < 2; ++_i) \
;         __builtin_amdgcn_global_load_lds((const unsigned*)((const char*)(gbase) + (voff)[_i]), (PG8_LAS unsigned*)(lds + (bufoff) + ldsw + _i * 8192), 16, 0, 0); } while (0)
; #define PG8_LDA(dst, b, h) do { _Pragma("unroll") for (int m = 0; m < 4; ++m) _Pragma("unroll") for (int k = 0; k < 2; ++k) dst[m][k] = *(const PG8_LAS bf16x8*)(lds + PG8_SA(b, h) + aoff + m * 2048 + k * 1024); } while (0)
; #define PG8_LDB(dst, b, h) do { _Pragma("unroll") for (int n = 0; n < 2; ++n) _Pragma("unroll") for (int k = 0; k < 2; ++k) dst[n][k] = *(const PG8_LAS bf16x8*)(lds + PG8_SB(b, h) + boff + n * 2048 + k * 1024); } while (0)
; #define PG8_MMA(ai, bj, At, Bt) do { __builtin_amdgcn_s_setprio(1); _Pragma("unroll") for (int m = 0; m < 4; ++m) _Pragma("unroll") for (int n = 0; n < 2; ++n) _Pragma("unroll") for (int k = 0; k < 2; ++k) \
;         acc[ai][bj][m][n] = mma16<Epi::I8>(Bt[n][k], At[m][k], acc[ai][bj][m][n]); __builtin_amdgcn_s_setprio(0); } while (0)
; #define PG8_WAIT_V(n) asm volatile("s_waitcnt vmcnt(" #n ")" ::: "memory")
; #define PG8_WAIT_L(n) asm volatile("s_waitcnt lgkmcnt(" #n ")" ::: "memory")
; #define PG8_BAR __builtin_amdgcn_s_barrier()
; #define PG8_SCHED __builtin_amdgcn_sched_barrier(0)
; template <class Epi, class Sched, bool ALIGN_EPI = false, bool SP2 = false>
; __device__ __forceinline__ void gemm_phase(PG8_LAS unsigned char* lds, const Gemm g, const Sched& S, const Epi& E) {
;     ...
;         for (int t = 0; t < nt; t += 2) {
;     ...
;             PG8_LDB(B0, 1, 0); PG8_LDB(B1, 1, 1); PG8_SCHED; PG8_LDA(At, 1, 0); PG8_STAGE(PG8_SA(0, 1), a2 + hstep, voffA);
;             PG8_WAIT_V(8); PG8_WAIT_L(0); PG8_BAR; PG8_MMA(0, 0, At, B0); PG8_MMA(0, 1, At, B1); PG8_BAR; PG8_SCHED;
;             PG8_LDA(At, 1, 1); PG8_STAGE(PG8_SB(1, 0), b3, voffB); PG8_STAGE(PG8_SB(1, 1), b3 + hstep, voffB); PG8_STAGE(PG8_SA(1, 0), a3, voffA);
;             PG8_WAIT_V(8); PG8_WAIT_L(0); PG8_BAR; PG8_MMA(1, 0, At, B0); PG8_MMA(1, 1, At, B1); PG8_BAR; PG8_SCHED;
	s_add_i32 s4, 0, 0x18000
	v_add_u32_e32 v126, s4, v242
	s_add_i32 s5, 0, 0x1c000
	ds_read_b128 v[50:53], v126
	ds_read_b128 v[66:69], v126 offset:1024
	ds_read_b128 v[114:117], v126 offset:2048
	ds_read_b128 v[130:133], v126 offset:3072
	v_add_u32_e32 v126, s5, v242
	ds_read_b128 v[134:137], v126
	ds_read_b128 v[154:157], v126 offset:1024
	ds_read_b128 v[158:161], v126 offset:2048
	ds_read_b128 v[162:165], v126 offset:3072
	s_add_u32 s0, s12, 0x40000
	s_addc_u32 s1, s13, 0
	s_mov_b32 m0, s80
	ds_read_b128 v[126:129], v243 offset:32768
	ds_read_b128 v[166:169], v243 offset:33792
	ds_read_b128 v[170:173], v243 offset:34816
	ds_read_b128 v[174:177], v243 offset:35840
	ds_read_b128 v[178:181], v243 offset:36864
	ds_read_b128 v[182:185], v243 offset:37888
	ds_read_b128 v[186:189], v243 offset:38912
	ds_read_b128 v[190:193], v243 offset:39936
	global_load_lds_dwordx4 v210, s[0:1]
	s_mov_b32 m0, s81
	s_nop 0
	global_load_lds_dwordx4 v212, s[0:1]
	s_waitcnt vmcnt(8)
	s_waitcnt lgkmcnt(0)
	s_barrier
	s_waitcnt lgkmcnt(0)
	v_mfma_i32_16x16x64_i8 v[150:153], v[50:53], v[126:129], v[150:153]
	v_mfma_i32_16x16x64_i8 v[146:149], v[114:117], v[126:129], v[146:149]
	v_mfma_i32_16x16x64_i8 v[110:113], v[114:117], v[170:173], v[110:113]
	v_mfma_i32_16x16x64_i8 v[118:121], v[50:53], v[170:173], v[118:121]
	v_mfma_i32_16x16x64_i8 v[54:57], v[50:53], v[178:181], v[54:57]
	v_mfma_i32_16x16x64_i8 v[30:33], v[114:117], v[178:181], v[30:33]
	v_mfma_i32_16x16x64_i8 v[58:61], v[114:117], v[186:189], v[58:61]
	v_mfma_i32_16x16x64_i8 v[94:97], v[50:53], v[186:189], v[94:97]
	v_mfma_i32_16x16x64_i8 v[62:65], v[158:161], v[186:189], v[62:65]
	v_mfma_i32_16x16x64_i8 v[98:101], v[158:161], v[170:173], v[98:101]
	v_mfma_i32_16x16x64_i8 v[102:105], v[134:137], v[170:173], v[102:105]
	v_mfma_i32_16x16x64_i8 v[142:145], v[134:137], v[126:129], v[142:145]
	v_mfma_i32_16x16x64_i8 v[126:129], v[158:161], v[126:129], v[138:141]
	v_mfma_i32_16x16x64_i8 v[26:29], v[158:161], v[178:181], v[26:29]
	v_mfma_i32_16x16x64_i8 v[42:45], v[134:137], v[178:181], v[42:45]
	v_mfma_i32_16x16x64_i8 v[78:81], v[134:137], v[186:189], v[78:81]
	v_mfma_i32_16x16x64_i8 v[150:153], v[66:69], v[166:169], v[150:153]
	v_mfma_i32_16x16x64_i8 v[146:149], v[130:133], v[166:169], v[146:149]
	v_mfma_i32_16x16x64_i8 v[110:113], v[130:133], v[174:177], v[110:113]
	v_mfma_i32_16x16x64_i8 v[118:121], v[66:69], v[174:177], v[118:121]
	v_mfma_i32_16x16x64_i8 v[54:57], v[66:69], v[182:185], v[54:57]
	v_mfma_i32_16x16x64_i8 v[30:33], v[130:133], v[182:185], v[30:33]
	v_mfma_i32_16x16x64_i8 v[58:61], v[130:133], v[190:193], v[58:61]
	v_mfma_i32_16x16x64_i8 v[94:97], v[66:69], v[190:193], v[94:97]
	v_mfma_i32_16x16x64_i8 v[62:65], v[162:165], v[190:193], v[62:65]
	v_mfma_i32_16x16x64_i8 v[138:141], v[162:165], v[166:169], v[126:129]
	v_mfma_i32_16x16x64_i8 v[142:145], v[154:157], v[166:169], v[142:145]
	v_mfma_i32_16x16x64_i8 v[102:105], v[154:157], v[174:177], v[102:105]
	v_mfma_i32_16x16x64_i8 v[98:101], v[162:165], v[174:177], v[98:101]
	v_mfma_i32_16x16x64_i8 v[26:29], v[162:165], v[182:185], v[26:29]
	v_mfma_i32_16x16x64_i8 v[42:45], v[154:157], v[182:185], v[42:45]
	v_mfma_i32_16x16x64_i8 v[78:81], v[154:157], v[190:193], v[78:81]
	s_barrier
	s_add_i32 s0, s4, s69
	v_lshl_add_u64 v[126:127], v[198:199], 0, s[92:93]
	s_mov_b32 m0, s0
	ds_read_b128 v[166:169], v243 offset:49152
	ds_read_b128 v[170:173], v243 offset:50176
	ds_read_b128 v[174:177], v243 offset:51200
	ds_read_b128 v[178:181], v243 offset:52224
	ds_read_b128 v[182:185], v243 offset:53248
	ds_read_b128 v[186:189], v243 offset:54272
	ds_read_b128 v[190:193], v243 offset:55296
	ds_read_b128 v[194:197], v243 offset:56320
	global_load_lds_dwordx4 v[126:127], off
	s_add_i32 m0, s0, 0x2000
	s_add_u32 s0, s6, 0x40080
	v_lshl_add_u64 v[126:127], v[200:201], 0, s[92:93]
	s_addc_u32 s1, s7, 0
	s_add_i32 s4, s5, s69
	global_load_lds_dwordx4 v[126:127], off
	s_mov_b32 m0, s4
	s_nop 0
	global_load_lds_dwordx4 v0, s[0:1]
	s_add_i32 m0, s4, 0x2000
	s_nop 0
	global_load_lds_dwordx4 v214, s[0:1]
	v_lshl_add_u64 v[126:127], v[206:207], 0, s[92:93]
	s_mov_b32 m0, s84
	s_nop 0
	global_load_lds_dwordx4 v[126:127], off
	v_lshl_add_u64 v[126:127], v[220:221], 0, s[92:93]
	s_mov_b32 m0, s85
	s_nop 0
	global_load_lds_dwordx4 v[126:127], off
	s_waitcnt vmcnt(8)
	s_waitcnt lgkmcnt(0)
	s_barrier
	s_waitcnt lgkmcnt(0)
	v_mfma_i32_16x16x64_i8 v[18:21], v[50:53], v[190:193], v[18:21]
	v_mfma_i32_16x16x64_i8 v[106:109], v[50:53], v[166:169], v[106:109]
	v_mfma_i32_16x16x64_i8 v[46:49], v[114:117], v[166:169], v[46:49]
	v_mfma_i32_16x16x64_i8 v[6:9], v[114:117], v[174:177], v[6:9]
	v_mfma_i32_16x16x64_i8 v[14:17], v[50:53], v[174:177], v[14:17]
	v_mfma_i32_16x16x64_i8 v[90:93], v[50:53], v[182:185], v[90:93]
	v_mfma_i32_16x16x64_i8 v[86:89], v[114:117], v[182:185], v[86:89]
	v_mfma_i32_16x16x64_i8 v[126:129], v[66:69], v[194:197], v[18:21]
	v_mfma_i32_16x16x64_i8 v[106:109], v[66:69], v[170:173], v[106:109]
	v_mfma_i32_16x16x64_i8 v[46:49], v[130:133], v[170:173], v[46:49]
	v_mfma_i32_16x16x64_i8 v[6:9], v[130:133], v[178:181], v[6:9]
	v_mfma_i32_16x16x64_i8 v[14:17], v[66:69], v[178:181], v[14:17]
	v_mfma_i32_16x16x64_i8 v[90:93], v[66:69], v[186:189], v[90:93]
	v_mfma_i32_16x16x64_i8 v[86:89], v[130:133], v[186:189], v[86:89]
	v_mfma_i32_16x16x64_i8 v[18:21], v[114:117], v[190:193], v[22:25]
	v_mfma_i32_16x16x64_i8 v[10:13], v[134:137], v[174:177], v[10:13]
	v_mfma_i32_16x16x64_i8 v[2:5], v[158:161], v[174:177], v[2:5]
	v_mfma_i32_16x16x64_i8 v[66:69], v[130:133], v[194:197], v[18:21]
	v_mfma_i32_16x16x64_i8 v[18:21], v[134:137], v[166:169], v[34:37]
	v_mfma_i32_16x16x64_i8 v[114:117], v[154:157], v[170:173], v[18:21]
	v_mfma_i32_16x16x64_i8 v[18:21], v[158:161], v[166:169], v[38:41]
	v_mfma_i32_16x16x64_i8 v[10:13], v[154:157], v[178:181], v[10:13]
	v_mfma_i32_16x16x64_i8 v[2:5], v[162:165], v[178:181], v[2:5]
	v_mfma_i32_16x16x64_i8 v[50:53], v[162:165], v[170:173], v[18:21]
	v_mfma_i32_16x16x64_i8 v[18:21], v[134:137], v[182:185], v[82:85]
	v_mfma_i32_16x16x64_i8 v[82:85], v[154:157], v[186:189], v[18:21]
	v_mfma_i32_16x16x64_i8 v[18:21], v[158:161], v[182:185], v[74:77]
	v_mfma_i32_16x16x64_i8 v[74:77], v[162:165], v[186:189], v[18:21]
	v_mfma_i32_16x16x64_i8 v[18:21], v[134:137], v[190:193], v[122:125]
	v_mfma_i32_16x16x64_i8 v[122:125], v[154:157], v[194:197], v[18:21]
	v_mfma_i32_16x16x64_i8 v[18:21], v[158:161], v[190:193], v[70:73]
	v_mfma_i32_16x16x64_i8 v[70:73], v[162:165], v[194:197], v[18:21]
	s_barrier
	s_add_i32 vcc_lo, vcc_lo, 2
	s_add_u32 s96, s96, 0x100
	s_addc_u32 s97, s97, 0
	s_cmp_gt_u32 vcc_lo, 13
	s_mov_b64 s[0:1], s[8:9]
	s_cbranch_scc0 .LBB0_80
	s_branch .Lpeelx80
; #define PG8_STAGE(bufoff, gbase, voff) do { _Pragma("unroll") for (int _i = 0; _i < 2; ++_i) \
;         __builtin_amdgcn_global_load_lds((const unsigned*)((const char*)(gbase) + (voff)[_i]), (PG8_LAS unsigned*)(lds + (bufoff) + ldsw + _i * 8192), 16, 0, 0); } while (0)
; #define PG8_LDA(dst, b, h) do { _Pragma("unroll") for (int m = 0; m < 4; ++m) _Pragma("unroll") for (int k = 0; k < 2; ++k) dst[m][k] = *(const PG8_LAS bf16x8*)(lds + PG8_SA(b, h) + aoff + m * 2048 + k * 1024); } while (0)
; #define PG8_LDB(dst, b, h) do { _Pragma("unroll") for (int n = 0; n < 2; ++n) _Pragma("unroll") for (int k = 0; k < 2; ++k) dst[n][k] = *(const PG8_LAS bf16x8*)(lds + PG8_SB(b, h) + boff + n * 2048 + k * 1024); } while (0)
; template <class Epi, class Sched, bool ALIGN_EPI = false, bool SP2 = false>
; __device__ __forceinline__ void gemm_phase(PG8_LAS unsigned char* lds, const Gemm g, const Sched& S, const Epi& E) {
;     ...
;         for (int t = 0; t < nt; t += 2) {
;             const bool last = (t == nt - 2);
;             const char* a1 = cA + (size_t)(t + 1) * kstep;
;             const char* a2 = last ? nA : cA + (size_t)(t + 2) * kstep; const char* b2 = last ? nB : cB + (size_t)(t + 2) * kstep;
;             const char* a3 = a2 + kstep; const char* b3 = b2 + kstep;
;             if (last && has_next) S.a_ready(nxt);
;             if constexpr (SP2) {
;             PG8_LDB(B0, 0, 0); PG8_LDB(B1, 0, 1); PG8_SCHED; PG8_LDA(At, 0, 0); PG8_STAGE(PG8_SA(1, 1), a1 + hstep, voffA);
;             PG8_WAIT_V(8); PG8_WAIT_L(0); PG8_BAR; PG8_MMA(0, 0, At, B0); PG8_MMA(0, 1, At, B1); PG8_BAR; PG8_SCHED;
;             PG8_LDA(At, 0, 1); PG8_STAGE(PG8_SB(0, 0), b2, voffB); PG8_STAGE(PG8_SB(0, 1), b2 + hstep, voffB); PG8_STAGE(PG8_SA(0, 0), a2, voffA);
;             PG8_WAIT_V(8); PG8_WAIT_L(0); PG8_BAR; PG8_MMA(1, 0, At, B0); PG8_MMA(1, 1, At, B1); PG8_BAR; PG8_SCHED;
;             PG8_LDB(B0, 1, 0); PG8_LDB(B1, 1, 1); PG8_SCHED; PG8_LDA(At, 1, 0); PG8_STAGE(PG8_SA(0, 1), a2 + hstep, voffA);
;             PG8_WAIT_V(8); PG8_WAIT_L(0); PG8_BAR; PG8_MMA(0, 0, At, B0); PG8_MMA(0, 1, At, B1); PG8_BAR; PG8_SCHED;
;             PG8_LDA(At, 1, 1); PG8_STAGE(PG8_SB(1, 0), b3, voffB); PG8_STAGE(PG8_SB(1, 1), b3 + hstep, voffB); PG8_STAGE(PG8_SA(1, 0), a3, voffA);
;             PG8_WAIT_V(8); PG8_WAIT_L(0); PG8_BAR; PG8_MMA(1, 0, At, B0); PG8_MMA(1, 1, At, B1); PG8_BAR; PG8_SCHED;
.LBB0_80:
	s_add_u32 s8, s0, 0x100
	s_addc_u32 s9, s1, 0
	s_add_i32 vcc_hi, 0, 0x10000
	s_cmp_eq_u32 vcc_lo, 12
	s_cselect_b32 s13, s66, s9
	s_cselect_b32 s12, s67, s8
	s_cselect_b32 s7, s82, s97
	s_cselect_b32 s6, s83, s96
	s_add_i32 s4, 0, 0x14000
	v_add_u32_e32 v38, vcc_hi, v242
	v_add_u32_e32 v158, s4, v242
	ds_read_b128 v[18:21], v38
	ds_read_b128 v[22:25], v38 offset:1024
	ds_read_b128 v[34:37], v38 offset:2048
	ds_read_b128 v[38:41], v38 offset:3072
	ds_read_b128 v[130:133], v158
	ds_read_b128 v[134:137], v158 offset:1024
	ds_read_b128 v[154:157], v158 offset:2048
	ds_read_b128 v[158:161], v158 offset:3072
	s_add_i32 m0, s11, 0xc000
	ds_read_b128 v[162:165], v243
	ds_read_b128 v[166:169], v243 offset:1024
	ds_read_b128 v[170:173], v243 offset:2048
	ds_read_b128 v[174:177], v243 offset:3072
	ds_read_b128 v[178:181], v243 offset:4096
	ds_read_b128 v[182:185], v243 offset:5120
	ds_read_b128 v[186:189], v243 offset:6144
	ds_read_b128 v[190:193], v243 offset:7168
	global_load_lds_dwordx4 v216, s[0:1]
	s_add_i32 m0, s11, 0xe000
	s_nop 0
	global_load_lds_dwordx4 v218, s[0:1]
	s_waitcnt vmcnt(8)
	s_waitcnt lgkmcnt(0)
	s_barrier
	s_waitcnt lgkmcnt(0)
	v_mfma_i32_16x16x64_i8 v[150:153], v[18:21], v[162:165], v[150:153]
	v_mfma_i32_16x16x64_i8 v[146:149], v[34:37], v[162:165], v[146:149]
	v_mfma_i32_16x16x64_i8 v[110:113], v[34:37], v[170:173], v[110:113]
	v_mfma_i32_16x16x64_i8 v[118:121], v[18:21], v[170:173], v[118:121]
	v_mfma_i32_16x16x64_i8 v[54:57], v[18:21], v[178:181], v[54:57]
	v_mfma_i32_16x16x64_i8 v[30:33], v[34:37], v[178:181], v[30:33]
	v_mfma_i32_16x16x64_i8 v[58:61], v[34:37], v[186:189], v[58:61]
	v_mfma_i32_16x16x64_i8 v[94:97], v[18:21], v[186:189], v[94:97]
	v_mfma_i32_16x16x64_i8 v[62:65], v[154:157], v[186:189], v[62:65]
	v_mfma_i32_16x16x64_i8 v[138:141], v[154:157], v[162:165], v[138:141]
	v_mfma_i32_16x16x64_i8 v[142:145], v[130:133], v[162:165], v[142:145]
	v_mfma_i32_16x16x64_i8 v[102:105], v[130:133], v[170:173], v[102:105]
	v_mfma_i32_16x16x64_i8 v[98:101], v[154:157], v[170:173], v[98:101]
	v_mfma_i32_16x16x64_i8 v[26:29], v[154:157], v[178:181], v[26:29]
	v_mfma_i32_16x16x64_i8 v[42:45], v[130:133], v[178:181], v[42:45]
	v_mfma_i32_16x16x64_i8 v[78:81], v[130:133], v[186:189], v[78:81]
	v_mfma_i32_16x16x64_i8 v[150:153], v[22:25], v[166:169], v[150:153]
	v_mfma_i32_16x16x64_i8 v[146:149], v[38:41], v[166:169], v[146:149]
	v_mfma_i32_16x16x64_i8 v[110:113], v[38:41], v[174:177], v[110:113]
	v_mfma_i32_16x16x64_i8 v[118:121], v[22:25], v[174:177], v[118:121]
	v_mfma_i32_16x16x64_i8 v[54:57], v[22:25], v[182:185], v[54:57]
	v_mfma_i32_16x16x64_i8 v[30:33], v[38:41], v[182:185], v[30:33]
	v_mfma_i32_16x16x64_i8 v[58:61], v[38:41], v[190:193], v[58:61]
	v_mfma_i32_16x16x64_i8 v[94:97], v[22:25], v[190:193], v[94:97]
	v_mfma_i32_16x16x64_i8 v[62:65], v[158:161], v[190:193], v[62:65]
	v_mfma_i32_16x16x64_i8 v[138:141], v[158:161], v[166:169], v[138:141]
	v_mfma_i32_16x16x64_i8 v[142:145], v[134:137], v[166:169], v[142:145]
	v_mfma_i32_16x16x64_i8 v[102:105], v[134:137], v[174:177], v[102:105]
	v_mfma_i32_16x16x64_i8 v[98:101], v[158:161], v[174:177], v[98:101]
	v_mfma_i32_16x16x64_i8 v[26:29], v[158:161], v[182:185], v[26:29]
	v_mfma_i32_16x16x64_i8 v[42:45], v[134:137], v[182:185], v[42:45]
	v_mfma_i32_16x16x64_i8 v[78:81], v[134:137], v[190:193], v[78:81]
	s_barrier
	s_add_i32 s0, vcc_hi, s69
	v_lshl_add_u64 v[198:199], s[6:7], 0, v[0:1]
	s_mov_b32 m0, s0
	ds_read_b128 v[162:165], v243 offset:16384
	ds_read_b128 v[166:169], v243 offset:17408
	ds_read_b128 v[170:173], v243 offset:18432
	ds_read_b128 v[174:177], v243 offset:19456
	ds_read_b128 v[178:181], v243 offset:20480
	ds_read_b128 v[182:185], v243 offset:21504
	ds_read_b128 v[186:189], v243 offset:22528
	ds_read_b128 v[190:193], v243 offset:23552
	global_load_lds_dwordx4 v[198:199], off
	s_add_i32 m0, s0, 0x2000
	s_add_u32 s0, s6, 0x40000
	v_lshl_add_u64 v[200:201], s[6:7], 0, v[214:215]
	s_addc_u32 s1, s7, 0
	s_add_i32 s4, s4, s69
	global_load_lds_dwordx4 v[200:201], off
	s_mov_b32 m0, s4
	v_lshl_add_u64 v[206:207], s[12:13], 0, v[210:211]
	global_load_lds_dwordx4 v0, s[0:1]
	s_add_i32 m0, s4, 0x2000
	v_lshl_add_u64 v[220:221], s[12:13], 0, v[212:213]
	global_load_lds_dwordx4 v214, s[0:1]
	s_mov_b32 m0, s11
	s_nop 0
	global_load_lds_dwordx4 v[206:207], off
	s_mov_b32 m0, s71
	s_nop 0
	global_load_lds_dwordx4 v[220:221], off
	s_waitcnt vmcnt(8)
	s_waitcnt lgkmcnt(0)
	s_barrier
	s_waitcnt lgkmcnt(0)
	v_mfma_i32_16x16x64_i8 v[106:109], v[18:21], v[162:165], v[106:109]
	v_mfma_i32_16x16x64_i8 v[46:49], v[34:37], v[162:165], v[46:49]
	v_mfma_i32_16x16x64_i8 v[6:9], v[34:37], v[170:173], v[6:9]
	v_mfma_i32_16x16x64_i8 v[14:17], v[18:21], v[170:173], v[14:17]
	v_mfma_i32_16x16x64_i8 v[90:93], v[18:21], v[178:181], v[90:93]
	v_mfma_i32_16x16x64_i8 v[86:89], v[34:37], v[178:181], v[86:89]
	v_mfma_i32_16x16x64_i8 v[18:21], v[18:21], v[186:189], v[126:129]
	v_mfma_i32_16x16x64_i8 v[106:109], v[22:25], v[166:169], v[106:109]
	v_mfma_i32_16x16x64_i8 v[46:49], v[38:41], v[166:169], v[46:49]
	v_mfma_i32_16x16x64_i8 v[6:9], v[38:41], v[174:177], v[6:9]
	v_mfma_i32_16x16x64_i8 v[14:17], v[22:25], v[174:177], v[14:17]
	v_mfma_i32_16x16x64_i8 v[90:93], v[22:25], v[182:185], v[90:93]
	v_mfma_i32_16x16x64_i8 v[86:89], v[38:41], v[182:185], v[86:89]
	v_mfma_i32_16x16x64_i8 v[18:21], v[22:25], v[190:193], v[18:21]
	v_mfma_i32_16x16x64_i8 v[22:25], v[34:37], v[186:189], v[66:69]
	v_mfma_i32_16x16x64_i8 v[2:5], v[154:157], v[170:173], v[2:5]
	v_mfma_i32_16x16x64_i8 v[10:13], v[130:133], v[170:173], v[10:13]
	v_mfma_i32_16x16x64_i8 v[34:37], v[130:133], v[162:165], v[114:117]
	v_mfma_i32_16x16x64_i8 v[22:25], v[38:41], v[190:193], v[22:25]
	v_mfma_i32_16x16x64_i8 v[38:41], v[154:157], v[162:165], v[50:53]
	v_mfma_i32_16x16x64_i8 v[50:53], v[130:133], v[178:181], v[82:85]
	v_mfma_i32_16x16x64_i8 v[2:5], v[158:161], v[174:177], v[2:5]
	v_mfma_i32_16x16x64_i8 v[10:13], v[134:137], v[174:177], v[10:13]
	v_mfma_i32_16x16x64_i8 v[34:37], v[134:137], v[166:169], v[34:37]
	v_mfma_i32_16x16x64_i8 v[82:85], v[134:137], v[182:185], v[50:53]
	v_mfma_i32_16x16x64_i8 v[50:53], v[154:157], v[178:181], v[74:77]
	v_mfma_i32_16x16x64_i8 v[38:41], v[158:161], v[166:169], v[38:41]
	v_mfma_i32_16x16x64_i8 v[74:77], v[158:161], v[182:185], v[50:53]
	v_mfma_i32_16x16x64_i8 v[50:53], v[130:133], v[186:189], v[122:125]
	v_mfma_i32_16x16x64_i8 v[122:125], v[134:137], v[190:193], v[50:53]
	v_mfma_i32_16x16x64_i8 v[50:53], v[154:157], v[186:189], v[70:73]
	v_mfma_i32_16x16x64_i8 v[70:73], v[158:161], v[190:193], v[50:53]
	s_barrier
; #define PG8_STAGE(bufoff, gbase, voff) do { _Pragma("unroll") for (int _i = 0; _i < 2; ++_i) \
;         __builtin_amdgcn_global_load_lds((const unsigned*)((const char*)(gbase) + (voff)[_i]), (PG8_LAS unsigned*)(lds + (bufoff) + ldsw + _i * 8192), 16, 0, 0); } while (0)
; #define PG8_LDA(dst, b, h) do { _Pragma("unroll") for (int m = 0; m < 4; ++m) _Pragma("unroll") for (int k = 0; k < 2; ++k) dst[m][k] = *(const PG8_LAS bf16x8*)(lds + PG8_SA(b, h) + aoff + m * 2048 + k * 1024); } while (0)
; #define PG8_LDB(dst, b, h) do { _Pragma("unroll") for (int n = 0; n < 2; ++n) _Pragma("unroll") for (int k = 0; k < 2; ++k) dst[n][k] = *(const PG8_LAS bf16x8*)(lds + PG8_SB(b, h) + boff + n * 2048 + k * 1024); } while (0)
; template <class Epi, class Sched, bool ALIGN_EPI = false, bool SP2 = false>
; __device__ __forceinline__ void gemm_phase(PG8_LAS unsigned char* lds, const Gemm g, const Sched& S, const Epi& E) {
;     ...
;         for (int t = 0; t < nt; t += 2) {
;             const bool last = (t == nt - 2);
;             const char* a1 = cA + (size_t)(t + 1) * kstep;
;             const char* a2 = last ? nA : cA + (size_t)(t + 2) * kstep; const char* b2 = last ? nB : cB + (size_t)(t + 2) * kstep;
;             const char* a3 = a2 + kstep; const char* b3 = b2 + kstep;
;             if (last && has_next) S.a_ready(nxt);
;             if constexpr (SP2) {
;             PG8_LDB(B0, 0, 0); PG8_LDB(B1, 0, 1); PG8_SCHED; PG8_LDA(At, 0, 0); PG8_STAGE(PG8_SA(1, 1), a1 + hstep, voffA);
;             PG8_WAIT_V(8); PG8_WAIT_L(0); PG8_BAR; PG8_MMA(0, 0, At, B0); PG8_MMA(0, 1, At, B1); PG8_BAR; PG8_SCHED;
;             PG8_LDA(At, 0, 1); PG8_STAGE(PG8_SB(0, 0), b2, voffB); PG8_STAGE(PG8_SB(0, 1), b2 + hstep, voffB); PG8_STAGE(PG8_SA(0, 0), a2, voffA);
;             PG8_WAIT_V(8); PG8_WAIT_L(0); PG8_BAR; PG8_MMA(1, 0, At, B0); PG8_MMA(1, 1, At, B1); PG8_BAR; PG8_SCHED;
;             PG8_LDB(B0, 1, 0); PG8_LDB(B1, 1, 1); PG8_SCHED; PG8_LDA(At, 1, 0); PG8_STAGE(PG8_SA(0, 1), a2 + hstep, voffA);
;             PG8_WAIT_V(8); PG8_WAIT_L(0); PG8_BAR; PG8_MMA(0, 0, At, B0); PG8_MMA(0, 1, At, B1); PG8_BAR; PG8_SCHED;
;             PG8_LDA(At, 1, 1); PG8_STAGE(PG8_SB(1, 0), b3, voffB); PG8_STAGE(PG8_SB(1, 1), b3 + hstep, voffB); PG8_STAGE(PG8_SA(1, 0), a3, voffA);
;             PG8_WAIT_V(8); PG8_WAIT_L(0); PG8_BAR; PG8_MMA(1, 0, At, B0); PG8_MMA(1, 1, At, B1); PG8_BAR; PG8_SCHED;
	s_add_i32 s4, 0, 0x18000
	v_add_u32_e32 v126, s4, v242
	s_add_i32 s5, 0, 0x1c000
	ds_read_b128 v[50:53], v126
	ds_read_b128 v[66:69], v126 offset:1024
	ds_read_b128 v[114:117], v126 offset:2048
	ds_read_b128 v[130:133], v126 offset:3072
	v_add_u32_e32 v126, s5, v242
	ds_read_b128 v[134:137], v126
	ds_read_b128 v[154:157], v126 offset:1024
	ds_read_b128 v[158:161], v126 offset:2048
	ds_read_b128 v[162:165], v126 offset:3072
	s_add_u32 s0, s12, 0x40000
	s_addc_u32 s1, s13, 0
	s_mov_b32 m0, s80
	ds_read_b128 v[126:129], v243 offset:32768
	ds_read_b128 v[166:169], v243 offset:33792
	ds_read_b128 v[170:173], v243 offset:34816
	ds_read_b128 v[174:177], v243 offset:35840
	ds_read_b128 v[178:181], v243 offset:36864
	ds_read_b128 v[182:185], v243 offset:37888
	ds_read_b128 v[186:189], v243 offset:38912
	ds_read_b128 v[190:193], v243 offset:39936
	global_load_lds_dwordx4 v210, s[0:1]
	s_mov_b32 m0, s81
	s_nop 0
	global_load_lds_dwordx4 v212, s[0:1]
	s_waitcnt vmcnt(8)
	s_waitcnt lgkmcnt(0)
	s_barrier
	s_waitcnt lgkmcnt(0)
	v_mfma_i32_16x16x64_i8 v[150:153], v[50:53], v[126:129], v[150:153]
	v_mfma_i32_16x16x64_i8 v[146:149], v[114:117], v[126:129], v[146:149]
	v_mfma_i32_16x16x64_i8 v[110:113], v[114:117], v[170:173], v[110:113]
	v_mfma_i32_16x16x64_i8 v[118:121], v[50:53], v[170:173], v[118:121]
	v_mfma_i32_16x16x64_i8 v[54:57], v[50:53], v[178:181], v[54:57]
	v_mfma_i32_16x16x64_i8 v[30:33], v[114:117], v[178:181], v[30:33]
	v_mfma_i32_16x16x64_i8 v[58:61], v[114:117], v[186:189], v[58:61]
	v_mfma_i32_16x16x64_i8 v[94:97], v[50:53], v[186:189], v[94:97]
	v_mfma_i32_16x16x64_i8 v[62:65], v[158:161], v[186:189], v[62:65]
	v_mfma_i32_16x16x64_i8 v[98:101], v[158:161], v[170:173], v[98:101]
	v_mfma_i32_16x16x64_i8 v[102:105], v[134:137], v[170:173], v[102:105]
	v_mfma_i32_16x16x64_i8 v[142:145], v[134:137], v[126:129], v[142:145]
	v_mfma_i32_16x16x64_i8 v[126:129], v[158:161], v[126:129], v[138:141]
	v_mfma_i32_16x16x64_i8 v[26:29], v[158:161], v[178:181], v[26:29]
	v_mfma_i32_16x16x64_i8 v[42:45], v[134:137], v[178:181], v[42:45]
	v_mfma_i32_16x16x64_i8 v[78:81], v[134:137], v[186:189], v[78:81]
	v_mfma_i32_16x16x64_i8 v[150:153], v[66:69], v[166:169], v[150:153]
	v_mfma_i32_16x16x64_i8 v[146:149], v[130:133], v[166:169], v[146:149]
	v_mfma_i32_16x16x64_i8 v[110:113], v[130:133], v[174:177], v[110:113]
	v_mfma_i32_16x16x64_i8 v[118:121], v[66:69], v[174:177], v[118:121]
	v_mfma_i32_16x16x64_i8 v[54:57], v[66:69], v[182:185], v[54:57]
	v_mfma_i32_16x16x64_i8 v[30:33], v[130:133], v[182:185], v[30:33]
	v_mfma_i32_16x16x64_i8 v[58:61], v[130:133], v[190:193], v[58:61]
	v_mfma_i32_16x16x64_i8 v[94:97], v[66:69], v[190:193], v[94:97]
	v_mfma_i32_16x16x64_i8 v[62:65], v[162:165], v[190:193], v[62:65]
	v_mfma_i32_16x16x64_i8 v[138:141], v[162:165], v[166:169], v[126:129]
	v_mfma_i32_16x16x64_i8 v[142:145], v[154:157], v[166:169], v[142:145]
	v_mfma_i32_16x16x64_i8 v[102:105], v[154:157], v[174:177], v[102:105]
	v_mfma_i32_16x16x64_i8 v[98:101], v[162:165], v[174:177], v[98:101]
	v_mfma_i32_16x16x64_i8 v[26:29], v[162:165], v[182:185], v[26:29]
	v_mfma_i32_16x16x64_i8 v[42:45], v[154:157], v[182:185], v[42:45]
	v_mfma_i32_16x16x64_i8 v[78:81], v[154:157], v[190:193], v[78:81]
	s_barrier
	s_add_i32 s0, s4, s69
	v_lshl_add_u64 v[126:127], v[198:199], 0, s[92:93]
	s_mov_b32 m0, s0
	ds_read_b128 v[166:169], v243 offset:49152
	ds_read_b128 v[170:173], v243 offset:50176
	ds_read_b128 v[174:177], v243 offset:51200
	ds_read_b128 v[178:181], v243 offset:52224
	ds_read_b128 v[182:185], v243 offset:53248
	ds_read_b128 v[186:189], v243 offset:54272
	ds_read_b128 v[190:193], v243 offset:55296
	ds_read_b128 v[194:197], v243 offset:56320
	global_load_lds_dwordx4 v[126:127], off
	s_add_i32 m0, s0, 0x2000
	s_add_u32 s0, s6, 0x40080
	v_lshl_add_u64 v[126:127], v[200:201], 0, s[92:93]
	s_addc_u32 s1, s7, 0
	s_add_i32 s4, s5, s69
	global_load_lds_dwordx4 v[126:127], off
	s_mov_b32 m0, s4
	s_nop 0
	global_load_lds_dwordx4 v0, s[0:1]
	s_add_i32 m0, s4, 0x2000
	s_nop 0
	global_load_lds_dwordx4 v214, s[0:1]
	v_lshl_add_u64 v[126:127], v[206:207], 0, s[92:93]
	s_mov_b32 m0, s84
	s_nop 0
	global_load_lds_dwordx4 v[126:127], off
	v_lshl_add_u64 v[126:127], v[220:221], 0, s[92:93]
	s_mov_b32 m0, s85
	s_nop 0
	global_load_lds_dwordx4 v[126:127], off
	s_waitcnt vmcnt(8)
	s_waitcnt lgkmcnt(0)
	s_barrier
	s_waitcnt lgkmcnt(0)
	v_mfma_i32_16x16x64_i8 v[18:21], v[50:53], v[190:193], v[18:21]
	v_mfma_i32_16x16x64_i8 v[106:109], v[50:53], v[166:169], v[106:109]
	v_mfma_i32_16x16x64_i8 v[46:49], v[114:117], v[166:169], v[46:49]
	v_mfma_i32_16x16x64_i8 v[6:9], v[114:117], v[174:177], v[6:9]
	v_mfma_i32_16x16x64_i8 v[14:17], v[50:53], v[174:177], v[14:17]
	v_mfma_i32_16x16x64_i8 v[90:93], v[50:53], v[182:185], v[90:93]
	v_mfma_i32_16x16x64_i8 v[86:89], v[114:117], v[182:185], v[86:89]
	v_mfma_i32_16x16x64_i8 v[126:129], v[66:69], v[194:197], v[18:21]
	v_mfma_i32_16x16x64_i8 v[106:109], v[66:69], v[170:173], v[106:109]
	v_mfma_i32_16x16x64_i8 v[46:49], v[130:133], v[170:173], v[46:49]
	v_mfma_i32_16x16x64_i8 v[6:9], v[130:133], v[178:181], v[6:9]
	v_mfma_i32_16x16x64_i8 v[14:17], v[66:69], v[178:181], v[14:17]
	v_mfma_i32_16x16x64_i8 v[90:93], v[66:69], v[186:189], v[90:93]
	v_mfma_i32_16x16x64_i8 v[86:89], v[130:133], v[186:189], v[86:89]
	v_mfma_i32_16x16x64_i8 v[18:21], v[114:117], v[190:193], v[22:25]
	v_mfma_i32_16x16x64_i8 v[10:13], v[134:137], v[174:177], v[10:13]
	v_mfma_i32_16x16x64_i8 v[2:5], v[158:161], v[174:177], v[2:5]
	v_mfma_i32_16x16x64_i8 v[66:69], v[130:133], v[194:197], v[18:21]
	v_mfma_i32_16x16x64_i8 v[18:21], v[134:137], v[166:169], v[34:37]
	v_mfma_i32_16x16x64_i8 v[114:117], v[154:157], v[170:173], v[18:21]
	v_mfma_i32_16x16x64_i8 v[18:21], v[158:161], v[166:169], v[38:41]
	v_mfma_i32_16x16x64_i8 v[10:13], v[154:157], v[178:181], v[10:13]
	v_mfma_i32_16x16x64_i8 v[2:5], v[162:165], v[178:181], v[2:5]
	v_mfma_i32_16x16x64_i8 v[50:53], v[162:165], v[170:173], v[18:21]
	v_mfma_i32_16x16x64_i8 v[18:21], v[134:137], v[182:185], v[82:85]
	v_mfma_i32_16x16x64_i8 v[82:85], v[154:157], v[186:189], v[18:21]
	v_mfma_i32_16x16x64_i8 v[18:21], v[158:161], v[182:185], v[74:77]
	v_mfma_i32_16x16x64_i8 v[74:77], v[162:165], v[186:189], v[18:21]
	v_mfma_i32_16x16x64_i8 v[18:21], v[134:137], v[190:193], v[122:125]
	v_mfma_i32_16x16x64_i8 v[122:125], v[154:157], v[194:197], v[18:21]
	v_mfma_i32_16x16x64_i8 v[18:21], v[158:161], v[190:193], v[70:73]
	v_mfma_i32_16x16x64_i8 v[70:73], v[162:165], v[194:197], v[18:21]
	s_barrier
	s_add_i32 vcc_lo, vcc_lo, 2
	s_add_u32 s96, s96, 0x100
	s_addc_u32 s97, s97, 0
	s_cmp_gt_u32 vcc_lo, 13
	s_mov_b64 s[0:1], s[8:9]
	s_cbranch_scc0 .LBB0_80

; #define PG8_STAGE(bufoff, gbase, voff) do { _Pragma("unroll") for (int _i = 0; _i < 2; ++_i) \
;         __builtin_amdgcn_global_load_lds((const unsigned*)((const char*)(gbase) + (voff)[_i]), (PG8_LAS unsigned*)(lds + (bufoff) + ldsw + _i * 8192), 16, 0, 0); } while (0)
; #define PG8_LDA(dst, b, h) do { _Pragma("unroll") for (int m = 0; m < 4; ++m) _Pragma("unroll") for (int k = 0; k < 2; ++k) dst[m][k] = *(const PG8_LAS bf16x8*)(lds + PG8_SA(b, h) + aoff + m * 2048 + k * 1024); } while (0)
; #define PG8_LDB(dst, b, h) do { _Pragma("unroll") for (int n = 0; n < 2; ++n) _Pragma("unroll") for (int k = 0; k < 2; ++k) dst[n][k] = *(const PG8_LAS bf16x8*)(lds + PG8_SB(b, h) + boff + n * 2048 + k * 1024); } while (0)
; template <class Epi, class Sched, bool ALIGN_EPI = false, bool SP2 = false>
; __device__ __forceinline__ void gemm_phase(PG8_LAS unsigned char* lds, const Gemm g, const Sched& S, const Epi& E) {
;     ...
;         for (int t = 0; t < nt; t += 2) {
;             const bool last = (t == nt - 2);
;             const char* a1 = cA + (size_t)(t + 1) * kstep;
;             const char* a2 = last ? nA : cA + (size_t)(t + 2) * kstep; const char* b2 = last ? nB : cB + (size_t)(t + 2) * kstep;
;             const char* a3 = a2 + kstep; const char* b3 = b2 + kstep;
;             if (last && has_next) S.a_ready(nxt);
;             if constexpr (SP2) {
;             PG8_LDB(B0, 0, 0); PG8_LDB(B1, 0, 1); PG8_SCHED; PG8_LDA(At, 0, 0); PG8_STAGE(PG8_SA(1, 1), a1 + hstep, voffA);
;             PG8_WAIT_V(8); PG8_WAIT_L(0); PG8_BAR; PG8_MMA(0, 0, At, B0); PG8_MMA(0, 1, At, B1); PG8_BAR; PG8_SCHED;
;             PG8_LDA(At, 0, 1); PG8_STAGE(PG8_SB(0, 0), b2, voffB); PG8_STAGE(PG8_SB(0, 1), b2 + hstep, voffB); PG8_STAGE(PG8_SA(0, 0), a2, voffA);
;             PG8_WAIT_V(8); PG8_WAIT_L(0); PG8_BAR; PG8_MMA(1, 0, At, B0); PG8_MMA(1, 1, At, B1); PG8_BAR; PG8_SCHED;
;             PG8_LDB(B0, 1, 0); PG8_LDB(B1, 1, 1); PG8_SCHED; PG8_LDA(At, 1, 0); PG8_STAGE(PG8_SA(0, 1), a2 + hstep, voffA);
;             PG8_WAIT_V(8); PG8_WAIT_L(0); PG8_BAR; PG8_MMA(0, 0, At, B0); PG8_MMA(0, 1, At, B1); PG8_BAR; PG8_SCHED;
;             PG8_LDA(At, 1, 1); PG8_STAGE(PG8_SB(1, 0), b3, voffB); PG8_STAGE(PG8_SB(1, 1), b3 + hstep, voffB); PG8_STAGE(PG8_SA(1, 0), a3, voffA);
;             PG8_WAIT_V(8); PG8_WAIT_L(0); PG8_BAR; PG8_MMA(1, 0, At, B0); PG8_MMA(1, 1, At, B1); PG8_BAR; PG8_SCHED;
.Lpeel175:
	s_add_i32 vcc_lo, s8, 2
	s_add_u32 s4, s6, s98
	s_addc_u32 s5, s7, 0
	s_add_i32 vcc_hi, 0, 0x10000
	s_cmp_eq_u32 s13, s8
	s_cselect_b32 s9, s1, s5
	s_cselect_b32 s8, s0, s4
	s_cselect_b32 s5, s97, s85
	s_cselect_b32 s4, s96, s67
	s_add_i32 s84, 0, 0x14000
	v_add_u32_e32 v122, vcc_hi, v248
	v_add_u32_e32 v154, s84, v248
	ds_read_b128 v[98:101], v122
	ds_read_b128 v[102:105], v122 offset:1024
	ds_read_b128 v[114:117], v122 offset:2048
	ds_read_b128 v[122:125], v122 offset:3072
	ds_read_b128 v[130:133], v154
	ds_read_b128 v[138:141], v154 offset:1024
	ds_read_b128 v[146:149], v154 offset:2048
	ds_read_b128 v[154:157], v154 offset:3072
	v_lshl_add_u64 v[206:207], s[6:7], 0, v[200:201]
	s_add_i32 m0, s81, 0xc000
	ds_read_b128 v[162:165], v249
	ds_read_b128 v[166:169], v249 offset:1024
	ds_read_b128 v[170:173], v249 offset:2048
	ds_read_b128 v[174:177], v249 offset:3072
	ds_read_b128 v[178:181], v249 offset:4096
	ds_read_b128 v[182:185], v249 offset:5120
	ds_read_b128 v[186:189], v249 offset:6144
	ds_read_b128 v[190:193], v249 offset:7168
	global_load_lds_dwordx4 v[206:207], off
	v_lshl_add_u64 v[206:207], s[6:7], 0, v[210:211]
	s_add_i32 m0, s81, 0xe000
	s_nop 0
	global_load_lds_dwordx4 v[206:207], off
	s_waitcnt vmcnt(8)
	s_waitcnt lgkmcnt(0)
	s_barrier
	s_waitcnt lgkmcnt(0)
	v_mfma_f32_16x16x32_bf16 v[158:161], v[98:101], v[162:165], 0
	v_mfma_f32_16x16x32_bf16 v[150:153], v[114:117], v[162:165], 0
	v_mfma_f32_16x16x32_bf16 v[118:121], v[114:117], v[170:173], 0
	v_mfma_f32_16x16x32_bf16 v[126:129], v[98:101], v[170:173], 0
	v_mfma_f32_16x16x32_bf16 v[94:97], v[98:101], v[178:181], 0
	v_mfma_f32_16x16x32_bf16 v[90:93], v[114:117], v[178:181], 0
	v_mfma_f32_16x16x32_bf16 v[74:77], v[114:117], v[186:189], 0
	v_mfma_f32_16x16x32_bf16 v[78:81], v[98:101], v[186:189], 0
	v_mfma_f32_16x16x32_bf16 v[66:69], v[146:149], v[186:189], 0
	v_mfma_f32_16x16x32_bf16 v[134:137], v[146:149], v[162:165], 0
	v_mfma_f32_16x16x32_bf16 v[142:145], v[130:133], v[162:165], 0
	v_mfma_f32_16x16x32_bf16 v[110:113], v[130:133], v[170:173], 0
	v_mfma_f32_16x16x32_bf16 v[106:109], v[146:149], v[170:173], 0
	v_mfma_f32_16x16x32_bf16 v[82:85], v[146:149], v[178:181], 0
	v_mfma_f32_16x16x32_bf16 v[86:89], v[130:133], v[178:181], 0
	v_mfma_f32_16x16x32_bf16 v[70:73], v[130:133], v[186:189], 0
	v_mfma_f32_16x16x32_bf16 v[158:161], v[102:105], v[166:169], v[158:161]
	v_mfma_f32_16x16x32_bf16 v[150:153], v[122:125], v[166:169], v[150:153]
	v_mfma_f32_16x16x32_bf16 v[118:121], v[122:125], v[174:177], v[118:121]
	v_mfma_f32_16x16x32_bf16 v[126:129], v[102:105], v[174:177], v[126:129]
	v_mfma_f32_16x16x32_bf16 v[94:97], v[102:105], v[182:185], v[94:97]
	v_mfma_f32_16x16x32_bf16 v[90:93], v[122:125], v[182:185], v[90:93]
	v_mfma_f32_16x16x32_bf16 v[74:77], v[122:125], v[190:193], v[74:77]
	v_mfma_f32_16x16x32_bf16 v[78:81], v[102:105], v[190:193], v[78:81]
	v_mfma_f32_16x16x32_bf16 v[66:69], v[154:157], v[190:193], v[66:69]
	v_mfma_f32_16x16x32_bf16 v[134:137], v[154:157], v[166:169], v[134:137]
	v_mfma_f32_16x16x32_bf16 v[142:145], v[138:141], v[166:169], v[142:145]
	v_mfma_f32_16x16x32_bf16 v[110:113], v[138:141], v[174:177], v[110:113]
	v_mfma_f32_16x16x32_bf16 v[106:109], v[154:157], v[174:177], v[106:109]
	v_mfma_f32_16x16x32_bf16 v[82:85], v[154:157], v[182:185], v[82:85]
	v_mfma_f32_16x16x32_bf16 v[86:89], v[138:141], v[182:185], v[86:89]
	v_mfma_f32_16x16x32_bf16 v[70:73], v[138:141], v[190:193], v[70:73]
	s_barrier
	s_add_i32 vcc_hi, vcc_hi, s80
	v_lshl_add_u64 v[206:207], s[4:5], 0, v[0:1]
	s_mov_b32 m0, vcc_hi
	ds_read_b128 v[162:165], v249 offset:16384
	ds_read_b128 v[166:169], v249 offset:17408
	ds_read_b128 v[170:173], v249 offset:18432
	ds_read_b128 v[174:177], v249 offset:19456
	ds_read_b128 v[178:181], v249 offset:20480
	ds_read_b128 v[182:185], v249 offset:21504
	ds_read_b128 v[186:189], v249 offset:22528
	ds_read_b128 v[190:193], v249 offset:23552
	global_load_lds_dwordx4 v[206:207], off
	s_add_i32 m0, vcc_hi, 0x2000
	v_lshl_add_u64 v[212:213], s[4:5], 0, v[198:199]
	s_add_u32 s4, s4, s100
	s_addc_u32 s5, s5, 0
	s_add_i32 s84, s84, s80
	global_load_lds_dwordx4 v[212:213], off
	v_lshl_add_u64 v[214:215], s[4:5], 0, v[0:1]
	s_mov_b32 m0, s84
	v_lshl_add_u64 v[216:217], s[4:5], 0, v[198:199]
	global_load_lds_dwordx4 v[214:215], off
	s_add_i32 m0, s84, 0x2000
	v_lshl_add_u64 v[218:219], s[8:9], 0, v[194:195]
	global_load_lds_dwordx4 v[216:217], off
	s_mov_b32 m0, s81
	v_lshl_add_u64 v[220:221], s[8:9], 0, v[196:197]
	global_load_lds_dwordx4 v[218:219], off
	s_mov_b32 m0, s70
	s_nop 0
	global_load_lds_dwordx4 v[220:221], off
	s_waitcnt vmcnt(8)
	s_waitcnt lgkmcnt(0)
	s_barrier
; #define PG8_STAGE(bufoff, gbase, voff) do { _Pragma("unroll") for (int _i = 0; _i < 2; ++_i) \
;         __builtin_amdgcn_global_load_lds((const unsigned*)((const char*)(gbase) + (voff)[_i]), (PG8_LAS unsigned*)(lds + (bufoff) + ldsw + _i * 8192), 16, 0, 0); } while (0)
; #define PG8_LDA(dst, b, h) do { _Pragma("unroll") for (int m = 0; m < 4; ++m) _Pragma("unroll") for (int k = 0; k < 2; ++k) dst[m][k] = *(const PG8_LAS bf16x8*)(lds + PG8_SA(b, h) + aoff + m * 2048 + k * 1024); } while (0)
; #define PG8_LDB(dst, b, h) do { _Pragma("unroll") for (int n = 0; n < 2; ++n) _Pragma("unroll") for (int k = 0; k < 2; ++k) dst[n][k] = *(const PG8_LAS bf16x8*)(lds + PG8_SB(b, h) + boff + n * 2048 + k * 1024); } while (0)
; template <class Epi, class Sched, bool ALIGN_EPI = false, bool SP2 = false>
; __device__ __forceinline__ void gemm_phase(PG8_LAS unsigned char* lds, const Gemm g, const Sched& S, const Epi& E) {
;     ...
;         for (int t = 0; t < nt; t += 2) {
;             const bool last = (t == nt - 2);
;             const char* a1 = cA + (size_t)(t + 1) * kstep;
;             const char* a2 = last ? nA : cA + (size_t)(t + 2) * kstep; const char* b2 = last ? nB : cB + (size_t)(t + 2) * kstep;
;             const char* a3 = a2 + kstep; const char* b3 = b2 + kstep;
;             if (last && has_next) S.a_ready(nxt);
;             if constexpr (SP2) {
;             PG8_LDB(B0, 0, 0); PG8_LDB(B1, 0, 1); PG8_SCHED; PG8_LDA(At, 0, 0); PG8_STAGE(PG8_SA(1, 1), a1 + hstep, voffA);
;             PG8_WAIT_V(8); PG8_WAIT_L(0); PG8_BAR; PG8_MMA(0, 0, At, B0); PG8_MMA(0, 1, At, B1); PG8_BAR; PG8_SCHED;
;             PG8_LDA(At, 0, 1); PG8_STAGE(PG8_SB(0, 0), b2, voffB); PG8_STAGE(PG8_SB(0, 1), b2 + hstep, voffB); PG8_STAGE(PG8_SA(0, 0), a2, voffA);
;             PG8_WAIT_V(8); PG8_WAIT_L(0); PG8_BAR; PG8_MMA(1, 0, At, B0); PG8_MMA(1, 1, At, B1); PG8_BAR; PG8_SCHED;
;             PG8_LDB(B0, 1, 0); PG8_LDB(B1, 1, 1); PG8_SCHED; PG8_LDA(At, 1, 0); PG8_STAGE(PG8_SA(0, 1), a2 + hstep, voffA);
;             PG8_WAIT_V(8); PG8_WAIT_L(0); PG8_BAR; PG8_MMA(0, 0, At, B0); PG8_MMA(0, 1, At, B1); PG8_BAR; PG8_SCHED;
;             PG8_LDA(At, 1, 1); PG8_STAGE(PG8_SB(1, 0), b3, voffB); PG8_STAGE(PG8_SB(1, 1), b3 + hstep, voffB); PG8_STAGE(PG8_SA(1, 0), a3, voffA);
;             PG8_WAIT_V(8); PG8_WAIT_L(0); PG8_BAR; PG8_MMA(1, 0, At, B0); PG8_MMA(1, 1, At, B1); PG8_BAR; PG8_SCHED;
	s_waitcnt lgkmcnt(0)
	v_mfma_f32_16x16x32_bf16 v[62:65], v[98:101], v[162:165], 0
	v_mfma_f32_16x16x32_bf16 v[58:61], v[114:117], v[162:165], 0
	v_mfma_f32_16x16x32_bf16 v[42:45], v[114:117], v[170:173], 0
	v_mfma_f32_16x16x32_bf16 v[46:49], v[98:101], v[170:173], 0
	v_mfma_f32_16x16x32_bf16 v[30:33], v[98:101], v[178:181], 0
	v_mfma_f32_16x16x32_bf16 v[26:29], v[114:117], v[178:181], 0
	v_mfma_f32_16x16x32_bf16 v[10:13], v[114:117], v[186:189], 0
	v_mfma_f32_16x16x32_bf16 v[14:17], v[98:101], v[186:189], 0
	v_mfma_f32_16x16x32_bf16 v[2:5], v[146:149], v[186:189], 0
	v_mfma_f32_16x16x32_bf16 v[50:53], v[146:149], v[162:165], 0
	v_mfma_f32_16x16x32_bf16 v[54:57], v[130:133], v[162:165], 0
	v_mfma_f32_16x16x32_bf16 v[38:41], v[130:133], v[170:173], 0
	v_mfma_f32_16x16x32_bf16 v[34:37], v[146:149], v[170:173], 0
	v_mfma_f32_16x16x32_bf16 v[18:21], v[146:149], v[178:181], 0
	v_mfma_f32_16x16x32_bf16 v[22:25], v[130:133], v[178:181], 0
	v_mfma_f32_16x16x32_bf16 v[6:9], v[130:133], v[186:189], 0
	v_mfma_f32_16x16x32_bf16 v[62:65], v[102:105], v[166:169], v[62:65]
	v_mfma_f32_16x16x32_bf16 v[58:61], v[122:125], v[166:169], v[58:61]
	v_mfma_f32_16x16x32_bf16 v[42:45], v[122:125], v[174:177], v[42:45]
	v_mfma_f32_16x16x32_bf16 v[46:49], v[102:105], v[174:177], v[46:49]
	v_mfma_f32_16x16x32_bf16 v[30:33], v[102:105], v[182:185], v[30:33]
	v_mfma_f32_16x16x32_bf16 v[26:29], v[122:125], v[182:185], v[26:29]
	v_mfma_f32_16x16x32_bf16 v[10:13], v[122:125], v[190:193], v[10:13]
	v_mfma_f32_16x16x32_bf16 v[14:17], v[102:105], v[190:193], v[14:17]
	v_mfma_f32_16x16x32_bf16 v[2:5], v[154:157], v[190:193], v[2:5]
	v_mfma_f32_16x16x32_bf16 v[50:53], v[154:157], v[166:169], v[50:53]
	v_mfma_f32_16x16x32_bf16 v[54:57], v[138:141], v[166:169], v[54:57]
	v_mfma_f32_16x16x32_bf16 v[38:41], v[138:141], v[174:177], v[38:41]
	v_mfma_f32_16x16x32_bf16 v[34:37], v[154:157], v[174:177], v[34:37]
	v_mfma_f32_16x16x32_bf16 v[18:21], v[154:157], v[182:185], v[18:21]
	v_mfma_f32_16x16x32_bf16 v[22:25], v[138:141], v[182:185], v[22:25]
	v_mfma_f32_16x16x32_bf16 v[6:9], v[138:141], v[190:193], v[6:9]
	s_barrier
	s_add_i32 s84, 0, 0x18000
	s_add_i32 vcc_hi, 0, 0x1c000
	v_add_u32_e32 v122, s84, v248
	v_add_u32_e32 v154, vcc_hi, v248
	ds_read_b128 v[98:101], v122
	ds_read_b128 v[102:105], v122 offset:1024
	ds_read_b128 v[114:117], v122 offset:2048
	ds_read_b128 v[122:125], v122 offset:3072
	ds_read_b128 v[130:133], v154
	ds_read_b128 v[138:141], v154 offset:1024
	ds_read_b128 v[146:149], v154 offset:2048
	ds_read_b128 v[154:157], v154 offset:3072
	s_add_u32 s4, s8, s100
	s_addc_u32 s5, s9, 0
	s_mov_b32 m0, s71
	v_lshl_add_u64 v[222:223], s[4:5], 0, v[194:195]
	ds_read_b128 v[162:165], v249 offset:32768
	ds_read_b128 v[166:169], v249 offset:33792
	ds_read_b128 v[170:173], v249 offset:34816
	ds_read_b128 v[174:177], v249 offset:35840
	ds_read_b128 v[178:181], v249 offset:36864
	ds_read_b128 v[182:185], v249 offset:37888
	ds_read_b128 v[186:189], v249 offset:38912
	ds_read_b128 v[190:193], v249 offset:39936
	global_load_lds_dwordx4 v[222:223], off
	v_lshl_add_u64 v[222:223], s[4:5], 0, v[196:197]
	s_mov_b32 m0, s12
	s_nop 0
	global_load_lds_dwordx4 v[222:223], off
	s_waitcnt vmcnt(8)
	s_waitcnt lgkmcnt(0)
	s_barrier
	s_waitcnt lgkmcnt(0)
	v_mfma_f32_16x16x32_bf16 v[158:161], v[98:101], v[162:165], v[158:161]
	v_mfma_f32_16x16x32_bf16 v[150:153], v[114:117], v[162:165], v[150:153]
	v_mfma_f32_16x16x32_bf16 v[118:121], v[114:117], v[170:173], v[118:121]
	v_mfma_f32_16x16x32_bf16 v[126:129], v[98:101], v[170:173], v[126:129]
	v_mfma_f32_16x16x32_bf16 v[94:97], v[98:101], v[178:181], v[94:97]
	v_mfma_f32_16x16x32_bf16 v[90:93], v[114:117], v[178:181], v[90:93]
	v_mfma_f32_16x16x32_bf16 v[74:77], v[114:117], v[186:189], v[74:77]
	v_mfma_f32_16x16x32_bf16 v[78:81], v[98:101], v[186:189], v[78:81]
	v_mfma_f32_16x16x32_bf16 v[66:69], v[146:149], v[186:189], v[66:69]
	v_mfma_f32_16x16x32_bf16 v[134:137], v[146:149], v[162:165], v[134:137]
	v_mfma_f32_16x16x32_bf16 v[142:145], v[130:133], v[162:165], v[142:145]
	v_mfma_f32_16x16x32_bf16 v[110:113], v[130:133], v[170:173], v[110:113]
	v_mfma_f32_16x16x32_bf16 v[106:109], v[146:149], v[170:173], v[106:109]
	v_mfma_f32_16x16x32_bf16 v[82:85], v[146:149], v[178:181], v[82:85]
	v_mfma_f32_16x16x32_bf16 v[86:89], v[130:133], v[178:181], v[86:89]
	v_mfma_f32_16x16x32_bf16 v[70:73], v[130:133], v[186:189], v[70:73]
	v_mfma_f32_16x16x32_bf16 v[158:161], v[102:105], v[166:169], v[158:161]
	v_mfma_f32_16x16x32_bf16 v[150:153], v[122:125], v[166:169], v[150:153]
	v_mfma_f32_16x16x32_bf16 v[118:121], v[122:125], v[174:177], v[118:121]
	v_mfma_f32_16x16x32_bf16 v[126:129], v[102:105], v[174:177], v[126:129]
	v_mfma_f32_16x16x32_bf16 v[94:97], v[102:105], v[182:185], v[94:97]
	v_mfma_f32_16x16x32_bf16 v[90:93], v[122:125], v[182:185], v[90:93]
	v_mfma_f32_16x16x32_bf16 v[74:77], v[122:125], v[190:193], v[74:77]
	v_mfma_f32_16x16x32_bf16 v[78:81], v[102:105], v[190:193], v[78:81]
	v_mfma_f32_16x16x32_bf16 v[66:69], v[154:157], v[190:193], v[66:69]
	v_mfma_f32_16x16x32_bf16 v[134:137], v[154:157], v[166:169], v[134:137]
	v_mfma_f32_16x16x32_bf16 v[142:145], v[138:141], v[166:169], v[142:145]
	v_mfma_f32_16x16x32_bf16 v[110:113], v[138:141], v[174:177], v[110:113]
	v_mfma_f32_16x16x32_bf16 v[106:109], v[154:157], v[174:177], v[106:109]
	v_mfma_f32_16x16x32_bf16 v[82:85], v[154:157], v[182:185], v[82:85]
	v_mfma_f32_16x16x32_bf16 v[86:89], v[138:141], v[182:185], v[86:89]
	v_mfma_f32_16x16x32_bf16 v[70:73], v[138:141], v[190:193], v[70:73]
	s_barrier
; #define PG8_STAGE(bufoff, gbase, voff) do { _Pragma("unroll") for (int _i = 0; _i < 2; ++_i) \
;         __builtin_amdgcn_global_load_lds((const unsigned*)((const char*)(gbase) + (voff)[_i]), (PG8_LAS unsigned*)(lds + (bufoff) + ldsw + _i * 8192), 16, 0, 0); } while (0)
; #define PG8_LDA(dst, b, h) do { _Pragma("unroll") for (int m = 0; m < 4; ++m) _Pragma("unroll") for (int k = 0; k < 2; ++k) dst[m][k] = *(const PG8_LAS bf16x8*)(lds + PG8_SA(b, h) + aoff + m * 2048 + k * 1024); } while (0)
; #define PG8_LDB(dst, b, h) do { _Pragma("unroll") for (int n = 0; n < 2; ++n) _Pragma("unroll") for (int k = 0; k < 2; ++k) dst[n][k] = *(const PG8_LAS bf16x8*)(lds + PG8_SB(b, h) + boff + n * 2048 + k * 1024); } while (0)
; template <class Epi, class Sched, bool ALIGN_EPI = false, bool SP2 = false>
; __device__ __forceinline__ void gemm_phase(PG8_LAS unsigned char* lds, const Gemm g, const Sched& S, const Epi& E) {
;     ...
;         for (int t = 0; t < nt; t += 2) {
;             const bool last = (t == nt - 2);
;             const char* a1 = cA + (size_t)(t + 1) * kstep;
;             const char* a2 = last ? nA : cA + (size_t)(t + 2) * kstep; const char* b2 = last ? nB : cB + (size_t)(t + 2) * kstep;
;             const char* a3 = a2 + kstep; const char* b3 = b2 + kstep;
;             if (last && has_next) S.a_ready(nxt);
;             if constexpr (SP2) {
;             PG8_LDB(B0, 0, 0); PG8_LDB(B1, 0, 1); PG8_SCHED; PG8_LDA(At, 0, 0); PG8_STAGE(PG8_SA(1, 1), a1 + hstep, voffA);
;             PG8_WAIT_V(8); PG8_WAIT_L(0); PG8_BAR; PG8_MMA(0, 0, At, B0); PG8_MMA(0, 1, At, B1); PG8_BAR; PG8_SCHED;
;             PG8_LDA(At, 0, 1); PG8_STAGE(PG8_SB(0, 0), b2, voffB); PG8_STAGE(PG8_SB(0, 1), b2 + hstep, voffB); PG8_STAGE(PG8_SA(0, 0), a2, voffA);
;             PG8_WAIT_V(8); PG8_WAIT_L(0); PG8_BAR; PG8_MMA(1, 0, At, B0); PG8_MMA(1, 1, At, B1); PG8_BAR; PG8_SCHED;
;             PG8_LDB(B0, 1, 0); PG8_LDB(B1, 1, 1); PG8_SCHED; PG8_LDA(At, 1, 0); PG8_STAGE(PG8_SA(0, 1), a2 + hstep, voffA);
;             PG8_WAIT_V(8); PG8_WAIT_L(0); PG8_BAR; PG8_MMA(0, 0, At, B0); PG8_MMA(0, 1, At, B1); PG8_BAR; PG8_SCHED;
;             PG8_LDA(At, 1, 1); PG8_STAGE(PG8_SB(1, 0), b3, voffB); PG8_STAGE(PG8_SB(1, 1), b3 + hstep, voffB); PG8_STAGE(PG8_SA(1, 0), a3, voffA);
;             PG8_WAIT_V(8); PG8_WAIT_L(0); PG8_BAR; PG8_MMA(1, 0, At, B0); PG8_MMA(1, 1, At, B1); PG8_BAR; PG8_SCHED;
	s_add_i32 s4, s84, s80
	v_lshl_add_u64 v[206:207], v[206:207], 0, s[98:99]
	s_mov_b32 m0, s4
	ds_read_b128 v[162:165], v249 offset:49152
	ds_read_b128 v[166:169], v249 offset:50176
	ds_read_b128 v[170:173], v249 offset:51200
	ds_read_b128 v[174:177], v249 offset:52224
	ds_read_b128 v[178:181], v249 offset:53248
	ds_read_b128 v[182:185], v249 offset:54272
	ds_read_b128 v[186:189], v249 offset:55296
	ds_read_b128 v[190:193], v249 offset:56320
	global_load_lds_dwordx4 v[206:207], off
	v_lshl_add_u64 v[206:207], v[212:213], 0, s[98:99]
	s_add_i32 m0, s4, 0x2000
	s_add_i32 s4, vcc_hi, s80
	global_load_lds_dwordx4 v[206:207], off
	v_lshl_add_u64 v[206:207], v[214:215], 0, s[98:99]
	s_mov_b32 m0, s4
	s_nop 0
	global_load_lds_dwordx4 v[206:207], off
	v_lshl_add_u64 v[206:207], v[216:217], 0, s[98:99]
	s_add_i32 m0, s4, 0x2000
	s_nop 0
	global_load_lds_dwordx4 v[206:207], off
	v_lshl_add_u64 v[206:207], v[218:219], 0, s[98:99]
	s_mov_b32 m0, s10
	s_nop 0
	global_load_lds_dwordx4 v[206:207], off
	v_lshl_add_u64 v[206:207], v[220:221], 0, s[98:99]
	s_mov_b32 m0, s11
	s_nop 0
	global_load_lds_dwordx4 v[206:207], off
	s_waitcnt vmcnt(8)
	s_waitcnt lgkmcnt(0)
	s_barrier
	s_waitcnt lgkmcnt(0)
	v_mfma_f32_16x16x32_bf16 v[62:65], v[98:101], v[162:165], v[62:65]
	v_mfma_f32_16x16x32_bf16 v[58:61], v[114:117], v[162:165], v[58:61]
	v_mfma_f32_16x16x32_bf16 v[42:45], v[114:117], v[170:173], v[42:45]
	v_mfma_f32_16x16x32_bf16 v[46:49], v[98:101], v[170:173], v[46:49]
	v_mfma_f32_16x16x32_bf16 v[30:33], v[98:101], v[178:181], v[30:33]
	v_mfma_f32_16x16x32_bf16 v[26:29], v[114:117], v[178:181], v[26:29]
	v_mfma_f32_16x16x32_bf16 v[10:13], v[114:117], v[186:189], v[10:13]
	v_mfma_f32_16x16x32_bf16 v[14:17], v[98:101], v[186:189], v[14:17]
	v_mfma_f32_16x16x32_bf16 v[2:5], v[146:149], v[186:189], v[2:5]
	v_mfma_f32_16x16x32_bf16 v[50:53], v[146:149], v[162:165], v[50:53]
	v_mfma_f32_16x16x32_bf16 v[54:57], v[130:133], v[162:165], v[54:57]
	v_mfma_f32_16x16x32_bf16 v[38:41], v[130:133], v[170:173], v[38:41]
	v_mfma_f32_16x16x32_bf16 v[34:37], v[146:149], v[170:173], v[34:37]
	v_mfma_f32_16x16x32_bf16 v[18:21], v[146:149], v[178:181], v[18:21]
	v_mfma_f32_16x16x32_bf16 v[22:25], v[130:133], v[178:181], v[22:25]
	v_mfma_f32_16x16x32_bf16 v[6:9], v[130:133], v[186:189], v[6:9]
	v_mfma_f32_16x16x32_bf16 v[62:65], v[102:105], v[166:169], v[62:65]
	v_mfma_f32_16x16x32_bf16 v[58:61], v[122:125], v[166:169], v[58:61]
	v_mfma_f32_16x16x32_bf16 v[42:45], v[122:125], v[174:177], v[42:45]
	v_mfma_f32_16x16x32_bf16 v[46:49], v[102:105], v[174:177], v[46:49]
	v_mfma_f32_16x16x32_bf16 v[30:33], v[102:105], v[182:185], v[30:33]
	v_mfma_f32_16x16x32_bf16 v[26:29], v[122:125], v[182:185], v[26:29]
	v_mfma_f32_16x16x32_bf16 v[10:13], v[122:125], v[190:193], v[10:13]
	v_mfma_f32_16x16x32_bf16 v[14:17], v[102:105], v[190:193], v[14:17]
	v_mfma_f32_16x16x32_bf16 v[2:5], v[154:157], v[190:193], v[2:5]
	v_mfma_f32_16x16x32_bf16 v[50:53], v[154:157], v[166:169], v[50:53]
	v_mfma_f32_16x16x32_bf16 v[54:57], v[138:141], v[166:169], v[54:57]
	v_mfma_f32_16x16x32_bf16 v[38:41], v[138:141], v[174:177], v[38:41]
	v_mfma_f32_16x16x32_bf16 v[34:37], v[154:157], v[174:177], v[34:37]
	v_mfma_f32_16x16x32_bf16 v[18:21], v[154:157], v[182:185], v[18:21]
	v_mfma_f32_16x16x32_bf16 v[22:25], v[138:141], v[182:185], v[22:25]
	v_mfma_f32_16x16x32_bf16 v[6:9], v[138:141], v[190:193], v[6:9]
	s_barrier
	s_add_u32 s6, s6, s98
	s_addc_u32 s7, s7, 0
	s_add_u32 s6, s6, s98
	s_addc_u32 s7, s7, 0
	s_add_u32 s67, s67, s98
	s_addc_u32 s85, s85, 0
	s_add_u32 s67, s67, s98
	s_addc_u32 s85, s85, 0
	s_cmp_ge_u32 vcc_lo, s69
	s_mov_b32 s8, vcc_lo
	s_cbranch_scc0 .LBB0_175
	s_branch .Lpeelx175
.LBB0_175:
	s_add_i32 vcc_lo, s8, 2
	s_add_u32 s4, s6, s98
	s_addc_u32 s5, s7, 0
	s_add_i32 vcc_hi, 0, 0x10000
	s_cmp_eq_u32 s13, s8
	s_cselect_b32 s9, s1, s5
	s_cselect_b32 s8, s0, s4
	s_cselect_b32 s5, s97, s85
	s_cselect_b32 s4, s96, s67
	s_add_i32 s84, 0, 0x14000
	v_add_u32_e32 v122, vcc_hi, v248
	v_add_u32_e32 v154, s84, v248
	ds_read_b128 v[98:101], v122
	ds_read_b128 v[102:105], v122 offset:1024
	ds_read_b128 v[114:117], v122 offset:2048
	ds_read_b128 v[122:125], v122 offset:3072
	ds_read_b128 v[130:133], v154
	ds_read_b128 v[138:141], v154 offset:1024
	ds_read_b128 v[146:149], v154 offset:2048
	ds_read_b128 v[154:157], v154 offset:3072
	v_lshl_add_u64 v[206:207], s[6:7], 0, v[200:201]
	s_add_i32 m0, s81, 0xc000
	ds_read_b128 v[162:165], v249
	ds_read_b128 v[166:169], v249 offset:1024
	ds_read_b128 v[170:173], v249 offset:2048
	ds_read_b128 v[174:177], v249 offset:3072
	ds_read_b128 v[178:181], v249 offset:4096
	ds_read_b128 v[182:185], v249 offset:5120
	ds_read_b128 v[186:189], v249 offset:6144
	ds_read_b128 v[190:193], v249 offset:7168
	global_load_lds_dwordx4 v[206:207], off
	v_lshl_add_u64 v[206:207], s[6:7], 0, v[210:211]
	s_add_i32 m0, s81, 0xe000
	s_nop 0
	global_load_lds_dwordx4 v[206:207], off
	s_waitcnt vmcnt(8)
	s_waitcnt lgkmcnt(0)
	s_barrier
; #define PG8_STAGE(bufoff, gbase, voff) do { _Pragma("unroll") for (int _i = 0; _i < 2; ++_i) \
;         __builtin_amdgcn_global_load_lds((const unsigned*)((const char*)(gbase) + (voff)[_i]), (PG8_LAS unsigned*)(lds + (bufoff) + ldsw + _i * 8192), 16, 0, 0); } while (0)
; #define PG8_LDA(dst, b, h) do { _Pragma("unroll") for (int m = 0; m < 4; ++m) _Pragma("unroll") for (int k = 0; k < 2; ++k) dst[m][k] = *(const PG8_LAS bf16x8*)(lds + PG8_SA(b, h) + aoff + m * 2048 + k * 1024); } while (0)
; #define PG8_LDB(dst, b, h) do { _Pragma("unroll") for (int n = 0; n < 2; ++n) _Pragma("unroll") for (int k = 0; k < 2; ++k) dst[n][k] = *(const PG8_LAS bf16x8*)(lds + PG8_SB(b, h) + boff + n * 2048 + k * 1024); } while (0)
; template <class Epi, class Sched, bool ALIGN_EPI = false, bool SP2 = false>
; __device__ __forceinline__ void gemm_phase(PG8_LAS unsigned char* lds, const Gemm g, const Sched& S, const Epi& E) {
;     ...
;         for (int t = 0; t < nt; t += 2) {
;             const bool last = (t == nt - 2);
;             const char* a1 = cA + (size_t)(t + 1) * kstep;
;             const char* a2 = last ? nA : cA + (size_t)(t + 2) * kstep; const char* b2 = last ? nB : cB + (size_t)(t + 2) * kstep;
;             const char* a3 = a2 + kstep; const char* b3 = b2 + kstep;
;             if (last && has_next) S.a_ready(nxt);
;             if constexpr (SP2) {
;             PG8_LDB(B0, 0, 0); PG8_LDB(B1, 0, 1); PG8_SCHED; PG8_LDA(At, 0, 0); PG8_STAGE(PG8_SA(1, 1), a1 + hstep, voffA);
;             PG8_WAIT_V(8); PG8_WAIT_L(0); PG8_BAR; PG8_MMA(0, 0, At, B0); PG8_MMA(0, 1, At, B1); PG8_BAR; PG8_SCHED;
;             PG8_LDA(At, 0, 1); PG8_STAGE(PG8_SB(0, 0), b2, voffB); PG8_STAGE(PG8_SB(0, 1), b2 + hstep, voffB); PG8_STAGE(PG8_SA(0, 0), a2, voffA);
;             PG8_WAIT_V(8); PG8_WAIT_L(0); PG8_BAR; PG8_MMA(1, 0, At, B0); PG8_MMA(1, 1, At, B1); PG8_BAR; PG8_SCHED;
;             PG8_LDB(B0, 1, 0); PG8_LDB(B1, 1, 1); PG8_SCHED; PG8_LDA(At, 1, 0); PG8_STAGE(PG8_SA(0, 1), a2 + hstep, voffA);
;             PG8_WAIT_V(8); PG8_WAIT_L(0); PG8_BAR; PG8_MMA(0, 0, At, B0); PG8_MMA(0, 1, At, B1); PG8_BAR; PG8_SCHED;
;             PG8_LDA(At, 1, 1); PG8_STAGE(PG8_SB(1, 0), b3, voffB); PG8_STAGE(PG8_SB(1, 1), b3 + hstep, voffB); PG8_STAGE(PG8_SA(1, 0), a3, voffA);
;             PG8_WAIT_V(8); PG8_WAIT_L(0); PG8_BAR; PG8_MMA(1, 0, At, B0); PG8_MMA(1, 1, At, B1); PG8_BAR; PG8_SCHED;
	s_waitcnt lgkmcnt(0)
	v_mfma_f32_16x16x32_bf16 v[158:161], v[98:101], v[162:165], v[158:161]
	v_mfma_f32_16x16x32_bf16 v[150:153], v[114:117], v[162:165], v[150:153]
	v_mfma_f32_16x16x32_bf16 v[118:121], v[114:117], v[170:173], v[118:121]
	v_mfma_f32_16x16x32_bf16 v[126:129], v[98:101], v[170:173], v[126:129]
	v_mfma_f32_16x16x32_bf16 v[94:97], v[98:101], v[178:181], v[94:97]
	v_mfma_f32_16x16x32_bf16 v[90:93], v[114:117], v[178:181], v[90:93]
	v_mfma_f32_16x16x32_bf16 v[74:77], v[114:117], v[186:189], v[74:77]
	v_mfma_f32_16x16x32_bf16 v[78:81], v[98:101], v[186:189], v[78:81]
	v_mfma_f32_16x16x32_bf16 v[66:69], v[146:149], v[186:189], v[66:69]
	v_mfma_f32_16x16x32_bf16 v[134:137], v[146:149], v[162:165], v[134:137]
	v_mfma_f32_16x16x32_bf16 v[142:145], v[130:133], v[162:165], v[142:145]
	v_mfma_f32_16x16x32_bf16 v[110:113], v[130:133], v[170:173], v[110:113]
	v_mfma_f32_16x16x32_bf16 v[106:109], v[146:149], v[170:173], v[106:109]
	v_mfma_f32_16x16x32_bf16 v[82:85], v[146:149], v[178:181], v[82:85]
	v_mfma_f32_16x16x32_bf16 v[86:89], v[130:133], v[178:181], v[86:89]
	v_mfma_f32_16x16x32_bf16 v[70:73], v[130:133], v[186:189], v[70:73]
	v_mfma_f32_16x16x32_bf16 v[158:161], v[102:105], v[166:169], v[158:161]
	v_mfma_f32_16x16x32_bf16 v[150:153], v[122:125], v[166:169], v[150:153]
	v_mfma_f32_16x16x32_bf16 v[118:121], v[122:125], v[174:177], v[118:121]
	v_mfma_f32_16x16x32_bf16 v[126:129], v[102:105], v[174:177], v[126:129]
	v_mfma_f32_16x16x32_bf16 v[94:97], v[102:105], v[182:185], v[94:97]
	v_mfma_f32_16x16x32_bf16 v[90:93], v[122:125], v[182:185], v[90:93]
	v_mfma_f32_16x16x32_bf16 v[74:77], v[122:125], v[190:193], v[74:77]
	v_mfma_f32_16x16x32_bf16 v[78:81], v[102:105], v[190:193], v[78:81]
	v_mfma_f32_16x16x32_bf16 v[66:69], v[154:157], v[190:193], v[66:69]
	v_mfma_f32_16x16x32_bf16 v[134:137], v[154:157], v[166:169], v[134:137]
	v_mfma_f32_16x16x32_bf16 v[142:145], v[138:141], v[166:169], v[142:145]
	v_mfma_f32_16x16x32_bf16 v[110:113], v[138:141], v[174:177], v[110:113]
	v_mfma_f32_16x16x32_bf16 v[106:109], v[154:157], v[174:177], v[106:109]
	v_mfma_f32_16x16x32_bf16 v[82:85], v[154:157], v[182:185], v[82:85]
	v_mfma_f32_16x16x32_bf16 v[86:89], v[138:141], v[182:185], v[86:89]
	v_mfma_f32_16x16x32_bf16 v[70:73], v[138:141], v[190:193], v[70:73]
	s_barrier
	s_add_i32 vcc_hi, vcc_hi, s80
	v_lshl_add_u64 v[206:207], s[4:5], 0, v[0:1]
	s_mov_b32 m0, vcc_hi
	ds_read_b128 v[162:165], v249 offset:16384
	ds_read_b128 v[166:169], v249 offset:17408
	ds_read_b128 v[170:173], v249 offset:18432
	ds_read_b128 v[174:177], v249 offset:19456
	ds_read_b128 v[178:181], v249 offset:20480
	ds_read_b128 v[182:185], v249 offset:21504
	ds_read_b128 v[186:189], v249 offset:22528
	ds_read_b128 v[190:193], v249 offset:23552
	global_load_lds_dwordx4 v[206:207], off
	s_add_i32 m0, vcc_hi, 0x2000
	v_lshl_add_u64 v[212:213], s[4:5], 0, v[198:199]
	s_add_u32 s4, s4, s100
	s_addc_u32 s5, s5, 0
	s_add_i32 s84, s84, s80
	global_load_lds_dwordx4 v[212:213], off
	v_lshl_add_u64 v[214:215], s[4:5], 0, v[0:1]
	s_mov_b32 m0, s84
	v_lshl_add_u64 v[216:217], s[4:5], 0, v[198:199]
	global_load_lds_dwordx4 v[214:215], off
	s_add_i32 m0, s84, 0x2000
	v_lshl_add_u64 v[218:219], s[8:9], 0, v[194:195]
	global_load_lds_dwordx4 v[216:217], off
	s_mov_b32 m0, s81
	v_lshl_add_u64 v[220:221], s[8:9], 0, v[196:197]
	global_load_lds_dwordx4 v[218:219], off
	s_mov_b32 m0, s70
	s_nop 0
	global_load_lds_dwordx4 v[220:221], off
	s_waitcnt vmcnt(8)
	s_waitcnt lgkmcnt(0)
	s_barrier
	s_waitcnt lgkmcnt(0)
	v_mfma_f32_16x16x32_bf16 v[62:65], v[98:101], v[162:165], v[62:65]
	v_mfma_f32_16x16x32_bf16 v[58:61], v[114:117], v[162:165], v[58:61]
	v_mfma_f32_16x16x32_bf16 v[42:45], v[114:117], v[170:173], v[42:45]
	v_mfma_f32_16x16x32_bf16 v[46:49], v[98:101], v[170:173], v[46:49]
	v_mfma_f32_16x16x32_bf16 v[30:33], v[98:101], v[178:181], v[30:33]
	v_mfma_f32_16x16x32_bf16 v[26:29], v[114:117], v[178:181], v[26:29]
	v_mfma_f32_16x16x32_bf16 v[10:13], v[114:117], v[186:189], v[10:13]
	v_mfma_f32_16x16x32_bf16 v[14:17], v[98:101], v[186:189], v[14:17]
	v_mfma_f32_16x16x32_bf16 v[2:5], v[146:149], v[186:189], v[2:5]
	v_mfma_f32_16x16x32_bf16 v[50:53], v[146:149], v[162:165], v[50:53]
	v_mfma_f32_16x16x32_bf16 v[54:57], v[130:133], v[162:165], v[54:57]
	v_mfma_f32_16x16x32_bf16 v[38:41], v[130:133], v[170:173], v[38:41]
	v_mfma_f32_16x16x32_bf16 v[34:37], v[146:149], v[170:173], v[34:37]
	v_mfma_f32_16x16x32_bf16 v[18:21], v[146:149], v[178:181], v[18:21]
	v_mfma_f32_16x16x32_bf16 v[22:25], v[130:133], v[178:181], v[22:25]
	v_mfma_f32_16x16x32_bf16 v[6:9], v[130:133], v[186:189], v[6:9]
	v_mfma_f32_16x16x32_bf16 v[62:65], v[102:105], v[166:169], v[62:65]
	v_mfma_f32_16x16x32_bf16 v[58:61], v[122:125], v[166:169], v[58:61]
	v_mfma_f32_16x16x32_bf16 v[42:45], v[122:125], v[174:177], v[42:45]
	v_mfma_f32_16x16x32_bf16 v[46:49], v[102:105], v[174:177], v[46:49]
	v_mfma_f32_16x16x32_bf16 v[30:33], v[102:105], v[182:185], v[30:33]
	v_mfma_f32_16x16x32_bf16 v[26:29], v[122:125], v[182:185], v[26:29]
	v_mfma_f32_16x16x32_bf16 v[10:13], v[122:125], v[190:193], v[10:13]
	v_mfma_f32_16x16x32_bf16 v[14:17], v[102:105], v[190:193], v[14:17]
	v_mfma_f32_16x16x32_bf16 v[2:5], v[154:157], v[190:193], v[2:5]
	v_mfma_f32_16x16x32_bf16 v[50:53], v[154:157], v[166:169], v[50:53]
	v_mfma_f32_16x16x32_bf16 v[54:57], v[138:141], v[166:169], v[54:57]
	v_mfma_f32_16x16x32_bf16 v[38:41], v[138:141], v[174:177], v[38:41]
	v_mfma_f32_16x16x32_bf16 v[34:37], v[154:157], v[174:177], v[34:37]
	v_mfma_f32_16x16x32_bf16 v[18:21], v[154:157], v[182:185], v[18:21]
	v_mfma_f32_16x16x32_bf16 v[22:25], v[138:141], v[182:185], v[22:25]
	v_mfma_f32_16x16x32_bf16 v[6:9], v[138:141], v[190:193], v[6:9]
	s_barrier
; #define PG8_STAGE(bufoff, gbase, voff) do { _Pragma("unroll") for (int _i = 0; _i < 2; ++_i) \
;         __builtin_amdgcn_global_load_lds((const unsigned*)((const char*)(gbase) + (voff)[_i]), (PG8_LAS unsigned*)(lds + (bufoff) + ldsw + _i * 8192), 16, 0, 0); } while (0)
; #define PG8_LDA(dst, b, h) do { _Pragma("unroll") for (int m = 0; m < 4; ++m) _Pragma("unroll") for (int k = 0; k < 2; ++k) dst[m][k] = *(const PG8_LAS bf16x8*)(lds + PG8_SA(b, h) + aoff + m * 2048 + k * 1024); } while (0)
; #define PG8_LDB(dst, b, h) do { _Pragma("unroll") for (int n = 0; n < 2; ++n) _Pragma("unroll") for (int k = 0; k < 2; ++k) dst[n][k] = *(const PG8_LAS bf16x8*)(lds + PG8_SB(b, h) + boff + n * 2048 + k * 1024); } while (0)
; template <class Epi, class Sched, bool ALIGN_EPI = false, bool SP2 = false>
; __device__ __forceinline__ void gemm_phase(PG8_LAS unsigned char* lds, const Gemm g, const Sched& S, const Epi& E) {
;     ...
;         for (int t = 0; t < nt; t += 2) {
;             const bool last = (t == nt - 2);
;             const char* a1 = cA + (size_t)(t + 1) * kstep;
;             const char* a2 = last ? nA : cA + (size_t)(t + 2) * kstep; const char* b2 = last ? nB : cB + (size_t)(t + 2) * kstep;
;             const char* a3 = a2 + kstep; const char* b3 = b2 + kstep;
;             if (last && has_next) S.a_ready(nxt);
;             if constexpr (SP2) {
;             PG8_LDB(B0, 0, 0); PG8_LDB(B1, 0, 1); PG8_SCHED; PG8_LDA(At, 0, 0); PG8_STAGE(PG8_SA(1, 1), a1 + hstep, voffA);
;             PG8_WAIT_V(8); PG8_WAIT_L(0); PG8_BAR; PG8_MMA(0, 0, At, B0); PG8_MMA(0, 1, At, B1); PG8_BAR; PG8_SCHED;
;             PG8_LDA(At, 0, 1); PG8_STAGE(PG8_SB(0, 0), b2, voffB); PG8_STAGE(PG8_SB(0, 1), b2 + hstep, voffB); PG8_STAGE(PG8_SA(0, 0), a2, voffA);
;             PG8_WAIT_V(8); PG8_WAIT_L(0); PG8_BAR; PG8_MMA(1, 0, At, B0); PG8_MMA(1, 1, At, B1); PG8_BAR; PG8_SCHED;
;             PG8_LDB(B0, 1, 0); PG8_LDB(B1, 1, 1); PG8_SCHED; PG8_LDA(At, 1, 0); PG8_STAGE(PG8_SA(0, 1), a2 + hstep, voffA);
;             PG8_WAIT_V(8); PG8_WAIT_L(0); PG8_BAR; PG8_MMA(0, 0, At, B0); PG8_MMA(0, 1, At, B1); PG8_BAR; PG8_SCHED;
;             PG8_LDA(At, 1, 1); PG8_STAGE(PG8_SB(1, 0), b3, voffB); PG8_STAGE(PG8_SB(1, 1), b3 + hstep, voffB); PG8_STAGE(PG8_SA(1, 0), a3, voffA);
;             PG8_WAIT_V(8); PG8_WAIT_L(0); PG8_BAR; PG8_MMA(1, 0, At, B0); PG8_MMA(1, 1, At, B1); PG8_BAR; PG8_SCHED;
	s_add_i32 s84, 0, 0x18000
	s_add_i32 vcc_hi, 0, 0x1c000
	v_add_u32_e32 v122, s84, v248
	v_add_u32_e32 v154, vcc_hi, v248
	ds_read_b128 v[98:101], v122
	ds_read_b128 v[102:105], v122 offset:1024
	ds_read_b128 v[114:117], v122 offset:2048
	ds_read_b128 v[122:125], v122 offset:3072
	ds_read_b128 v[130:133], v154
	ds_read_b128 v[138:141], v154 offset:1024
	ds_read_b128 v[146:149], v154 offset:2048
	ds_read_b128 v[154:157], v154 offset:3072
	s_add_u32 s4, s8, s100
	s_addc_u32 s5, s9, 0
	s_mov_b32 m0, s71
	v_lshl_add_u64 v[222:223], s[4:5], 0, v[194:195]
	ds_read_b128 v[162:165], v249 offset:32768
	ds_read_b128 v[166:169], v249 offset:33792
	ds_read_b128 v[170:173], v249 offset:34816
	ds_read_b128 v[174:177], v249 offset:35840
	ds_read_b128 v[178:181], v249 offset:36864
	ds_read_b128 v[182:185], v249 offset:37888
	ds_read_b128 v[186:189], v249 offset:38912
	ds_read_b128 v[190:193], v249 offset:39936
	global_load_lds_dwordx4 v[222:223], off
	v_lshl_add_u64 v[222:223], s[4:5], 0, v[196:197]
	s_mov_b32 m0, s12
	s_nop 0
	global_load_lds_dwordx4 v[222:223], off
	s_waitcnt vmcnt(8)
	s_waitcnt lgkmcnt(0)
	s_barrier
	s_waitcnt lgkmcnt(0)
	v_mfma_f32_16x16x32_bf16 v[158:161], v[98:101], v[162:165], v[158:161]
	v_mfma_f32_16x16x32_bf16 v[150:153], v[114:117], v[162:165], v[150:153]
	v_mfma_f32_16x16x32_bf16 v[118:121], v[114:117], v[170:173], v[118:121]
	v_mfma_f32_16x16x32_bf16 v[126:129], v[98:101], v[170:173], v[126:129]
	v_mfma_f32_16x16x32_bf16 v[94:97], v[98:101], v[178:181], v[94:97]
	v_mfma_f32_16x16x32_bf16 v[90:93], v[114:117], v[178:181], v[90:93]
	v_mfma_f32_16x16x32_bf16 v[74:77], v[114:117], v[186:189], v[74:77]
	v_mfma_f32_16x16x32_bf16 v[78:81], v[98:101], v[186:189], v[78:81]
	v_mfma_f32_16x16x32_bf16 v[66:69], v[146:149], v[186:189], v[66:69]
	v_mfma_f32_16x16x32_bf16 v[134:137], v[146:149], v[162:165], v[134:137]
	v_mfma_f32_16x16x32_bf16 v[142:145], v[130:133], v[162:165], v[142:145]
	v_mfma_f32_16x16x32_bf16 v[110:113], v[130:133], v[170:173], v[110:113]
	v_mfma_f32_16x16x32_bf16 v[106:109], v[146:149], v[170:173], v[106:109]
	v_mfma_f32_16x16x32_bf16 v[82:85], v[146:149], v[178:181], v[82:85]
	v_mfma_f32_16x16x32_bf16 v[86:89], v[130:133], v[178:181], v[86:89]
	v_mfma_f32_16x16x32_bf16 v[70:73], v[130:133], v[186:189], v[70:73]
	v_mfma_f32_16x16x32_bf16 v[158:161], v[102:105], v[166:169], v[158:161]
	v_mfma_f32_16x16x32_bf16 v[150:153], v[122:125], v[166:169], v[150:153]
	v_mfma_f32_16x16x32_bf16 v[118:121], v[122:125], v[174:177], v[118:121]
	v_mfma_f32_16x16x32_bf16 v[126:129], v[102:105], v[174:177], v[126:129]
	v_mfma_f32_16x16x32_bf16 v[94:97], v[102:105], v[182:185], v[94:97]
	v_mfma_f32_16x16x32_bf16 v[90:93], v[122:125], v[182:185], v[90:93]
	v_mfma_f32_16x16x32_bf16 v[74:77], v[122:125], v[190:193], v[74:77]
	v_mfma_f32_16x16x32_bf16 v[78:81], v[102:105], v[190:193], v[78:81]
	v_mfma_f32_16x16x32_bf16 v[66:69], v[154:157], v[190:193], v[66:69]
	v_mfma_f32_16x16x32_bf16 v[134:137], v[154:157], v[166:169], v[134:137]
	v_mfma_f32_16x16x32_bf16 v[142:145], v[138:141], v[166:169], v[142:145]
	v_mfma_f32_16x16x32_bf16 v[110:113], v[138:141], v[174:177], v[110:113]
	v_mfma_f32_16x16x32_bf16 v[106:109], v[154:157], v[174:177], v[106:109]
	v_mfma_f32_16x16x32_bf16 v[82:85], v[154:157], v[182:185], v[82:85]
	v_mfma_f32_16x16x32_bf16 v[86:89], v[138:141], v[182:185], v[86:89]
	v_mfma_f32_16x16x32_bf16 v[70:73], v[138:141], v[190:193], v[70:73]
	s_barrier
; #define PG8_STAGE(bufoff, gbase, voff) do { _Pragma("unroll") for (int _i = 0; _i < 2; ++_i) \
;         __builtin_amdgcn_global_load_lds((const unsigned*)((const char*)(gbase) + (voff)[_i]), (PG8_LAS unsigned*)(lds + (bufoff) + ldsw + _i * 8192), 16, 0, 0); } while (0)
; #define PG8_LDA(dst, b, h) do { _Pragma("unroll") for (int m = 0; m < 4; ++m) _Pragma("unroll") for (int k = 0; k < 2; ++k) dst[m][k] = *(const PG8_LAS bf16x8*)(lds + PG8_SA(b, h) + aoff + m * 2048 + k * 1024); } while (0)
; #define PG8_LDB(dst, b, h) do { _Pragma("unroll") for (int n = 0; n < 2; ++n) _Pragma("unroll") for (int k = 0; k < 2; ++k) dst[n][k] = *(const PG8_LAS bf16x8*)(lds + PG8_SB(b, h) + boff + n * 2048 + k * 1024); } while (0)
; template <class Epi, class Sched, bool ALIGN_EPI = false, bool SP2 = false>
; __device__ __forceinline__ void gemm_phase(PG8_LAS unsigned char* lds, const Gemm g, const Sched& S, const Epi& E) {
;     ...
;         for (int t = 0; t < nt; t += 2) {
;             const bool last = (t == nt - 2);
;             const char* a1 = cA + (size_t)(t + 1) * kstep;
;             const char* a2 = last ? nA : cA + (size_t)(t + 2) * kstep; const char* b2 = last ? nB : cB + (size_t)(t + 2) * kstep;
;             const char* a3 = a2 + kstep; const char* b3 = b2 + kstep;
;             if (last && has_next) S.a_ready(nxt);
;             if constexpr (SP2) {
;             PG8_LDB(B0, 0, 0); PG8_LDB(B1, 0, 1); PG8_SCHED; PG8_LDA(At, 0, 0); PG8_STAGE(PG8_SA(1, 1), a1 + hstep, voffA);
;             PG8_WAIT_V(8); PG8_WAIT_L(0); PG8_BAR; PG8_MMA(0, 0, At, B0); PG8_MMA(0, 1, At, B1); PG8_BAR; PG8_SCHED;
;             PG8_LDA(At, 0, 1); PG8_STAGE(PG8_SB(0, 0), b2, voffB); PG8_STAGE(PG8_SB(0, 1), b2 + hstep, voffB); PG8_STAGE(PG8_SA(0, 0), a2, voffA);
;             PG8_WAIT_V(8); PG8_WAIT_L(0); PG8_BAR; PG8_MMA(1, 0, At, B0); PG8_MMA(1, 1, At, B1); PG8_BAR; PG8_SCHED;
;             PG8_LDB(B0, 1, 0); PG8_LDB(B1, 1, 1); PG8_SCHED; PG8_LDA(At, 1, 0); PG8_STAGE(PG8_SA(0, 1), a2 + hstep, voffA);
;             PG8_WAIT_V(8); PG8_WAIT_L(0); PG8_BAR; PG8_MMA(0, 0, At, B0); PG8_MMA(0, 1, At, B1); PG8_BAR; PG8_SCHED;
;             PG8_LDA(At, 1, 1); PG8_STAGE(PG8_SB(1, 0), b3, voffB); PG8_STAGE(PG8_SB(1, 1), b3 + hstep, voffB); PG8_STAGE(PG8_SA(1, 0), a3, voffA);
;             PG8_WAIT_V(8); PG8_WAIT_L(0); PG8_BAR; PG8_MMA(1, 0, At, B0); PG8_MMA(1, 1, At, B1); PG8_BAR; PG8_SCHED;
	s_add_i32 s4, s84, s80
	v_lshl_add_u64 v[206:207], v[206:207], 0, s[98:99]
	s_mov_b32 m0, s4
	ds_read_b128 v[162:165], v249 offset:49152
	ds_read_b128 v[166:169], v249 offset:50176
	ds_read_b128 v[170:173], v249 offset:51200
	ds_read_b128 v[174:177], v249 offset:52224
	ds_read_b128 v[178:181], v249 offset:53248
	ds_read_b128 v[182:185], v249 offset:54272
	ds_read_b128 v[186:189], v249 offset:55296
	ds_read_b128 v[190:193], v249 offset:56320
	global_load_lds_dwordx4 v[206:207], off
	v_lshl_add_u64 v[206:207], v[212:213], 0, s[98:99]
	s_add_i32 m0, s4, 0x2000
	s_add_i32 s4, vcc_hi, s80
	global_load_lds_dwordx4 v[206:207], off
	v_lshl_add_u64 v[206:207], v[214:215], 0, s[98:99]
	s_mov_b32 m0, s4
	s_nop 0
	global_load_lds_dwordx4 v[206:207], off
	v_lshl_add_u64 v[206:207], v[216:217], 0, s[98:99]
	s_add_i32 m0, s4, 0x2000
	s_nop 0
	global_load_lds_dwordx4 v[206:207], off
	v_lshl_add_u64 v[206:207], v[218:219], 0, s[98:99]
	s_mov_b32 m0, s10
	s_nop 0
	global_load_lds_dwordx4 v[206:207], off
	v_lshl_add_u64 v[206:207], v[220:221], 0, s[98:99]
	s_mov_b32 m0, s11
	s_nop 0
	global_load_lds_dwordx4 v[206:207], off
	s_waitcnt vmcnt(8)
	s_waitcnt lgkmcnt(0)
	s_barrier
	s_waitcnt lgkmcnt(0)
	v_mfma_f32_16x16x32_bf16 v[62:65], v[98:101], v[162:165], v[62:65]
	v_mfma_f32_16x16x32_bf16 v[58:61], v[114:117], v[162:165], v[58:61]
	v_mfma_f32_16x16x32_bf16 v[42:45], v[114:117], v[170:173], v[42:45]
	v_mfma_f32_16x16x32_bf16 v[46:49], v[98:101], v[170:173], v[46:49]
	v_mfma_f32_16x16x32_bf16 v[30:33], v[98:101], v[178:181], v[30:33]
	v_mfma_f32_16x16x32_bf16 v[26:29], v[114:117], v[178:181], v[26:29]
	v_mfma_f32_16x16x32_bf16 v[10:13], v[114:117], v[186:189], v[10:13]
	v_mfma_f32_16x16x32_bf16 v[14:17], v[98:101], v[186:189], v[14:17]
	v_mfma_f32_16x16x32_bf16 v[2:5], v[146:149], v[186:189], v[2:5]
	v_mfma_f32_16x16x32_bf16 v[50:53], v[146:149], v[162:165], v[50:53]
	v_mfma_f32_16x16x32_bf16 v[54:57], v[130:133], v[162:165], v[54:57]
	v_mfma_f32_16x16x32_bf16 v[38:41], v[130:133], v[170:173], v[38:41]
	v_mfma_f32_16x16x32_bf16 v[34:37], v[146:149], v[170:173], v[34:37]
	v_mfma_f32_16x16x32_bf16 v[18:21], v[146:149], v[178:181], v[18:21]
	v_mfma_f32_16x16x32_bf16 v[22:25], v[130:133], v[178:181], v[22:25]
	v_mfma_f32_16x16x32_bf16 v[6:9], v[130:133], v[186:189], v[6:9]
	v_mfma_f32_16x16x32_bf16 v[62:65], v[102:105], v[166:169], v[62:65]
	v_mfma_f32_16x16x32_bf16 v[58:61], v[122:125], v[166:169], v[58:61]
	v_mfma_f32_16x16x32_bf16 v[42:45], v[122:125], v[174:177], v[42:45]
	v_mfma_f32_16x16x32_bf16 v[46:49], v[102:105], v[174:177], v[46:49]
	v_mfma_f32_16x16x32_bf16 v[30:33], v[102:105], v[182:185], v[30:33]
	v_mfma_f32_16x16x32_bf16 v[26:29], v[122:125], v[182:185], v[26:29]
	v_mfma_f32_16x16x32_bf16 v[10:13], v[122:125], v[190:193], v[10:13]
	v_mfma_f32_16x16x32_bf16 v[14:17], v[102:105], v[190:193], v[14:17]
	v_mfma_f32_16x16x32_bf16 v[2:5], v[154:157], v[190:193], v[2:5]
	v_mfma_f32_16x16x32_bf16 v[50:53], v[154:157], v[166:169], v[50:53]
	v_mfma_f32_16x16x32_bf16 v[54:57], v[138:141], v[166:169], v[54:57]
	v_mfma_f32_16x16x32_bf16 v[38:41], v[138:141], v[174:177], v[38:41]
	v_mfma_f32_16x16x32_bf16 v[34:37], v[154:157], v[174:177], v[34:37]
	v_mfma_f32_16x16x32_bf16 v[18:21], v[154:157], v[182:185], v[18:21]
	v_mfma_f32_16x16x32_bf16 v[22:25], v[138:141], v[182:185], v[22:25]
	v_mfma_f32_16x16x32_bf16 v[6:9], v[138:141], v[190:193], v[6:9]
	s_barrier
	s_add_u32 s6, s6, s98
	s_addc_u32 s7, s7, 0
	s_add_u32 s6, s6, s98
	s_addc_u32 s7, s7, 0
	s_add_u32 s67, s67, s98
	s_addc_u32 s85, s85, 0
	s_add_u32 s67, s67, s98
	s_addc_u32 s85, s85, 0
	s_cmp_ge_u32 vcc_lo, s69
	s_mov_b32 s8, vcc_lo
	s_cbranch_scc0 .LBB0_175

; #define PG8_STAGE(bufoff, gbase, voff) do { _Pragma("unroll") for (int _i = 0; _i < 2; ++_i) \
;         __builtin_amdgcn_global_load_lds((const unsigned*)((const char*)(gbase) + (voff)[_i]), (PG8_LAS unsigned*)(lds + (bufoff) + ldsw + _i * 8192), 16, 0, 0); } while (0)
; #define PG8_LDA(dst, b, h) do { _Pragma("unroll") for (int m = 0; m < 4; ++m) _Pragma("unroll") for (int k = 0; k < 2; ++k) dst[m][k] = *(const PG8_LAS bf16x8*)(lds + PG8_SA(b, h) + aoff + m * 2048 + k * 1024); } while (0)
; #define PG8_LDB(dst, b, h) do { _Pragma("unroll") for (int n = 0; n < 2; ++n) _Pragma("unroll") for (int k = 0; k < 2; ++k) dst[n][k] = *(const PG8_LAS bf16x8*)(lds + PG8_SB(b, h) + boff + n * 2048 + k * 1024); } while (0)
; template <class Epi, class Sched, bool ALIGN_EPI = false, bool SP2 = false>
; __device__ __forceinline__ void gemm_phase(PG8_LAS unsigned char* lds, const Gemm g, const Sched& S, const Epi& E) {
;     ...
;         for (int t = 0; t < nt; t += 2) {
;             const bool last = (t == nt - 2);
;             const char* a1 = cA + (size_t)(t + 1) * kstep;
;             const char* a2 = last ? nA : cA + (size_t)(t + 2) * kstep; const char* b2 = last ? nB : cB + (size_t)(t + 2) * kstep;
;             const char* a3 = a2 + kstep; const char* b3 = b2 + kstep;
;             if (last && has_next) S.a_ready(nxt);
;             if constexpr (SP2) {
;             PG8_LDB(B0, 0, 0); PG8_LDB(B1, 0, 1); PG8_SCHED; PG8_LDA(At, 0, 0); PG8_STAGE(PG8_SA(1, 1), a1 + hstep, voffA);
;             PG8_WAIT_V(8); PG8_WAIT_L(0); PG8_BAR; PG8_MMA(0, 0, At, B0); PG8_MMA(0, 1, At, B1); PG8_BAR; PG8_SCHED;
;             PG8_LDA(At, 0, 1); PG8_STAGE(PG8_SB(0, 0), b2, voffB); PG8_STAGE(PG8_SB(0, 1), b2 + hstep, voffB); PG8_STAGE(PG8_SA(0, 0), a2, voffA);
;             PG8_WAIT_V(8); PG8_WAIT_L(0); PG8_BAR; PG8_MMA(1, 0, At, B0); PG8_MMA(1, 1, At, B1); PG8_BAR; PG8_SCHED;
;             PG8_LDB(B0, 1, 0); PG8_LDB(B1, 1, 1); PG8_SCHED; PG8_LDA(At, 1, 0); PG8_STAGE(PG8_SA(0, 1), a2 + hstep, voffA);
;             PG8_WAIT_V(8); PG8_WAIT_L(0); PG8_BAR; PG8_MMA(0, 0, At, B0); PG8_MMA(0, 1, At, B1); PG8_BAR; PG8_SCHED;
;             PG8_LDA(At, 1, 1); PG8_STAGE(PG8_SB(1, 0), b3, voffB); PG8_STAGE(PG8_SB(1, 1), b3 + hstep, voffB); PG8_STAGE(PG8_SA(1, 0), a3, voffA);
;             PG8_WAIT_V(8); PG8_WAIT_L(0); PG8_BAR; PG8_MMA(1, 0, At, B0); PG8_MMA(1, 1, At, B1); PG8_BAR; PG8_SCHED;
.Lpeel291:
	s_add_u32 s84, s8, 0x100
	s_addc_u32 s85, s9, 0
	s_add_i32 s66, 0, 0x10000
	s_cmp_eq_u32 s10, 12
	s_cselect_b32 vcc_hi, s5, s85
	s_cselect_b32 vcc_lo, s7, s84
	s_cselect_b32 s97, s11, s68
	s_cselect_b32 s96, s67, s69
	s_add_i32 s70, 0, 0x14000
	v_add_u32_e32 v110, s66, v175
	v_add_u32_e32 v168, s70, v175
	s_waitcnt vmcnt(0)
	ds_read_b128 v[66:69], v110
	ds_read_b128 v[70:73], v110 offset:1024
	ds_read_b128 v[106:109], v110 offset:2048
	ds_read_b128 v[110:113], v110 offset:3072
	ds_read_b128 v[114:117], v168
	ds_read_b128 v[118:121], v168 offset:1024
	ds_read_b128 v[126:129], v168 offset:2048
	ds_read_b128 v[178:181], v168 offset:3072
	v_lshl_add_u64 v[168:169], s[8:9], 0, v[164:165]
	s_add_i32 m0, s1, 0xc000
	ds_read_b128 v[182:185], v177
	ds_read_b128 v[186:189], v177 offset:1024
	ds_read_b128 v[190:193], v177 offset:2048
	ds_read_b128 v[194:197], v177 offset:3072
	ds_read_b128 v[198:201], v177 offset:4096
	ds_read_b128 v[210:213], v177 offset:5120
	ds_read_b128 v[214:217], v177 offset:6144
	ds_read_b128 v[218:221], v177 offset:7168
	global_load_lds_dwordx4 v[168:169], off
	v_lshl_add_u64 v[168:169], s[8:9], 0, v[166:167]
	s_add_i32 m0, s1, 0xe000
	s_nop 0
	global_load_lds_dwordx4 v[168:169], off
	s_waitcnt vmcnt(8)
	s_waitcnt lgkmcnt(0)
	s_barrier
	s_waitcnt lgkmcnt(0)
	v_mfma_i32_16x16x64_i8 v[154:157], v[66:69], v[182:185], 0
	v_mfma_i32_16x16x64_i8 v[146:149], v[106:109], v[182:185], 0
	v_mfma_i32_16x16x64_i8 v[138:141], v[106:109], v[190:193], 0
	v_mfma_i32_16x16x64_i8 v[150:153], v[66:69], v[190:193], 0
	v_mfma_i32_16x16x64_i8 v[142:145], v[66:69], v[198:201], 0
	v_mfma_i32_16x16x64_i8 v[130:133], v[106:109], v[198:201], 0
	v_mfma_i32_16x16x64_i8 v[122:125], v[106:109], v[214:217], 0
	v_mfma_i32_16x16x64_i8 v[134:137], v[66:69], v[214:217], 0
	v_mfma_i32_16x16x64_i8 v[74:77], v[126:129], v[214:217], 0
	v_mfma_i32_16x16x64_i8 v[94:97], v[126:129], v[182:185], 0
	v_mfma_i32_16x16x64_i8 v[102:105], v[114:117], v[182:185], 0
	v_mfma_i32_16x16x64_i8 v[98:101], v[114:117], v[190:193], 0
	v_mfma_i32_16x16x64_i8 v[86:89], v[126:129], v[190:193], 0
	v_mfma_i32_16x16x64_i8 v[78:81], v[126:129], v[198:201], 0
	v_mfma_i32_16x16x64_i8 v[90:93], v[114:117], v[198:201], 0
	v_mfma_i32_16x16x64_i8 v[82:85], v[114:117], v[214:217], 0
	v_mfma_i32_16x16x64_i8 v[154:157], v[70:73], v[186:189], v[154:157]
	v_mfma_i32_16x16x64_i8 v[146:149], v[110:113], v[186:189], v[146:149]
	v_mfma_i32_16x16x64_i8 v[138:141], v[110:113], v[194:197], v[138:141]
	v_mfma_i32_16x16x64_i8 v[150:153], v[70:73], v[194:197], v[150:153]
	v_mfma_i32_16x16x64_i8 v[142:145], v[70:73], v[210:213], v[142:145]
	v_mfma_i32_16x16x64_i8 v[130:133], v[110:113], v[210:213], v[130:133]
	v_mfma_i32_16x16x64_i8 v[122:125], v[110:113], v[218:221], v[122:125]
	v_mfma_i32_16x16x64_i8 v[134:137], v[70:73], v[218:221], v[134:137]
	v_mfma_i32_16x16x64_i8 v[74:77], v[178:181], v[218:221], v[74:77]
	v_mfma_i32_16x16x64_i8 v[94:97], v[178:181], v[186:189], v[94:97]
	v_mfma_i32_16x16x64_i8 v[102:105], v[118:121], v[186:189], v[102:105]
	v_mfma_i32_16x16x64_i8 v[98:101], v[118:121], v[194:197], v[98:101]
	v_mfma_i32_16x16x64_i8 v[86:89], v[178:181], v[194:197], v[86:89]
	v_mfma_i32_16x16x64_i8 v[78:81], v[178:181], v[210:213], v[78:81]
	v_mfma_i32_16x16x64_i8 v[90:93], v[118:121], v[210:213], v[90:93]
	v_mfma_i32_16x16x64_i8 v[82:85], v[118:121], v[218:221], v[82:85]
	s_barrier
	s_add_i32 s8, s66, s81
	v_lshl_add_u64 v[168:169], s[96:97], 0, v[0:1]
	s_mov_b32 m0, s8
	ds_read_b128 v[182:185], v177 offset:16384
	ds_read_b128 v[186:189], v177 offset:17408
	ds_read_b128 v[190:193], v177 offset:18432
	ds_read_b128 v[194:197], v177 offset:19456
	ds_read_b128 v[198:201], v177 offset:20480
	ds_read_b128 v[210:213], v177 offset:21504
	ds_read_b128 v[214:217], v177 offset:22528
	ds_read_b128 v[218:221], v177 offset:23552
	global_load_lds_dwordx4 v[168:169], off
	s_add_i32 m0, s8, 0x2000
	s_add_u32 s8, s96, 0x40000
	v_lshl_add_u64 v[206:207], s[96:97], 0, v[158:159]
	s_addc_u32 s9, s97, 0
	s_add_i32 s66, s70, s81
	global_load_lds_dwordx4 v[206:207], off
	v_lshl_add_u64 v[222:223], s[8:9], 0, v[0:1]
	s_mov_b32 m0, s66
	v_lshl_add_u64 v[224:225], vcc, 0, v[160:161]
	global_load_lds_dwordx4 v[222:223], off
	v_lshl_add_u64 v[222:223], s[8:9], 0, v[158:159]
	s_add_i32 m0, s66, 0x2000
	s_nop 0
	global_load_lds_dwordx4 v[222:223], off
	v_lshl_add_u64 v[222:223], vcc, 0, v[162:163]
	s_mov_b32 m0, s1
	s_nop 0
	global_load_lds_dwordx4 v[222:223], off
	s_mov_b32 m0, s58
	s_nop 0
	global_load_lds_dwordx4 v[224:225], off
	s_waitcnt vmcnt(8)
	s_waitcnt lgkmcnt(0)
	s_barrier
	s_waitcnt lgkmcnt(0)
	v_mfma_i32_16x16x64_i8 v[62:65], v[66:69], v[182:185], 0
	v_mfma_i32_16x16x64_i8 v[54:57], v[106:109], v[182:185], 0
	v_mfma_i32_16x16x64_i8 v[46:49], v[106:109], v[190:193], 0
	v_mfma_i32_16x16x64_i8 v[58:61], v[66:69], v[190:193], 0
	v_mfma_i32_16x16x64_i8 v[50:53], v[66:69], v[198:201], 0
	v_mfma_i32_16x16x64_i8 v[38:41], v[106:109], v[198:201], 0
	v_mfma_i32_16x16x64_i8 v[34:37], v[106:109], v[214:217], 0
	v_mfma_i32_16x16x64_i8 v[42:45], v[66:69], v[214:217], 0
	v_mfma_i32_16x16x64_i8 v[2:5], v[126:129], v[214:217], 0
	v_mfma_i32_16x16x64_i8 v[22:25], v[126:129], v[182:185], 0
	v_mfma_i32_16x16x64_i8 v[30:33], v[114:117], v[182:185], 0
	v_mfma_i32_16x16x64_i8 v[26:29], v[114:117], v[190:193], 0
	v_mfma_i32_16x16x64_i8 v[14:17], v[126:129], v[190:193], 0
	v_mfma_i32_16x16x64_i8 v[6:9], v[126:129], v[198:201], 0
	v_mfma_i32_16x16x64_i8 v[18:21], v[114:117], v[198:201], 0
	v_mfma_i32_16x16x64_i8 v[10:13], v[114:117], v[214:217], 0
	v_mfma_i32_16x16x64_i8 v[62:65], v[70:73], v[186:189], v[62:65]
	v_mfma_i32_16x16x64_i8 v[54:57], v[110:113], v[186:189], v[54:57]
	v_mfma_i32_16x16x64_i8 v[46:49], v[110:113], v[194:197], v[46:49]
	v_mfma_i32_16x16x64_i8 v[58:61], v[70:73], v[194:197], v[58:61]
	v_mfma_i32_16x16x64_i8 v[50:53], v[70:73], v[210:213], v[50:53]
	v_mfma_i32_16x16x64_i8 v[38:41], v[110:113], v[210:213], v[38:41]
	v_mfma_i32_16x16x64_i8 v[34:37], v[110:113], v[218:221], v[34:37]
	v_mfma_i32_16x16x64_i8 v[42:45], v[70:73], v[218:221], v[42:45]
	v_mfma_i32_16x16x64_i8 v[2:5], v[178:181], v[218:221], v[2:5]
	v_mfma_i32_16x16x64_i8 v[22:25], v[178:181], v[186:189], v[22:25]
	v_mfma_i32_16x16x64_i8 v[30:33], v[118:121], v[186:189], v[30:33]
	v_mfma_i32_16x16x64_i8 v[26:29], v[118:121], v[194:197], v[26:29]
	v_mfma_i32_16x16x64_i8 v[14:17], v[178:181], v[194:197], v[14:17]
	v_mfma_i32_16x16x64_i8 v[6:9], v[178:181], v[210:213], v[6:9]
	v_mfma_i32_16x16x64_i8 v[18:21], v[118:121], v[210:213], v[18:21]
	v_mfma_i32_16x16x64_i8 v[10:13], v[118:121], v[218:221], v[10:13]
	s_barrier
; #define PG8_STAGE(bufoff, gbase, voff) do { _Pragma("unroll") for (int _i = 0; _i < 2; ++_i) \
;         __builtin_amdgcn_global_load_lds((const unsigned*)((const char*)(gbase) + (voff)[_i]), (PG8_LAS unsigned*)(lds + (bufoff) + ldsw + _i * 8192), 16, 0, 0); } while (0)
; #define PG8_LDA(dst, b, h) do { _Pragma("unroll") for (int m = 0; m < 4; ++m) _Pragma("unroll") for (int k = 0; k < 2; ++k) dst[m][k] = *(const PG8_LAS bf16x8*)(lds + PG8_SA(b, h) + aoff + m * 2048 + k * 1024); } while (0)
; #define PG8_LDB(dst, b, h) do { _Pragma("unroll") for (int n = 0; n < 2; ++n) _Pragma("unroll") for (int k = 0; k < 2; ++k) dst[n][k] = *(const PG8_LAS bf16x8*)(lds + PG8_SB(b, h) + boff + n * 2048 + k * 1024); } while (0)
; template <class Epi, class Sched, bool ALIGN_EPI = false, bool SP2 = false>
; __device__ __forceinline__ void gemm_phase(PG8_LAS unsigned char* lds, const Gemm g, const Sched& S, const Epi& E) {
;     ...
;         for (int t = 0; t < nt; t += 2) {
;             const bool last = (t == nt - 2);
;             const char* a1 = cA + (size_t)(t + 1) * kstep;
;             const char* a2 = last ? nA : cA + (size_t)(t + 2) * kstep; const char* b2 = last ? nB : cB + (size_t)(t + 2) * kstep;
;             const char* a3 = a2 + kstep; const char* b3 = b2 + kstep;
;             if (last && has_next) S.a_ready(nxt);
;             if constexpr (SP2) {
;             PG8_LDB(B0, 0, 0); PG8_LDB(B1, 0, 1); PG8_SCHED; PG8_LDA(At, 0, 0); PG8_STAGE(PG8_SA(1, 1), a1 + hstep, voffA);
;             PG8_WAIT_V(8); PG8_WAIT_L(0); PG8_BAR; PG8_MMA(0, 0, At, B0); PG8_MMA(0, 1, At, B1); PG8_BAR; PG8_SCHED;
;             PG8_LDA(At, 0, 1); PG8_STAGE(PG8_SB(0, 0), b2, voffB); PG8_STAGE(PG8_SB(0, 1), b2 + hstep, voffB); PG8_STAGE(PG8_SA(0, 0), a2, voffA);
;             PG8_WAIT_V(8); PG8_WAIT_L(0); PG8_BAR; PG8_MMA(1, 0, At, B0); PG8_MMA(1, 1, At, B1); PG8_BAR; PG8_SCHED;
;             PG8_LDB(B0, 1, 0); PG8_LDB(B1, 1, 1); PG8_SCHED; PG8_LDA(At, 1, 0); PG8_STAGE(PG8_SA(0, 1), a2 + hstep, voffA);
;             PG8_WAIT_V(8); PG8_WAIT_L(0); PG8_BAR; PG8_MMA(0, 0, At, B0); PG8_MMA(0, 1, At, B1); PG8_BAR; PG8_SCHED;
;             PG8_LDA(At, 1, 1); PG8_STAGE(PG8_SB(1, 0), b3, voffB); PG8_STAGE(PG8_SB(1, 1), b3 + hstep, voffB); PG8_STAGE(PG8_SA(1, 0), a3, voffA);
;             PG8_WAIT_V(8); PG8_WAIT_L(0); PG8_BAR; PG8_MMA(1, 0, At, B0); PG8_MMA(1, 1, At, B1); PG8_BAR; PG8_SCHED;
	s_add_i32 s66, 0, 0x18000
	s_add_i32 s70, 0, 0x1c000
	v_add_u32_e32 v110, s66, v175
	v_add_u32_e32 v170, s70, v175
	ds_read_b128 v[66:69], v110
	ds_read_b128 v[70:73], v110 offset:1024
	ds_read_b128 v[106:109], v110 offset:2048
	ds_read_b128 v[110:113], v110 offset:3072
	ds_read_b128 v[114:117], v170
	ds_read_b128 v[118:121], v170 offset:1024
	ds_read_b128 v[126:129], v170 offset:2048
	ds_read_b128 v[178:181], v170 offset:3072
	s_add_u32 s8, vcc_lo, 0x40000
	s_addc_u32 s9, vcc_hi, 0
	s_mov_b32 m0, s80
	v_lshl_add_u64 v[226:227], s[8:9], 0, v[162:163]
	ds_read_b128 v[182:185], v177 offset:32768
	ds_read_b128 v[186:189], v177 offset:33792
	ds_read_b128 v[190:193], v177 offset:34816
	ds_read_b128 v[194:197], v177 offset:35840
	ds_read_b128 v[198:201], v177 offset:36864
	ds_read_b128 v[210:213], v177 offset:37888
	ds_read_b128 v[214:217], v177 offset:38912
	ds_read_b128 v[218:221], v177 offset:39936
	global_load_lds_dwordx4 v[226:227], off
	v_lshl_add_u64 v[226:227], s[8:9], 0, v[160:161]
	s_mov_b32 m0, s0
	s_nop 0
	global_load_lds_dwordx4 v[226:227], off
	s_waitcnt vmcnt(8)
	s_waitcnt lgkmcnt(0)
	s_barrier
	s_waitcnt lgkmcnt(0)
	v_mfma_i32_16x16x64_i8 v[154:157], v[66:69], v[182:185], v[154:157]
	v_mfma_i32_16x16x64_i8 v[146:149], v[106:109], v[182:185], v[146:149]
	v_mfma_i32_16x16x64_i8 v[138:141], v[106:109], v[190:193], v[138:141]
	v_mfma_i32_16x16x64_i8 v[150:153], v[66:69], v[190:193], v[150:153]
	v_mfma_i32_16x16x64_i8 v[142:145], v[66:69], v[198:201], v[142:145]
	v_mfma_i32_16x16x64_i8 v[130:133], v[106:109], v[198:201], v[130:133]
	v_mfma_i32_16x16x64_i8 v[122:125], v[106:109], v[214:217], v[122:125]
	v_mfma_i32_16x16x64_i8 v[134:137], v[66:69], v[214:217], v[134:137]
	v_mfma_i32_16x16x64_i8 v[74:77], v[126:129], v[214:217], v[74:77]
	v_mfma_i32_16x16x64_i8 v[94:97], v[126:129], v[182:185], v[94:97]
	v_mfma_i32_16x16x64_i8 v[102:105], v[114:117], v[182:185], v[102:105]
	v_mfma_i32_16x16x64_i8 v[98:101], v[114:117], v[190:193], v[98:101]
	v_mfma_i32_16x16x64_i8 v[86:89], v[126:129], v[190:193], v[86:89]
	v_mfma_i32_16x16x64_i8 v[78:81], v[126:129], v[198:201], v[78:81]
	v_mfma_i32_16x16x64_i8 v[90:93], v[114:117], v[198:201], v[90:93]
	v_mfma_i32_16x16x64_i8 v[82:85], v[114:117], v[214:217], v[82:85]
	v_mfma_i32_16x16x64_i8 v[154:157], v[70:73], v[186:189], v[154:157]
	v_mfma_i32_16x16x64_i8 v[146:149], v[110:113], v[186:189], v[146:149]
	v_mfma_i32_16x16x64_i8 v[138:141], v[110:113], v[194:197], v[138:141]
	v_mfma_i32_16x16x64_i8 v[150:153], v[70:73], v[194:197], v[150:153]
	v_mfma_i32_16x16x64_i8 v[142:145], v[70:73], v[210:213], v[142:145]
	v_mfma_i32_16x16x64_i8 v[130:133], v[110:113], v[210:213], v[130:133]
	v_mfma_i32_16x16x64_i8 v[122:125], v[110:113], v[218:221], v[122:125]
	v_mfma_i32_16x16x64_i8 v[134:137], v[70:73], v[218:221], v[134:137]
	v_mfma_i32_16x16x64_i8 v[74:77], v[178:181], v[218:221], v[74:77]
	v_mfma_i32_16x16x64_i8 v[94:97], v[178:181], v[186:189], v[94:97]
	v_mfma_i32_16x16x64_i8 v[102:105], v[118:121], v[186:189], v[102:105]
	v_mfma_i32_16x16x64_i8 v[98:101], v[118:121], v[194:197], v[98:101]
	v_mfma_i32_16x16x64_i8 v[86:89], v[178:181], v[194:197], v[86:89]
	v_mfma_i32_16x16x64_i8 v[78:81], v[178:181], v[210:213], v[78:81]
	v_mfma_i32_16x16x64_i8 v[90:93], v[118:121], v[210:213], v[90:93]
	v_mfma_i32_16x16x64_i8 v[82:85], v[118:121], v[218:221], v[82:85]
	s_barrier
	s_add_i32 s8, s66, s81
	v_lshl_add_u64 v[168:169], v[168:169], 0, s[92:93]
	s_mov_b32 m0, s8
	ds_read_b128 v[182:185], v177 offset:49152
	ds_read_b128 v[186:189], v177 offset:50176
	ds_read_b128 v[190:193], v177 offset:51200
	ds_read_b128 v[194:197], v177 offset:52224
	ds_read_b128 v[198:201], v177 offset:53248
	ds_read_b128 v[210:213], v177 offset:54272
	ds_read_b128 v[214:217], v177 offset:55296
	ds_read_b128 v[218:221], v177 offset:56320
	global_load_lds_dwordx4 v[168:169], off
	s_add_i32 m0, s8, 0x2000
	s_add_u32 s8, s96, 0x40080
	v_lshl_add_u64 v[168:169], v[206:207], 0, s[92:93]
	s_addc_u32 s9, s97, 0
	s_add_i32 s66, s70, s81
	global_load_lds_dwordx4 v[168:169], off
	v_lshl_add_u64 v[168:169], s[8:9], 0, v[0:1]
	s_mov_b32 m0, s66
	s_nop 0
	global_load_lds_dwordx4 v[168:169], off
	v_lshl_add_u64 v[168:169], s[8:9], 0, v[158:159]
	s_add_i32 m0, s66, 0x2000
	s_nop 0
	global_load_lds_dwordx4 v[168:169], off
	v_lshl_add_u64 v[168:169], v[222:223], 0, s[92:93]
	s_mov_b32 m0, s13
	s_nop 0
	global_load_lds_dwordx4 v[168:169], off
	v_lshl_add_u64 v[168:169], v[224:225], 0, s[92:93]
	s_mov_b32 m0, s12
	s_nop 0
	global_load_lds_dwordx4 v[168:169], off
	s_waitcnt vmcnt(8)
	s_waitcnt lgkmcnt(0)
	s_barrier
	s_waitcnt lgkmcnt(0)
	v_mfma_i32_16x16x64_i8 v[62:65], v[66:69], v[182:185], v[62:65]
	v_mfma_i32_16x16x64_i8 v[54:57], v[106:109], v[182:185], v[54:57]
	v_mfma_i32_16x16x64_i8 v[46:49], v[106:109], v[190:193], v[46:49]
	v_mfma_i32_16x16x64_i8 v[58:61], v[66:69], v[190:193], v[58:61]
	v_mfma_i32_16x16x64_i8 v[50:53], v[66:69], v[198:201], v[50:53]
	v_mfma_i32_16x16x64_i8 v[38:41], v[106:109], v[198:201], v[38:41]
	v_mfma_i32_16x16x64_i8 v[34:37], v[106:109], v[214:217], v[34:37]
	v_mfma_i32_16x16x64_i8 v[42:45], v[66:69], v[214:217], v[42:45]
	v_mfma_i32_16x16x64_i8 v[2:5], v[126:129], v[214:217], v[2:5]
	v_mfma_i32_16x16x64_i8 v[22:25], v[126:129], v[182:185], v[22:25]
	v_mfma_i32_16x16x64_i8 v[30:33], v[114:117], v[182:185], v[30:33]
	v_mfma_i32_16x16x64_i8 v[26:29], v[114:117], v[190:193], v[26:29]
	v_mfma_i32_16x16x64_i8 v[14:17], v[126:129], v[190:193], v[14:17]
	v_mfma_i32_16x16x64_i8 v[6:9], v[126:129], v[198:201], v[6:9]
	v_mfma_i32_16x16x64_i8 v[18:21], v[114:117], v[198:201], v[18:21]
	v_mfma_i32_16x16x64_i8 v[10:13], v[114:117], v[214:217], v[10:13]
	v_mfma_i32_16x16x64_i8 v[62:65], v[70:73], v[186:189], v[62:65]
	v_mfma_i32_16x16x64_i8 v[54:57], v[110:113], v[186:189], v[54:57]
	v_mfma_i32_16x16x64_i8 v[46:49], v[110:113], v[194:197], v[46:49]
	v_mfma_i32_16x16x64_i8 v[58:61], v[70:73], v[194:197], v[58:61]
	v_mfma_i32_16x16x64_i8 v[50:53], v[70:73], v[210:213], v[50:53]
	v_mfma_i32_16x16x64_i8 v[38:41], v[110:113], v[210:213], v[38:41]
	v_mfma_i32_16x16x64_i8 v[34:37], v[110:113], v[218:221], v[34:37]
	v_mfma_i32_16x16x64_i8 v[42:45], v[70:73], v[218:221], v[42:45]
	v_mfma_i32_16x16x64_i8 v[2:5], v[178:181], v[218:221], v[2:5]
	v_mfma_i32_16x16x64_i8 v[22:25], v[178:181], v[186:189], v[22:25]
	v_mfma_i32_16x16x64_i8 v[30:33], v[118:121], v[186:189], v[30:33]
	v_mfma_i32_16x16x64_i8 v[26:29], v[118:121], v[194:197], v[26:29]
	v_mfma_i32_16x16x64_i8 v[14:17], v[178:181], v[194:197], v[14:17]
	v_mfma_i32_16x16x64_i8 v[6:9], v[178:181], v[210:213], v[6:9]
	v_mfma_i32_16x16x64_i8 v[18:21], v[118:121], v[210:213], v[18:21]
	v_mfma_i32_16x16x64_i8 v[10:13], v[118:121], v[218:221], v[10:13]
	s_barrier
	s_add_i32 s10, s10, 2
	s_add_u32 s69, s69, 0x100
	s_addc_u32 s68, s68, 0
	s_cmp_gt_u32 s10, 13
	s_mov_b64 s[8:9], s[84:85]
	s_cbranch_scc0 .LBB0_291
	s_branch .Lpeelx291
; #define PG8_STAGE(bufoff, gbase, voff) do { _Pragma("unroll") for (int _i = 0; _i < 2; ++_i) \
;         __builtin_amdgcn_global_load_lds((const unsigned*)((const char*)(gbase) + (voff)[_i]), (PG8_LAS unsigned*)(lds + (bufoff) + ldsw + _i * 8192), 16, 0, 0); } while (0)
; #define PG8_LDA(dst, b, h) do { _Pragma("unroll") for (int m = 0; m < 4; ++m) _Pragma("unroll") for (int k = 0; k < 2; ++k) dst[m][k] = *(const PG8_LAS bf16x8*)(lds + PG8_SA(b, h) + aoff + m * 2048 + k * 1024); } while (0)
; #define PG8_LDB(dst, b, h) do { _Pragma("unroll") for (int n = 0; n < 2; ++n) _Pragma("unroll") for (int k = 0; k < 2; ++k) dst[n][k] = *(const PG8_LAS bf16x8*)(lds + PG8_SB(b, h) + boff + n * 2048 + k * 1024); } while (0)
; template <class Epi, class Sched, bool ALIGN_EPI = false, bool SP2 = false>
; __device__ __forceinline__ void gemm_phase(PG8_LAS unsigned char* lds, const Gemm g, const Sched& S, const Epi& E) {
;     ...
;         for (int t = 0; t < nt; t += 2) {
;             const bool last = (t == nt - 2);
;             const char* a1 = cA + (size_t)(t + 1) * kstep;
;             const char* a2 = last ? nA : cA + (size_t)(t + 2) * kstep; const char* b2 = last ? nB : cB + (size_t)(t + 2) * kstep;
;             const char* a3 = a2 + kstep; const char* b3 = b2 + kstep;
;             if (last && has_next) S.a_ready(nxt);
;             if constexpr (SP2) {
;             PG8_LDB(B0, 0, 0); PG8_LDB(B1, 0, 1); PG8_SCHED; PG8_LDA(At, 0, 0); PG8_STAGE(PG8_SA(1, 1), a1 + hstep, voffA);
;             PG8_WAIT_V(8); PG8_WAIT_L(0); PG8_BAR; PG8_MMA(0, 0, At, B0); PG8_MMA(0, 1, At, B1); PG8_BAR; PG8_SCHED;
;             PG8_LDA(At, 0, 1); PG8_STAGE(PG8_SB(0, 0), b2, voffB); PG8_STAGE(PG8_SB(0, 1), b2 + hstep, voffB); PG8_STAGE(PG8_SA(0, 0), a2, voffA);
;             PG8_WAIT_V(8); PG8_WAIT_L(0); PG8_BAR; PG8_MMA(1, 0, At, B0); PG8_MMA(1, 1, At, B1); PG8_BAR; PG8_SCHED;
;             PG8_LDB(B0, 1, 0); PG8_LDB(B1, 1, 1); PG8_SCHED; PG8_LDA(At, 1, 0); PG8_STAGE(PG8_SA(0, 1), a2 + hstep, voffA);
;             PG8_WAIT_V(8); PG8_WAIT_L(0); PG8_BAR; PG8_MMA(0, 0, At, B0); PG8_MMA(0, 1, At, B1); PG8_BAR; PG8_SCHED;
;             PG8_LDA(At, 1, 1); PG8_STAGE(PG8_SB(1, 0), b3, voffB); PG8_STAGE(PG8_SB(1, 1), b3 + hstep, voffB); PG8_STAGE(PG8_SA(1, 0), a3, voffA);
;             PG8_WAIT_V(8); PG8_WAIT_L(0); PG8_BAR; PG8_MMA(1, 0, At, B0); PG8_MMA(1, 1, At, B1); PG8_BAR; PG8_SCHED;
.LBB0_291:
	s_add_u32 s84, s8, 0x100
	s_addc_u32 s85, s9, 0
	s_add_i32 s66, 0, 0x10000
	s_cmp_eq_u32 s10, 12
	s_cselect_b32 vcc_hi, s5, s85
	s_cselect_b32 vcc_lo, s7, s84
	s_cselect_b32 s97, s11, s68
	s_cselect_b32 s96, s67, s69
	s_add_i32 s70, 0, 0x14000
	v_add_u32_e32 v110, s66, v175
	v_add_u32_e32 v168, s70, v175
	s_waitcnt vmcnt(0)
	ds_read_b128 v[66:69], v110
	ds_read_b128 v[70:73], v110 offset:1024
	ds_read_b128 v[106:109], v110 offset:2048
	ds_read_b128 v[110:113], v110 offset:3072
	ds_read_b128 v[114:117], v168
	ds_read_b128 v[118:121], v168 offset:1024
	ds_read_b128 v[126:129], v168 offset:2048
	ds_read_b128 v[178:181], v168 offset:3072
	v_lshl_add_u64 v[168:169], s[8:9], 0, v[164:165]
	s_add_i32 m0, s1, 0xc000
	ds_read_b128 v[182:185], v177
	ds_read_b128 v[186:189], v177 offset:1024
	ds_read_b128 v[190:193], v177 offset:2048
	ds_read_b128 v[194:197], v177 offset:3072
	ds_read_b128 v[198:201], v177 offset:4096
	ds_read_b128 v[210:213], v177 offset:5120
	ds_read_b128 v[214:217], v177 offset:6144
	ds_read_b128 v[218:221], v177 offset:7168
	global_load_lds_dwordx4 v[168:169], off
	v_lshl_add_u64 v[168:169], s[8:9], 0, v[166:167]
	s_add_i32 m0, s1, 0xe000
	s_nop 0
	global_load_lds_dwordx4 v[168:169], off
	s_waitcnt vmcnt(8)
	s_waitcnt lgkmcnt(0)
	s_barrier
	s_waitcnt lgkmcnt(0)
	v_mfma_i32_16x16x64_i8 v[154:157], v[66:69], v[182:185], v[154:157]
	v_mfma_i32_16x16x64_i8 v[146:149], v[106:109], v[182:185], v[146:149]
	v_mfma_i32_16x16x64_i8 v[138:141], v[106:109], v[190:193], v[138:141]
	v_mfma_i32_16x16x64_i8 v[150:153], v[66:69], v[190:193], v[150:153]
	v_mfma_i32_16x16x64_i8 v[142:145], v[66:69], v[198:201], v[142:145]
	v_mfma_i32_16x16x64_i8 v[130:133], v[106:109], v[198:201], v[130:133]
	v_mfma_i32_16x16x64_i8 v[122:125], v[106:109], v[214:217], v[122:125]
	v_mfma_i32_16x16x64_i8 v[134:137], v[66:69], v[214:217], v[134:137]
	v_mfma_i32_16x16x64_i8 v[74:77], v[126:129], v[214:217], v[74:77]
	v_mfma_i32_16x16x64_i8 v[94:97], v[126:129], v[182:185], v[94:97]
	v_mfma_i32_16x16x64_i8 v[102:105], v[114:117], v[182:185], v[102:105]
	v_mfma_i32_16x16x64_i8 v[98:101], v[114:117], v[190:193], v[98:101]
	v_mfma_i32_16x16x64_i8 v[86:89], v[126:129], v[190:193], v[86:89]
	v_mfma_i32_16x16x64_i8 v[78:81], v[126:129], v[198:201], v[78:81]
	v_mfma_i32_16x16x64_i8 v[90:93], v[114:117], v[198:201], v[90:93]
	v_mfma_i32_16x16x64_i8 v[82:85], v[114:117], v[214:217], v[82:85]
	v_mfma_i32_16x16x64_i8 v[154:157], v[70:73], v[186:189], v[154:157]
	v_mfma_i32_16x16x64_i8 v[146:149], v[110:113], v[186:189], v[146:149]
	v_mfma_i32_16x16x64_i8 v[138:141], v[110:113], v[194:197], v[138:141]
	v_mfma_i32_16x16x64_i8 v[150:153], v[70:73], v[194:197], v[150:153]
	v_mfma_i32_16x16x64_i8 v[142:145], v[70:73], v[210:213], v[142:145]
	v_mfma_i32_16x16x64_i8 v[130:133], v[110:113], v[210:213], v[130:133]
	v_mfma_i32_16x16x64_i8 v[122:125], v[110:113], v[218:221], v[122:125]
	v_mfma_i32_16x16x64_i8 v[134:137], v[70:73], v[218:221], v[134:137]
	v_mfma_i32_16x16x64_i8 v[74:77], v[178:181], v[218:221], v[74:77]
	v_mfma_i32_16x16x64_i8 v[94:97], v[178:181], v[186:189], v[94:97]
	v_mfma_i32_16x16x64_i8 v[102:105], v[118:121], v[186:189], v[102:105]
	v_mfma_i32_16x16x64_i8 v[98:101], v[118:121], v[194:197], v[98:101]
	v_mfma_i32_16x16x64_i8 v[86:89], v[178:181], v[194:197], v[86:89]
	v_mfma_i32_16x16x64_i8 v[78:81], v[178:181], v[210:213], v[78:81]
	v_mfma_i32_16x16x64_i8 v[90:93], v[118:121], v[210:213], v[90:93]
	v_mfma_i32_16x16x64_i8 v[82:85], v[118:121], v[218:221], v[82:85]
	s_barrier
	s_add_i32 s8, s66, s81
	v_lshl_add_u64 v[168:169], s[96:97], 0, v[0:1]
	s_mov_b32 m0, s8
	ds_read_b128 v[182:185], v177 offset:16384
	ds_read_b128 v[186:189], v177 offset:17408
	ds_read_b128 v[190:193], v177 offset:18432
	ds_read_b128 v[194:197], v177 offset:19456
	ds_read_b128 v[198:201], v177 offset:20480
	ds_read_b128 v[210:213], v177 offset:21504
	ds_read_b128 v[214:217], v177 offset:22528
	ds_read_b128 v[218:221], v177 offset:23552
	global_load_lds_dwordx4 v[168:169], off
	s_add_i32 m0, s8, 0x2000
	s_add_u32 s8, s96, 0x40000
	v_lshl_add_u64 v[206:207], s[96:97], 0, v[158:159]
	s_addc_u32 s9, s97, 0
	s_add_i32 s66, s70, s81
	global_load_lds_dwordx4 v[206:207], off
	v_lshl_add_u64 v[222:223], s[8:9], 0, v[0:1]
	s_mov_b32 m0, s66
	v_lshl_add_u64 v[224:225], vcc, 0, v[160:161]
	global_load_lds_dwordx4 v[222:223], off
	v_lshl_add_u64 v[222:223], s[8:9], 0, v[158:159]
	s_add_i32 m0, s66, 0x2000
	s_nop 0
	global_load_lds_dwordx4 v[222:223], off
	v_lshl_add_u64 v[222:223], vcc, 0, v[162:163]
	s_mov_b32 m0, s1
	s_nop 0
	global_load_lds_dwordx4 v[222:223], off
	s_mov_b32 m0, s58
	s_nop 0
	global_load_lds_dwordx4 v[224:225], off
	s_waitcnt vmcnt(8)
	s_waitcnt lgkmcnt(0)
	s_barrier
; #define PG8_STAGE(bufoff, gbase, voff) do { _Pragma("unroll") for (int _i = 0; _i < 2; ++_i) \
;         __builtin_amdgcn_global_load_lds((const unsigned*)((const char*)(gbase) + (voff)[_i]), (PG8_LAS unsigned*)(lds + (bufoff) + ldsw + _i * 8192), 16, 0, 0); } while (0)
; #define PG8_LDA(dst, b, h) do { _Pragma("unroll") for (int m = 0; m < 4; ++m) _Pragma("unroll") for (int k = 0; k < 2; ++k) dst[m][k] = *(const PG8_LAS bf16x8*)(lds + PG8_SA(b, h) + aoff + m * 2048 + k * 1024); } while (0)
; #define PG8_LDB(dst, b, h) do { _Pragma("unroll") for (int n = 0; n < 2; ++n) _Pragma("unroll") for (int k = 0; k < 2; ++k) dst[n][k] = *(const PG8_LAS bf16x8*)(lds + PG8_SB(b, h) + boff + n * 2048 + k * 1024); } while (0)
; template <class Epi, class Sched, bool ALIGN_EPI = false, bool SP2 = false>
; __device__ __forceinline__ void gemm_phase(PG8_LAS unsigned char* lds, const Gemm g, const Sched& S, const Epi& E) {
;     ...
;         for (int t = 0; t < nt; t += 2) {
;             const bool last = (t == nt - 2);
;             const char* a1 = cA + (size_t)(t + 1) * kstep;
;             const char* a2 = last ? nA : cA + (size_t)(t + 2) * kstep; const char* b2 = last ? nB : cB + (size_t)(t + 2) * kstep;
;             const char* a3 = a2 + kstep; const char* b3 = b2 + kstep;
;             if (last && has_next) S.a_ready(nxt);
;             if constexpr (SP2) {
;             PG8_LDB(B0, 0, 0); PG8_LDB(B1, 0, 1); PG8_SCHED; PG8_LDA(At, 0, 0); PG8_STAGE(PG8_SA(1, 1), a1 + hstep, voffA);
;             PG8_WAIT_V(8); PG8_WAIT_L(0); PG8_BAR; PG8_MMA(0, 0, At, B0); PG8_MMA(0, 1, At, B1); PG8_BAR; PG8_SCHED;
;             PG8_LDA(At, 0, 1); PG8_STAGE(PG8_SB(0, 0), b2, voffB); PG8_STAGE(PG8_SB(0, 1), b2 + hstep, voffB); PG8_STAGE(PG8_SA(0, 0), a2, voffA);
;             PG8_WAIT_V(8); PG8_WAIT_L(0); PG8_BAR; PG8_MMA(1, 0, At, B0); PG8_MMA(1, 1, At, B1); PG8_BAR; PG8_SCHED;
;             PG8_LDB(B0, 1, 0); PG8_LDB(B1, 1, 1); PG8_SCHED; PG8_LDA(At, 1, 0); PG8_STAGE(PG8_SA(0, 1), a2 + hstep, voffA);
;             PG8_WAIT_V(8); PG8_WAIT_L(0); PG8_BAR; PG8_MMA(0, 0, At, B0); PG8_MMA(0, 1, At, B1); PG8_BAR; PG8_SCHED;
;             PG8_LDA(At, 1, 1); PG8_STAGE(PG8_SB(1, 0), b3, voffB); PG8_STAGE(PG8_SB(1, 1), b3 + hstep, voffB); PG8_STAGE(PG8_SA(1, 0), a3, voffA);
;             PG8_WAIT_V(8); PG8_WAIT_L(0); PG8_BAR; PG8_MMA(1, 0, At, B0); PG8_MMA(1, 1, At, B1); PG8_BAR; PG8_SCHED;
	s_waitcnt lgkmcnt(0)
	v_mfma_i32_16x16x64_i8 v[62:65], v[66:69], v[182:185], v[62:65]
	v_mfma_i32_16x16x64_i8 v[54:57], v[106:109], v[182:185], v[54:57]
	v_mfma_i32_16x16x64_i8 v[46:49], v[106:109], v[190:193], v[46:49]
	v_mfma_i32_16x16x64_i8 v[58:61], v[66:69], v[190:193], v[58:61]
	v_mfma_i32_16x16x64_i8 v[50:53], v[66:69], v[198:201], v[50:53]
	v_mfma_i32_16x16x64_i8 v[38:41], v[106:109], v[198:201], v[38:41]
	v_mfma_i32_16x16x64_i8 v[34:37], v[106:109], v[214:217], v[34:37]
	v_mfma_i32_16x16x64_i8 v[42:45], v[66:69], v[214:217], v[42:45]
	v_mfma_i32_16x16x64_i8 v[2:5], v[126:129], v[214:217], v[2:5]
	v_mfma_i32_16x16x64_i8 v[22:25], v[126:129], v[182:185], v[22:25]
	v_mfma_i32_16x16x64_i8 v[30:33], v[114:117], v[182:185], v[30:33]
	v_mfma_i32_16x16x64_i8 v[26:29], v[114:117], v[190:193], v[26:29]
	v_mfma_i32_16x16x64_i8 v[14:17], v[126:129], v[190:193], v[14:17]
	v_mfma_i32_16x16x64_i8 v[6:9], v[126:129], v[198:201], v[6:9]
	v_mfma_i32_16x16x64_i8 v[18:21], v[114:117], v[198:201], v[18:21]
	v_mfma_i32_16x16x64_i8 v[10:13], v[114:117], v[214:217], v[10:13]
	v_mfma_i32_16x16x64_i8 v[62:65], v[70:73], v[186:189], v[62:65]
	v_mfma_i32_16x16x64_i8 v[54:57], v[110:113], v[186:189], v[54:57]
	v_mfma_i32_16x16x64_i8 v[46:49], v[110:113], v[194:197], v[46:49]
	v_mfma_i32_16x16x64_i8 v[58:61], v[70:73], v[194:197], v[58:61]
	v_mfma_i32_16x16x64_i8 v[50:53], v[70:73], v[210:213], v[50:53]
	v_mfma_i32_16x16x64_i8 v[38:41], v[110:113], v[210:213], v[38:41]
	v_mfma_i32_16x16x64_i8 v[34:37], v[110:113], v[218:221], v[34:37]
	v_mfma_i32_16x16x64_i8 v[42:45], v[70:73], v[218:221], v[42:45]
	v_mfma_i32_16x16x64_i8 v[2:5], v[178:181], v[218:221], v[2:5]
	v_mfma_i32_16x16x64_i8 v[22:25], v[178:181], v[186:189], v[22:25]
	v_mfma_i32_16x16x64_i8 v[30:33], v[118:121], v[186:189], v[30:33]
	v_mfma_i32_16x16x64_i8 v[26:29], v[118:121], v[194:197], v[26:29]
	v_mfma_i32_16x16x64_i8 v[14:17], v[178:181], v[194:197], v[14:17]
	v_mfma_i32_16x16x64_i8 v[6:9], v[178:181], v[210:213], v[6:9]
	v_mfma_i32_16x16x64_i8 v[18:21], v[118:121], v[210:213], v[18:21]
	v_mfma_i32_16x16x64_i8 v[10:13], v[118:121], v[218:221], v[10:13]
	s_barrier
	s_add_i32 s66, 0, 0x18000
	s_add_i32 s70, 0, 0x1c000
	v_add_u32_e32 v110, s66, v175
	v_add_u32_e32 v170, s70, v175
	ds_read_b128 v[66:69], v110
	ds_read_b128 v[70:73], v110 offset:1024
	ds_read_b128 v[106:109], v110 offset:2048
	ds_read_b128 v[110:113], v110 offset:3072
	ds_read_b128 v[114:117], v170
	ds_read_b128 v[118:121], v170 offset:1024
	ds_read_b128 v[126:129], v170 offset:2048
	ds_read_b128 v[178:181], v170 offset:3072
	s_add_u32 s8, vcc_lo, 0x40000
	s_addc_u32 s9, vcc_hi, 0
	s_mov_b32 m0, s80
	v_lshl_add_u64 v[226:227], s[8:9], 0, v[162:163]
	ds_read_b128 v[182:185], v177 offset:32768
	ds_read_b128 v[186:189], v177 offset:33792
	ds_read_b128 v[190:193], v177 offset:34816
	ds_read_b128 v[194:197], v177 offset:35840
	ds_read_b128 v[198:201], v177 offset:36864
	ds_read_b128 v[210:213], v177 offset:37888
	ds_read_b128 v[214:217], v177 offset:38912
	ds_read_b128 v[218:221], v177 offset:39936
	global_load_lds_dwordx4 v[226:227], off
	v_lshl_add_u64 v[226:227], s[8:9], 0, v[160:161]
	s_mov_b32 m0, s0
	s_nop 0
	global_load_lds_dwordx4 v[226:227], off
	s_waitcnt vmcnt(8)
	s_waitcnt lgkmcnt(0)
	s_barrier
	s_waitcnt lgkmcnt(0)
	v_mfma_i32_16x16x64_i8 v[154:157], v[66:69], v[182:185], v[154:157]
	v_mfma_i32_16x16x64_i8 v[146:149], v[106:109], v[182:185], v[146:149]
	v_mfma_i32_16x16x64_i8 v[138:141], v[106:109], v[190:193], v[138:141]
	v_mfma_i32_16x16x64_i8 v[150:153], v[66:69], v[190:193], v[150:153]
	v_mfma_i32_16x16x64_i8 v[142:145], v[66:69], v[198:201], v[142:145]
	v_mfma_i32_16x16x64_i8 v[130:133], v[106:109], v[198:201], v[130:133]
	v_mfma_i32_16x16x64_i8 v[122:125], v[106:109], v[214:217], v[122:125]
	v_mfma_i32_16x16x64_i8 v[134:137], v[66:69], v[214:217], v[134:137]
	v_mfma_i32_16x16x64_i8 v[74:77], v[126:129], v[214:217], v[74:77]
	v_mfma_i32_16x16x64_i8 v[94:97], v[126:129], v[182:185], v[94:97]
	v_mfma_i32_16x16x64_i8 v[102:105], v[114:117], v[182:185], v[102:105]
	v_mfma_i32_16x16x64_i8 v[98:101], v[114:117], v[190:193], v[98:101]
	v_mfma_i32_16x16x64_i8 v[86:89], v[126:129], v[190:193], v[86:89]
	v_mfma_i32_16x16x64_i8 v[78:81], v[126:129], v[198:201], v[78:81]
	v_mfma_i32_16x16x64_i8 v[90:93], v[114:117], v[198:201], v[90:93]
	v_mfma_i32_16x16x64_i8 v[82:85], v[114:117], v[214:217], v[82:85]
	v_mfma_i32_16x16x64_i8 v[154:157], v[70:73], v[186:189], v[154:157]
	v_mfma_i32_16x16x64_i8 v[146:149], v[110:113], v[186:189], v[146:149]
	v_mfma_i32_16x16x64_i8 v[138:141], v[110:113], v[194:197], v[138:141]
	v_mfma_i32_16x16x64_i8 v[150:153], v[70:73], v[194:197], v[150:153]
	v_mfma_i32_16x16x64_i8 v[142:145], v[70:73], v[210:213], v[142:145]
	v_mfma_i32_16x16x64_i8 v[130:133], v[110:113], v[210:213], v[130:133]
	v_mfma_i32_16x16x64_i8 v[122:125], v[110:113], v[218:221], v[122:125]
	v_mfma_i32_16x16x64_i8 v[134:137], v[70:73], v[218:221], v[134:137]
	v_mfma_i32_16x16x64_i8 v[74:77], v[178:181], v[218:221], v[74:77]
	v_mfma_i32_16x16x64_i8 v[94:97], v[178:181], v[186:189], v[94:97]
	v_mfma_i32_16x16x64_i8 v[102:105], v[118:121], v[186:189], v[102:105]
	v_mfma_i32_16x16x64_i8 v[98:101], v[118:121], v[194:197], v[98:101]
	v_mfma_i32_16x16x64_i8 v[86:89], v[178:181], v[194:197], v[86:89]
	v_mfma_i32_16x16x64_i8 v[78:81], v[178:181], v[210:213], v[78:81]
	v_mfma_i32_16x16x64_i8 v[90:93], v[118:121], v[210:213], v[90:93]
	v_mfma_i32_16x16x64_i8 v[82:85], v[118:121], v[218:221], v[82:85]
	s_barrier
; #define PG8_STAGE(bufoff, gbase, voff) do { _Pragma("unroll") for (int _i = 0; _i < 2; ++_i) \
;         __builtin_amdgcn_global_load_lds((const unsigned*)((const char*)(gbase) + (voff)[_i]), (PG8_LAS unsigned*)(lds + (bufoff) + ldsw + _i * 8192), 16, 0, 0); } while (0)
; #define PG8_LDA(dst, b, h) do { _Pragma("unroll") for (int m = 0; m < 4; ++m) _Pragma("unroll") for (int k = 0; k < 2; ++k) dst[m][k] = *(const PG8_LAS bf16x8*)(lds + PG8_SA(b, h) + aoff + m * 2048 + k * 1024); } while (0)
; #define PG8_LDB(dst, b, h) do { _Pragma("unroll") for (int n = 0; n < 2; ++n) _Pragma("unroll") for (int k = 0; k < 2; ++k) dst[n][k] = *(const PG8_LAS bf16x8*)(lds + PG8_SB(b, h) + boff + n * 2048 + k * 1024); } while (0)
; template <class Epi, class Sched, bool ALIGN_EPI = false, bool SP2 = false>
; __device__ __forceinline__ void gemm_phase(PG8_LAS unsigned char* lds, const Gemm g, const Sched& S, const Epi& E) {
;     ...
;         for (int t = 0; t < nt; t += 2) {
;             const bool last = (t == nt - 2);
;             const char* a1 = cA + (size_t)(t + 1) * kstep;
;             const char* a2 = last ? nA : cA + (size_t)(t + 2) * kstep; const char* b2 = last ? nB : cB + (size_t)(t + 2) * kstep;
;             const char* a3 = a2 + kstep; const char* b3 = b2 + kstep;
;             if (last && has_next) S.a_ready(nxt);
;             if constexpr (SP2) {
;             PG8_LDB(B0, 0, 0); PG8_LDB(B1, 0, 1); PG8_SCHED; PG8_LDA(At, 0, 0); PG8_STAGE(PG8_SA(1, 1), a1 + hstep, voffA);
;             PG8_WAIT_V(8); PG8_WAIT_L(0); PG8_BAR; PG8_MMA(0, 0, At, B0); PG8_MMA(0, 1, At, B1); PG8_BAR; PG8_SCHED;
;             PG8_LDA(At, 0, 1); PG8_STAGE(PG8_SB(0, 0), b2, voffB); PG8_STAGE(PG8_SB(0, 1), b2 + hstep, voffB); PG8_STAGE(PG8_SA(0, 0), a2, voffA);
;             PG8_WAIT_V(8); PG8_WAIT_L(0); PG8_BAR; PG8_MMA(1, 0, At, B0); PG8_MMA(1, 1, At, B1); PG8_BAR; PG8_SCHED;
;             PG8_LDB(B0, 1, 0); PG8_LDB(B1, 1, 1); PG8_SCHED; PG8_LDA(At, 1, 0); PG8_STAGE(PG8_SA(0, 1), a2 + hstep, voffA);
;             PG8_WAIT_V(8); PG8_WAIT_L(0); PG8_BAR; PG8_MMA(0, 0, At, B0); PG8_MMA(0, 1, At, B1); PG8_BAR; PG8_SCHED;
;             PG8_LDA(At, 1, 1); PG8_STAGE(PG8_SB(1, 0), b3, voffB); PG8_STAGE(PG8_SB(1, 1), b3 + hstep, voffB); PG8_STAGE(PG8_SA(1, 0), a3, voffA);
;             PG8_WAIT_V(8); PG8_WAIT_L(0); PG8_BAR; PG8_MMA(1, 0, At, B0); PG8_MMA(1, 1, At, B1); PG8_BAR; PG8_SCHED;
	s_add_i32 s8, s66, s81
	v_lshl_add_u64 v[168:169], v[168:169], 0, s[92:93]
	s_mov_b32 m0, s8
	ds_read_b128 v[182:185], v177 offset:49152
	ds_read_b128 v[186:189], v177 offset:50176
	ds_read_b128 v[190:193], v177 offset:51200
	ds_read_b128 v[194:197], v177 offset:52224
	ds_read_b128 v[198:201], v177 offset:53248
	ds_read_b128 v[210:213], v177 offset:54272
	ds_read_b128 v[214:217], v177 offset:55296
	ds_read_b128 v[218:221], v177 offset:56320
	global_load_lds_dwordx4 v[168:169], off
	s_add_i32 m0, s8, 0x2000
	s_add_u32 s8, s96, 0x40080
	v_lshl_add_u64 v[168:169], v[206:207], 0, s[92:93]
	s_addc_u32 s9, s97, 0
	s_add_i32 s66, s70, s81
	global_load_lds_dwordx4 v[168:169], off
	v_lshl_add_u64 v[168:169], s[8:9], 0, v[0:1]
	s_mov_b32 m0, s66
	s_nop 0
	global_load_lds_dwordx4 v[168:169], off
	v_lshl_add_u64 v[168:169], s[8:9], 0, v[158:159]
	s_add_i32 m0, s66, 0x2000
	s_nop 0
	global_load_lds_dwordx4 v[168:169], off
	v_lshl_add_u64 v[168:169], v[222:223], 0, s[92:93]
	s_mov_b32 m0, s13
	s_nop 0
	global_load_lds_dwordx4 v[168:169], off
	v_lshl_add_u64 v[168:169], v[224:225], 0, s[92:93]
	s_mov_b32 m0, s12
	s_nop 0
	global_load_lds_dwordx4 v[168:169], off
	s_waitcnt vmcnt(8)
	s_waitcnt lgkmcnt(0)
	s_barrier
	s_waitcnt lgkmcnt(0)
	v_mfma_i32_16x16x64_i8 v[62:65], v[66:69], v[182:185], v[62:65]
	v_mfma_i32_16x16x64_i8 v[54:57], v[106:109], v[182:185], v[54:57]
	v_mfma_i32_16x16x64_i8 v[46:49], v[106:109], v[190:193], v[46:49]
	v_mfma_i32_16x16x64_i8 v[58:61], v[66:69], v[190:193], v[58:61]
	v_mfma_i32_16x16x64_i8 v[50:53], v[66:69], v[198:201], v[50:53]
	v_mfma_i32_16x16x64_i8 v[38:41], v[106:109], v[198:201], v[38:41]
	v_mfma_i32_16x16x64_i8 v[34:37], v[106:109], v[214:217], v[34:37]
	v_mfma_i32_16x16x64_i8 v[42:45], v[66:69], v[214:217], v[42:45]
	v_mfma_i32_16x16x64_i8 v[2:5], v[126:129], v[214:217], v[2:5]
	v_mfma_i32_16x16x64_i8 v[22:25], v[126:129], v[182:185], v[22:25]
	v_mfma_i32_16x16x64_i8 v[30:33], v[114:117], v[182:185], v[30:33]
	v_mfma_i32_16x16x64_i8 v[26:29], v[114:117], v[190:193], v[26:29]
	v_mfma_i32_16x16x64_i8 v[14:17], v[126:129], v[190:193], v[14:17]
	v_mfma_i32_16x16x64_i8 v[6:9], v[126:129], v[198:201], v[6:9]
	v_mfma_i32_16x16x64_i8 v[18:21], v[114:117], v[198:201], v[18:21]
	v_mfma_i32_16x16x64_i8 v[10:13], v[114:117], v[214:217], v[10:13]
	v_mfma_i32_16x16x64_i8 v[62:65], v[70:73], v[186:189], v[62:65]
	v_mfma_i32_16x16x64_i8 v[54:57], v[110:113], v[186:189], v[54:57]
	v_mfma_i32_16x16x64_i8 v[46:49], v[110:113], v[194:197], v[46:49]
	v_mfma_i32_16x16x64_i8 v[58:61], v[70:73], v[194:197], v[58:61]
	v_mfma_i32_16x16x64_i8 v[50:53], v[70:73], v[210:213], v[50:53]
	v_mfma_i32_16x16x64_i8 v[38:41], v[110:113], v[210:213], v[38:41]
	v_mfma_i32_16x16x64_i8 v[34:37], v[110:113], v[218:221], v[34:37]
	v_mfma_i32_16x16x64_i8 v[42:45], v[70:73], v[218:221], v[42:45]
	v_mfma_i32_16x16x64_i8 v[2:5], v[178:181], v[218:221], v[2:5]
	v_mfma_i32_16x16x64_i8 v[22:25], v[178:181], v[186:189], v[22:25]
	v_mfma_i32_16x16x64_i8 v[30:33], v[118:121], v[186:189], v[30:33]
	v_mfma_i32_16x16x64_i8 v[26:29], v[118:121], v[194:197], v[26:29]
	v_mfma_i32_16x16x64_i8 v[14:17], v[178:181], v[194:197], v[14:17]
	v_mfma_i32_16x16x64_i8 v[6:9], v[178:181], v[210:213], v[6:9]
	v_mfma_i32_16x16x64_i8 v[18:21], v[118:121], v[210:213], v[18:21]
	v_mfma_i32_16x16x64_i8 v[10:13], v[118:121], v[218:221], v[10:13]
	s_barrier
	s_add_i32 s10, s10, 2
	s_add_u32 s69, s69, 0x100
	s_addc_u32 s68, s68, 0
	s_cmp_gt_u32 s10, 13
	s_mov_b64 s[8:9], s[84:85]
	s_cbranch_scc0 .LBB0_291

; #define PG8_STAGE(bufoff, gbase, voff) do { _Pragma("unroll") for (int _i = 0; _i < 2; ++_i) \
;         __builtin_amdgcn_global_load_lds((const unsigned*)((const char*)(gbase) + (voff)[_i]), (PG8_LAS unsigned*)(lds + (bufoff) + ldsw + _i * 8192), 16, 0, 0); } while (0)
; #define PG8_LDA(dst, b, h) do { _Pragma("unroll") for (int m = 0; m < 4; ++m) _Pragma("unroll") for (int k = 0; k < 2; ++k) dst[m][k] = *(const PG8_LAS bf16x8*)(lds + PG8_SA(b, h) + aoff + m * 2048 + k * 1024); } while (0)
; #define PG8_LDB(dst, b, h) do { _Pragma("unroll") for (int n = 0; n < 2; ++n) _Pragma("unroll") for (int k = 0; k < 2; ++k) dst[n][k] = *(const PG8_LAS bf16x8*)(lds + PG8_SB(b, h) + boff + n * 2048 + k * 1024); } while (0)
; template <class Epi, class Sched, bool ALIGN_EPI = false, bool SP2 = false>
; __device__ __forceinline__ void gemm_phase(PG8_LAS unsigned char* lds, const Gemm g, const Sched& S, const Epi& E) {
;     ...
;         for (int t = 0; t < nt; t += 2) {
;             const bool last = (t == nt - 2);
;             const char* a1 = cA + (size_t)(t + 1) * kstep;
;             const char* a2 = last ? nA : cA + (size_t)(t + 2) * kstep; const char* b2 = last ? nB : cB + (size_t)(t + 2) * kstep;
;             const char* a3 = a2 + kstep; const char* b3 = b2 + kstep;
;             if (last && has_next) S.a_ready(nxt);
;             if constexpr (SP2) {
;             PG8_LDB(B0, 0, 0); PG8_LDB(B1, 0, 1); PG8_SCHED; PG8_LDA(At, 0, 0); PG8_STAGE(PG8_SA(1, 1), a1 + hstep, voffA);
;             PG8_WAIT_V(8); PG8_WAIT_L(0); PG8_BAR; PG8_MMA(0, 0, At, B0); PG8_MMA(0, 1, At, B1); PG8_BAR; PG8_SCHED;
;             PG8_LDA(At, 0, 1); PG8_STAGE(PG8_SB(0, 0), b2, voffB); PG8_STAGE(PG8_SB(0, 1), b2 + hstep, voffB); PG8_STAGE(PG8_SA(0, 0), a2, voffA);
;             PG8_WAIT_V(8); PG8_WAIT_L(0); PG8_BAR; PG8_MMA(1, 0, At, B0); PG8_MMA(1, 1, At, B1); PG8_BAR; PG8_SCHED;
;             PG8_LDB(B0, 1, 0); PG8_LDB(B1, 1, 1); PG8_SCHED; PG8_LDA(At, 1, 0); PG8_STAGE(PG8_SA(0, 1), a2 + hstep, voffA);
;             PG8_WAIT_V(8); PG8_WAIT_L(0); PG8_BAR; PG8_MMA(0, 0, At, B0); PG8_MMA(0, 1, At, B1); PG8_BAR; PG8_SCHED;
;             PG8_LDA(At, 1, 1); PG8_STAGE(PG8_SB(1, 0), b3, voffB); PG8_STAGE(PG8_SB(1, 1), b3 + hstep, voffB); PG8_STAGE(PG8_SA(1, 0), a3, voffA);
;             PG8_WAIT_V(8); PG8_WAIT_L(0); PG8_BAR; PG8_MMA(1, 0, At, B0); PG8_MMA(1, 1, At, B1); PG8_BAR; PG8_SCHED;
.Lpeel327:
	s_add_u32 s68, s8, 0x100
	s_addc_u32 s69, s9, 0
	s_add_i32 s84, 0, 0x10000
	s_cmp_eq_u32 s4, 28
	s_cselect_b32 vcc_hi, s1, s69
	s_cselect_b32 vcc_lo, s5, s68
	v_add_u32_e32 v0, s84, v188
	s_cselect_b32 s71, s7, s96
	s_cselect_b32 s70, s85, s97
	s_add_i32 s10, 0, 0x14000
	ds_read_b128 v[52:55], v0
	ds_read_b128 v[56:59], v0 offset:1024
	ds_read_b128 v[76:79], v0 offset:2048
	ds_read_b128 v[80:83], v0 offset:3072
	v_add_u32_e32 v0, s10, v188
	ds_read_b128 v[116:119], v0
	ds_read_b128 v[120:123], v0 offset:1024
	ds_read_b128 v[168:171], v0 offset:2048
	ds_read_b128 v[172:175], v0 offset:3072
	v_lshl_add_u64 v[2:3], s[8:9], 0, v[164:165]
	s_add_i32 m0, s58, 0xc000
	ds_read_b128 v[176:179], v189
	ds_read_b128 v[180:183], v189 offset:1024
	ds_read_b128 v[190:193], v189 offset:2048
	ds_read_b128 v[194:197], v189 offset:3072
	ds_read_b128 v[198:201], v189 offset:4096
	ds_read_b128 v[210:213], v189 offset:5120
	ds_read_b128 v[214:217], v189 offset:6144
	ds_read_b128 v[218:221], v189 offset:7168
	global_load_lds_dwordx4 v[2:3], off
	v_lshl_add_u64 v[2:3], s[8:9], 0, v[166:167]
	s_add_i32 m0, s58, 0xe000
	s_nop 0
	global_load_lds_dwordx4 v[2:3], off
	s_waitcnt vmcnt(8)
	s_waitcnt lgkmcnt(0)
	s_barrier
	s_waitcnt lgkmcnt(0)
	v_mfma_f32_16x16x32_bf16 v[152:155], v[52:55], v[176:179], 0
	v_mfma_f32_16x16x32_bf16 v[144:147], v[76:79], v[176:179], 0
	v_mfma_f32_16x16x32_bf16 v[140:143], v[76:79], v[190:193], 0
	v_mfma_f32_16x16x32_bf16 v[148:151], v[52:55], v[190:193], 0
	v_mfma_f32_16x16x32_bf16 v[136:139], v[52:55], v[198:201], 0
	v_mfma_f32_16x16x32_bf16 v[132:135], v[76:79], v[198:201], 0
	v_mfma_f32_16x16x32_bf16 v[124:127], v[76:79], v[214:217], 0
	v_mfma_f32_16x16x32_bf16 v[128:131], v[52:55], v[214:217], 0
	v_mfma_f32_16x16x32_bf16 v[84:87], v[168:171], v[214:217], 0
	v_mfma_f32_16x16x32_bf16 v[104:107], v[168:171], v[176:179], 0
	v_mfma_f32_16x16x32_bf16 v[112:115], v[116:119], v[176:179], 0
	v_mfma_f32_16x16x32_bf16 v[108:111], v[116:119], v[190:193], 0
	v_mfma_f32_16x16x32_bf16 v[100:103], v[168:171], v[190:193], 0
	v_mfma_f32_16x16x32_bf16 v[92:95], v[168:171], v[198:201], 0
	v_mfma_f32_16x16x32_bf16 v[96:99], v[116:119], v[198:201], 0
	v_mfma_f32_16x16x32_bf16 v[88:91], v[116:119], v[214:217], 0
	v_mfma_f32_16x16x32_bf16 v[152:155], v[56:59], v[180:183], v[152:155]
	v_mfma_f32_16x16x32_bf16 v[144:147], v[80:83], v[180:183], v[144:147]
	v_mfma_f32_16x16x32_bf16 v[140:143], v[80:83], v[194:197], v[140:143]
	v_mfma_f32_16x16x32_bf16 v[148:151], v[56:59], v[194:197], v[148:151]
	v_mfma_f32_16x16x32_bf16 v[136:139], v[56:59], v[210:213], v[136:139]
	v_mfma_f32_16x16x32_bf16 v[132:135], v[80:83], v[210:213], v[132:135]
	v_mfma_f32_16x16x32_bf16 v[124:127], v[80:83], v[218:221], v[124:127]
	v_mfma_f32_16x16x32_bf16 v[128:131], v[56:59], v[218:221], v[128:131]
	v_mfma_f32_16x16x32_bf16 v[84:87], v[172:175], v[218:221], v[84:87]
	v_mfma_f32_16x16x32_bf16 v[104:107], v[172:175], v[180:183], v[104:107]
	v_mfma_f32_16x16x32_bf16 v[112:115], v[120:123], v[180:183], v[112:115]
	v_mfma_f32_16x16x32_bf16 v[108:111], v[120:123], v[194:197], v[108:111]
	v_mfma_f32_16x16x32_bf16 v[100:103], v[172:175], v[194:197], v[100:103]
	v_mfma_f32_16x16x32_bf16 v[92:95], v[172:175], v[210:213], v[92:95]
	v_mfma_f32_16x16x32_bf16 v[96:99], v[120:123], v[210:213], v[96:99]
	v_mfma_f32_16x16x32_bf16 v[88:91], v[120:123], v[218:221], v[88:91]
	s_barrier
	s_add_i32 s8, s84, s80
	v_lshl_add_u64 v[184:185], s[70:71], 0, v[158:159]
	s_mov_b32 m0, s8
	ds_read_b128 v[176:179], v189 offset:16384
	ds_read_b128 v[180:183], v189 offset:17408
	ds_read_b128 v[190:193], v189 offset:18432
	ds_read_b128 v[194:197], v189 offset:19456
	ds_read_b128 v[198:201], v189 offset:20480
	ds_read_b128 v[210:213], v189 offset:21504
	ds_read_b128 v[214:217], v189 offset:22528
	ds_read_b128 v[218:221], v189 offset:23552
	global_load_lds_dwordx4 v[184:185], off
	s_add_i32 m0, s8, 0x2000
	s_add_u32 s8, s70, 0x80000
	v_lshl_add_u64 v[206:207], s[70:71], 0, v[162:163]
	s_addc_u32 s9, s71, 0
	s_add_i32 s10, s10, s80
	global_load_lds_dwordx4 v[206:207], off
	v_lshl_add_u64 v[2:3], s[8:9], 0, v[158:159]
	s_mov_b32 m0, s10
	v_lshl_add_u64 v[222:223], vcc, 0, v[156:157]
	global_load_lds_dwordx4 v[2:3], off
	v_lshl_add_u64 v[2:3], s[8:9], 0, v[162:163]
	s_add_i32 m0, s10, 0x2000
	v_lshl_add_u64 v[224:225], vcc, 0, v[160:161]
	global_load_lds_dwordx4 v[2:3], off
	s_mov_b32 m0, s58
	s_nop 0
	global_load_lds_dwordx4 v[222:223], off
	s_mov_b32 m0, s12
	s_nop 0
	global_load_lds_dwordx4 v[224:225], off
	s_waitcnt vmcnt(8)
	s_waitcnt lgkmcnt(0)
	s_barrier
	s_waitcnt lgkmcnt(0)
	v_mfma_f32_16x16x32_bf16 v[72:75], v[52:55], v[176:179], 0
	v_mfma_f32_16x16x32_bf16 v[64:67], v[76:79], v[176:179], 0
	v_mfma_f32_16x16x32_bf16 v[60:63], v[76:79], v[190:193], 0
	v_mfma_f32_16x16x32_bf16 v[68:71], v[52:55], v[190:193], 0
	v_mfma_f32_16x16x32_bf16 v[48:51], v[52:55], v[198:201], 0
	v_mfma_f32_16x16x32_bf16 v[44:47], v[76:79], v[198:201], 0
	v_mfma_f32_16x16x32_bf16 v[36:39], v[76:79], v[214:217], 0
	v_mfma_f32_16x16x32_bf16 v[40:43], v[52:55], v[214:217], 0
	v_mfma_f32_16x16x32_bf16 v[2:5], v[168:171], v[214:217], 0
	v_mfma_f32_16x16x32_bf16 v[24:27], v[168:171], v[176:179], 0
	v_mfma_f32_16x16x32_bf16 v[32:35], v[116:119], v[176:179], 0
	v_mfma_f32_16x16x32_bf16 v[28:31], v[116:119], v[190:193], 0
	v_mfma_f32_16x16x32_bf16 v[20:23], v[168:171], v[190:193], 0
	v_mfma_f32_16x16x32_bf16 v[12:15], v[168:171], v[198:201], 0
	v_mfma_f32_16x16x32_bf16 v[16:19], v[116:119], v[198:201], 0
	v_mfma_f32_16x16x32_bf16 v[8:11], v[116:119], v[214:217], 0
	v_mfma_f32_16x16x32_bf16 v[72:75], v[56:59], v[180:183], v[72:75]
	v_mfma_f32_16x16x32_bf16 v[64:67], v[80:83], v[180:183], v[64:67]
	v_mfma_f32_16x16x32_bf16 v[60:63], v[80:83], v[194:197], v[60:63]
	v_mfma_f32_16x16x32_bf16 v[68:71], v[56:59], v[194:197], v[68:71]
	v_mfma_f32_16x16x32_bf16 v[48:51], v[56:59], v[210:213], v[48:51]
	v_mfma_f32_16x16x32_bf16 v[44:47], v[80:83], v[210:213], v[44:47]
	v_mfma_f32_16x16x32_bf16 v[36:39], v[80:83], v[218:221], v[36:39]
	v_mfma_f32_16x16x32_bf16 v[40:43], v[56:59], v[218:221], v[40:43]
	v_mfma_f32_16x16x32_bf16 v[2:5], v[172:175], v[218:221], v[2:5]
	v_mfma_f32_16x16x32_bf16 v[24:27], v[172:175], v[180:183], v[24:27]
	v_mfma_f32_16x16x32_bf16 v[32:35], v[120:123], v[180:183], v[32:35]
	v_mfma_f32_16x16x32_bf16 v[28:31], v[120:123], v[194:197], v[28:31]
	v_mfma_f32_16x16x32_bf16 v[20:23], v[172:175], v[194:197], v[20:23]
	v_mfma_f32_16x16x32_bf16 v[12:15], v[172:175], v[210:213], v[12:15]
	v_mfma_f32_16x16x32_bf16 v[16:19], v[120:123], v[210:213], v[16:19]
	v_mfma_f32_16x16x32_bf16 v[8:11], v[120:123], v[218:221], v[8:11]
	s_barrier
; #define PG8_STAGE(bufoff, gbase, voff) do { _Pragma("unroll") for (int _i = 0; _i < 2; ++_i) \
;         __builtin_amdgcn_global_load_lds((const unsigned*)((const char*)(gbase) + (voff)[_i]), (PG8_LAS unsigned*)(lds + (bufoff) + ldsw + _i * 8192), 16, 0, 0); } while (0)
; #define PG8_LDA(dst, b, h) do { _Pragma("unroll") for (int m = 0; m < 4; ++m) _Pragma("unroll") for (int k = 0; k < 2; ++k) dst[m][k] = *(const PG8_LAS bf16x8*)(lds + PG8_SA(b, h) + aoff + m * 2048 + k * 1024); } while (0)
; #define PG8_LDB(dst, b, h) do { _Pragma("unroll") for (int n = 0; n < 2; ++n) _Pragma("unroll") for (int k = 0; k < 2; ++k) dst[n][k] = *(const PG8_LAS bf16x8*)(lds + PG8_SB(b, h) + boff + n * 2048 + k * 1024); } while (0)
; template <class Epi, class Sched, bool ALIGN_EPI = false, bool SP2 = false>
; __device__ __forceinline__ void gemm_phase(PG8_LAS unsigned char* lds, const Gemm g, const Sched& S, const Epi& E) {
;     ...
;         for (int t = 0; t < nt; t += 2) {
;             const bool last = (t == nt - 2);
;             const char* a1 = cA + (size_t)(t + 1) * kstep;
;             const char* a2 = last ? nA : cA + (size_t)(t + 2) * kstep; const char* b2 = last ? nB : cB + (size_t)(t + 2) * kstep;
;             const char* a3 = a2 + kstep; const char* b3 = b2 + kstep;
;             if (last && has_next) S.a_ready(nxt);
;             if constexpr (SP2) {
;             PG8_LDB(B0, 0, 0); PG8_LDB(B1, 0, 1); PG8_SCHED; PG8_LDA(At, 0, 0); PG8_STAGE(PG8_SA(1, 1), a1 + hstep, voffA);
;             PG8_WAIT_V(8); PG8_WAIT_L(0); PG8_BAR; PG8_MMA(0, 0, At, B0); PG8_MMA(0, 1, At, B1); PG8_BAR; PG8_SCHED;
;             PG8_LDA(At, 0, 1); PG8_STAGE(PG8_SB(0, 0), b2, voffB); PG8_STAGE(PG8_SB(0, 1), b2 + hstep, voffB); PG8_STAGE(PG8_SA(0, 0), a2, voffA);
;             PG8_WAIT_V(8); PG8_WAIT_L(0); PG8_BAR; PG8_MMA(1, 0, At, B0); PG8_MMA(1, 1, At, B1); PG8_BAR; PG8_SCHED;
;             PG8_LDB(B0, 1, 0); PG8_LDB(B1, 1, 1); PG8_SCHED; PG8_LDA(At, 1, 0); PG8_STAGE(PG8_SA(0, 1), a2 + hstep, voffA);
;             PG8_WAIT_V(8); PG8_WAIT_L(0); PG8_BAR; PG8_MMA(0, 0, At, B0); PG8_MMA(0, 1, At, B1); PG8_BAR; PG8_SCHED;
;             PG8_LDA(At, 1, 1); PG8_STAGE(PG8_SB(1, 0), b3, voffB); PG8_STAGE(PG8_SB(1, 1), b3 + hstep, voffB); PG8_STAGE(PG8_SA(1, 0), a3, voffA);
;             PG8_WAIT_V(8); PG8_WAIT_L(0); PG8_BAR; PG8_MMA(1, 0, At, B0); PG8_MMA(1, 1, At, B1); PG8_BAR; PG8_SCHED;
	s_add_i32 s10, 0, 0x18000
	v_add_u32_e32 v0, s10, v188
	s_add_i32 s11, 0, 0x1c000
	ds_read_b128 v[52:55], v0
	ds_read_b128 v[56:59], v0 offset:1024
	ds_read_b128 v[76:79], v0 offset:2048
	ds_read_b128 v[80:83], v0 offset:3072
	v_add_u32_e32 v0, s11, v188
	ds_read_b128 v[116:119], v0
	ds_read_b128 v[120:123], v0 offset:1024
	ds_read_b128 v[168:171], v0 offset:2048
	ds_read_b128 v[172:175], v0 offset:3072
	s_add_u32 s8, vcc_lo, 0x80000
	s_addc_u32 s9, vcc_hi, 0
	s_mov_b32 m0, s13
	v_lshl_add_u64 v[6:7], s[8:9], 0, v[156:157]
	ds_read_b128 v[176:179], v189 offset:32768
	ds_read_b128 v[180:183], v189 offset:33792
	ds_read_b128 v[190:193], v189 offset:34816
	ds_read_b128 v[194:197], v189 offset:35840
	ds_read_b128 v[198:201], v189 offset:36864
	ds_read_b128 v[210:213], v189 offset:37888
	ds_read_b128 v[214:217], v189 offset:38912
	ds_read_b128 v[218:221], v189 offset:39936
	global_load_lds_dwordx4 v[6:7], off
	v_lshl_add_u64 v[6:7], s[8:9], 0, v[160:161]
	s_mov_b32 m0, s66
	s_nop 0
	global_load_lds_dwordx4 v[6:7], off
	s_waitcnt vmcnt(8)
	s_waitcnt lgkmcnt(0)
	s_barrier
	s_waitcnt lgkmcnt(0)
	v_mfma_f32_16x16x32_bf16 v[152:155], v[52:55], v[176:179], v[152:155]
	v_mfma_f32_16x16x32_bf16 v[144:147], v[76:79], v[176:179], v[144:147]
	v_mfma_f32_16x16x32_bf16 v[140:143], v[76:79], v[190:193], v[140:143]
	v_mfma_f32_16x16x32_bf16 v[148:151], v[52:55], v[190:193], v[148:151]
	v_mfma_f32_16x16x32_bf16 v[136:139], v[52:55], v[198:201], v[136:139]
	v_mfma_f32_16x16x32_bf16 v[132:135], v[76:79], v[198:201], v[132:135]
	v_mfma_f32_16x16x32_bf16 v[124:127], v[76:79], v[214:217], v[124:127]
	v_mfma_f32_16x16x32_bf16 v[128:131], v[52:55], v[214:217], v[128:131]
	v_mfma_f32_16x16x32_bf16 v[84:87], v[168:171], v[214:217], v[84:87]
	v_mfma_f32_16x16x32_bf16 v[104:107], v[168:171], v[176:179], v[104:107]
	v_mfma_f32_16x16x32_bf16 v[112:115], v[116:119], v[176:179], v[112:115]
	v_mfma_f32_16x16x32_bf16 v[108:111], v[116:119], v[190:193], v[108:111]
	v_mfma_f32_16x16x32_bf16 v[100:103], v[168:171], v[190:193], v[100:103]
	v_mfma_f32_16x16x32_bf16 v[92:95], v[168:171], v[198:201], v[92:95]
	v_mfma_f32_16x16x32_bf16 v[96:99], v[116:119], v[198:201], v[96:99]
	v_mfma_f32_16x16x32_bf16 v[88:91], v[116:119], v[214:217], v[88:91]
	v_mfma_f32_16x16x32_bf16 v[152:155], v[56:59], v[180:183], v[152:155]
	v_mfma_f32_16x16x32_bf16 v[144:147], v[80:83], v[180:183], v[144:147]
	v_mfma_f32_16x16x32_bf16 v[140:143], v[80:83], v[194:197], v[140:143]
	v_mfma_f32_16x16x32_bf16 v[148:151], v[56:59], v[194:197], v[148:151]
	v_mfma_f32_16x16x32_bf16 v[136:139], v[56:59], v[210:213], v[136:139]
	v_mfma_f32_16x16x32_bf16 v[132:135], v[80:83], v[210:213], v[132:135]
	v_mfma_f32_16x16x32_bf16 v[124:127], v[80:83], v[218:221], v[124:127]
	v_mfma_f32_16x16x32_bf16 v[128:131], v[56:59], v[218:221], v[128:131]
	v_mfma_f32_16x16x32_bf16 v[84:87], v[172:175], v[218:221], v[84:87]
	v_mfma_f32_16x16x32_bf16 v[104:107], v[172:175], v[180:183], v[104:107]
	v_mfma_f32_16x16x32_bf16 v[112:115], v[120:123], v[180:183], v[112:115]
	v_mfma_f32_16x16x32_bf16 v[108:111], v[120:123], v[194:197], v[108:111]
	v_mfma_f32_16x16x32_bf16 v[100:103], v[172:175], v[194:197], v[100:103]
	v_mfma_f32_16x16x32_bf16 v[92:95], v[172:175], v[210:213], v[92:95]
	v_mfma_f32_16x16x32_bf16 v[96:99], v[120:123], v[210:213], v[96:99]
	v_mfma_f32_16x16x32_bf16 v[88:91], v[120:123], v[218:221], v[88:91]
	s_barrier
	s_add_i32 s8, s10, s80
	v_lshl_add_u64 v[6:7], v[184:185], 0, s[92:93]
	s_mov_b32 m0, s8
	ds_read_b128 v[176:179], v189 offset:49152
	ds_read_b128 v[180:183], v189 offset:50176
	ds_read_b128 v[190:193], v189 offset:51200
	ds_read_b128 v[194:197], v189 offset:52224
	ds_read_b128 v[198:201], v189 offset:53248
	ds_read_b128 v[210:213], v189 offset:54272
	ds_read_b128 v[214:217], v189 offset:55296
	ds_read_b128 v[218:221], v189 offset:56320
	global_load_lds_dwordx4 v[6:7], off
	s_add_i32 m0, s8, 0x2000
	s_add_u32 s8, s70, 0x80080
	v_lshl_add_u64 v[6:7], v[206:207], 0, s[92:93]
	s_addc_u32 s9, s71, 0
	s_add_i32 s10, s11, s80
	global_load_lds_dwordx4 v[6:7], off
	v_lshl_add_u64 v[6:7], s[8:9], 0, v[158:159]
	s_mov_b32 m0, s10
	s_nop 0
	global_load_lds_dwordx4 v[6:7], off
	v_lshl_add_u64 v[6:7], s[8:9], 0, v[162:163]
	s_add_i32 m0, s10, 0x2000
	s_nop 0
	global_load_lds_dwordx4 v[6:7], off
	v_lshl_add_u64 v[6:7], v[222:223], 0, s[92:93]
	s_mov_b32 m0, s67
	s_nop 0
	global_load_lds_dwordx4 v[6:7], off
	v_lshl_add_u64 v[6:7], v[224:225], 0, s[92:93]
	s_mov_b32 m0, s81
	s_nop 0
	global_load_lds_dwordx4 v[6:7], off
	s_waitcnt vmcnt(8)
	s_waitcnt lgkmcnt(0)
	s_barrier
	s_waitcnt lgkmcnt(0)
	v_mfma_f32_16x16x32_bf16 v[72:75], v[52:55], v[176:179], v[72:75]
	v_mfma_f32_16x16x32_bf16 v[64:67], v[76:79], v[176:179], v[64:67]
	v_mfma_f32_16x16x32_bf16 v[60:63], v[76:79], v[190:193], v[60:63]
	v_mfma_f32_16x16x32_bf16 v[68:71], v[52:55], v[190:193], v[68:71]
	v_mfma_f32_16x16x32_bf16 v[48:51], v[52:55], v[198:201], v[48:51]
	v_mfma_f32_16x16x32_bf16 v[44:47], v[76:79], v[198:201], v[44:47]
	v_mfma_f32_16x16x32_bf16 v[36:39], v[76:79], v[214:217], v[36:39]
	v_mfma_f32_16x16x32_bf16 v[40:43], v[52:55], v[214:217], v[40:43]
	v_mfma_f32_16x16x32_bf16 v[2:5], v[168:171], v[214:217], v[2:5]
	v_mfma_f32_16x16x32_bf16 v[24:27], v[168:171], v[176:179], v[24:27]
	v_mfma_f32_16x16x32_bf16 v[32:35], v[116:119], v[176:179], v[32:35]
	v_mfma_f32_16x16x32_bf16 v[28:31], v[116:119], v[190:193], v[28:31]
	v_mfma_f32_16x16x32_bf16 v[20:23], v[168:171], v[190:193], v[20:23]
	v_mfma_f32_16x16x32_bf16 v[12:15], v[168:171], v[198:201], v[12:15]
	v_mfma_f32_16x16x32_bf16 v[16:19], v[116:119], v[198:201], v[16:19]
	v_mfma_f32_16x16x32_bf16 v[6:9], v[116:119], v[214:217], v[8:11]
	v_mfma_f32_16x16x32_bf16 v[72:75], v[56:59], v[180:183], v[72:75]
	v_mfma_f32_16x16x32_bf16 v[64:67], v[80:83], v[180:183], v[64:67]
	v_mfma_f32_16x16x32_bf16 v[60:63], v[80:83], v[194:197], v[60:63]
	v_mfma_f32_16x16x32_bf16 v[68:71], v[56:59], v[194:197], v[68:71]
	v_mfma_f32_16x16x32_bf16 v[48:51], v[56:59], v[210:213], v[48:51]
	v_mfma_f32_16x16x32_bf16 v[44:47], v[80:83], v[210:213], v[44:47]
	v_mfma_f32_16x16x32_bf16 v[36:39], v[80:83], v[218:221], v[36:39]
	v_mfma_f32_16x16x32_bf16 v[40:43], v[56:59], v[218:221], v[40:43]
	v_mfma_f32_16x16x32_bf16 v[8:11], v[120:123], v[218:221], v[6:9]
	v_mfma_f32_16x16x32_bf16 v[32:35], v[120:123], v[180:183], v[32:35]
	v_mfma_f32_16x16x32_bf16 v[24:27], v[172:175], v[180:183], v[24:27]
	v_mfma_f32_16x16x32_bf16 v[20:23], v[172:175], v[194:197], v[20:23]
	v_mfma_f32_16x16x32_bf16 v[28:31], v[120:123], v[194:197], v[28:31]
	v_mfma_f32_16x16x32_bf16 v[16:19], v[120:123], v[210:213], v[16:19]
	v_mfma_f32_16x16x32_bf16 v[12:15], v[172:175], v[210:213], v[12:15]
	v_mfma_f32_16x16x32_bf16 v[4:7], v[172:175], v[218:221], v[2:5]
	s_barrier
	s_add_i32 s4, s4, 2
	s_add_u32 s97, s97, 0x100
	s_addc_u32 s96, s96, 0
	s_cmp_gt_u32 s4, 29
	s_mov_b64 s[8:9], s[68:69]
	s_cbranch_scc0 .LBB0_327
	s_branch .Lpeelx327
; #define PG8_STAGE(bufoff, gbase, voff) do { _Pragma("unroll") for (int _i = 0; _i < 2; ++_i) \
;         __builtin_amdgcn_global_load_lds((const unsigned*)((const char*)(gbase) + (voff)[_i]), (PG8_LAS unsigned*)(lds + (bufoff) + ldsw + _i * 8192), 16, 0, 0); } while (0)
; #define PG8_LDA(dst, b, h) do { _Pragma("unroll") for (int m = 0; m < 4; ++m) _Pragma("unroll") for (int k = 0; k < 2; ++k) dst[m][k] = *(const PG8_LAS bf16x8*)(lds + PG8_SA(b, h) + aoff + m * 2048 + k * 1024); } while (0)
; #define PG8_LDB(dst, b, h) do { _Pragma("unroll") for (int n = 0; n < 2; ++n) _Pragma("unroll") for (int k = 0; k < 2; ++k) dst[n][k] = *(const PG8_LAS bf16x8*)(lds + PG8_SB(b, h) + boff + n * 2048 + k * 1024); } while (0)
; template <class Epi, class Sched, bool ALIGN_EPI = false, bool SP2 = false>
; __device__ __forceinline__ void gemm_phase(PG8_LAS unsigned char* lds, const Gemm g, const Sched& S, const Epi& E) {
;     ...
;         for (int t = 0; t < nt; t += 2) {
;             const bool last = (t == nt - 2);
;             const char* a1 = cA + (size_t)(t + 1) * kstep;
;             const char* a2 = last ? nA : cA + (size_t)(t + 2) * kstep; const char* b2 = last ? nB : cB + (size_t)(t + 2) * kstep;
;             const char* a3 = a2 + kstep; const char* b3 = b2 + kstep;
;             if (last && has_next) S.a_ready(nxt);
;             if constexpr (SP2) {
;             PG8_LDB(B0, 0, 0); PG8_LDB(B1, 0, 1); PG8_SCHED; PG8_LDA(At, 0, 0); PG8_STAGE(PG8_SA(1, 1), a1 + hstep, voffA);
;             PG8_WAIT_V(8); PG8_WAIT_L(0); PG8_BAR; PG8_MMA(0, 0, At, B0); PG8_MMA(0, 1, At, B1); PG8_BAR; PG8_SCHED;
;             PG8_LDA(At, 0, 1); PG8_STAGE(PG8_SB(0, 0), b2, voffB); PG8_STAGE(PG8_SB(0, 1), b2 + hstep, voffB); PG8_STAGE(PG8_SA(0, 0), a2, voffA);
;             PG8_WAIT_V(8); PG8_WAIT_L(0); PG8_BAR; PG8_MMA(1, 0, At, B0); PG8_MMA(1, 1, At, B1); PG8_BAR; PG8_SCHED;
;             PG8_LDB(B0, 1, 0); PG8_LDB(B1, 1, 1); PG8_SCHED; PG8_LDA(At, 1, 0); PG8_STAGE(PG8_SA(0, 1), a2 + hstep, voffA);
;             PG8_WAIT_V(8); PG8_WAIT_L(0); PG8_BAR; PG8_MMA(0, 0, At, B0); PG8_MMA(0, 1, At, B1); PG8_BAR; PG8_SCHED;
;             PG8_LDA(At, 1, 1); PG8_STAGE(PG8_SB(1, 0), b3, voffB); PG8_STAGE(PG8_SB(1, 1), b3 + hstep, voffB); PG8_STAGE(PG8_SA(1, 0), a3, voffA);
;             PG8_WAIT_V(8); PG8_WAIT_L(0); PG8_BAR; PG8_MMA(1, 0, At, B0); PG8_MMA(1, 1, At, B1); PG8_BAR; PG8_SCHED;
.LBB0_327:
	s_add_u32 s68, s8, 0x100
	s_addc_u32 s69, s9, 0
	s_add_i32 s84, 0, 0x10000
	s_cmp_eq_u32 s4, 28
	s_cselect_b32 vcc_hi, s1, s69
	s_cselect_b32 vcc_lo, s5, s68
	v_add_u32_e32 v0, s84, v188
	s_cselect_b32 s71, s7, s96
	s_cselect_b32 s70, s85, s97
	s_add_i32 s10, 0, 0x14000
	ds_read_b128 v[52:55], v0
	ds_read_b128 v[56:59], v0 offset:1024
	ds_read_b128 v[76:79], v0 offset:2048
	ds_read_b128 v[80:83], v0 offset:3072
	v_add_u32_e32 v0, s10, v188
	ds_read_b128 v[116:119], v0
	ds_read_b128 v[120:123], v0 offset:1024
	ds_read_b128 v[168:171], v0 offset:2048
	ds_read_b128 v[172:175], v0 offset:3072
	v_lshl_add_u64 v[2:3], s[8:9], 0, v[164:165]
	s_add_i32 m0, s58, 0xc000
	ds_read_b128 v[176:179], v189
	ds_read_b128 v[180:183], v189 offset:1024
	ds_read_b128 v[190:193], v189 offset:2048
	ds_read_b128 v[194:197], v189 offset:3072
	ds_read_b128 v[198:201], v189 offset:4096
	ds_read_b128 v[210:213], v189 offset:5120
	ds_read_b128 v[214:217], v189 offset:6144
	ds_read_b128 v[218:221], v189 offset:7168
	global_load_lds_dwordx4 v[2:3], off
	v_lshl_add_u64 v[2:3], s[8:9], 0, v[166:167]
	s_add_i32 m0, s58, 0xe000
	s_nop 0
	global_load_lds_dwordx4 v[2:3], off
	s_waitcnt vmcnt(8)
	s_waitcnt lgkmcnt(0)
	s_barrier
	s_waitcnt lgkmcnt(0)
	v_mfma_f32_16x16x32_bf16 v[152:155], v[52:55], v[176:179], v[152:155]
	v_mfma_f32_16x16x32_bf16 v[144:147], v[76:79], v[176:179], v[144:147]
	v_mfma_f32_16x16x32_bf16 v[140:143], v[76:79], v[190:193], v[140:143]
	v_mfma_f32_16x16x32_bf16 v[148:151], v[52:55], v[190:193], v[148:151]
	v_mfma_f32_16x16x32_bf16 v[136:139], v[52:55], v[198:201], v[136:139]
	v_mfma_f32_16x16x32_bf16 v[132:135], v[76:79], v[198:201], v[132:135]
	v_mfma_f32_16x16x32_bf16 v[124:127], v[76:79], v[214:217], v[124:127]
	v_mfma_f32_16x16x32_bf16 v[128:131], v[52:55], v[214:217], v[128:131]
	v_mfma_f32_16x16x32_bf16 v[84:87], v[168:171], v[214:217], v[84:87]
	v_mfma_f32_16x16x32_bf16 v[104:107], v[168:171], v[176:179], v[104:107]
	v_mfma_f32_16x16x32_bf16 v[112:115], v[116:119], v[176:179], v[112:115]
	v_mfma_f32_16x16x32_bf16 v[108:111], v[116:119], v[190:193], v[108:111]
	v_mfma_f32_16x16x32_bf16 v[100:103], v[168:171], v[190:193], v[100:103]
	v_mfma_f32_16x16x32_bf16 v[92:95], v[168:171], v[198:201], v[92:95]
	v_mfma_f32_16x16x32_bf16 v[96:99], v[116:119], v[198:201], v[96:99]
	v_mfma_f32_16x16x32_bf16 v[88:91], v[116:119], v[214:217], v[88:91]
	v_mfma_f32_16x16x32_bf16 v[152:155], v[56:59], v[180:183], v[152:155]
	v_mfma_f32_16x16x32_bf16 v[144:147], v[80:83], v[180:183], v[144:147]
	v_mfma_f32_16x16x32_bf16 v[140:143], v[80:83], v[194:197], v[140:143]
	v_mfma_f32_16x16x32_bf16 v[148:151], v[56:59], v[194:197], v[148:151]
	v_mfma_f32_16x16x32_bf16 v[136:139], v[56:59], v[210:213], v[136:139]
	v_mfma_f32_16x16x32_bf16 v[132:135], v[80:83], v[210:213], v[132:135]
	v_mfma_f32_16x16x32_bf16 v[124:127], v[80:83], v[218:221], v[124:127]
	v_mfma_f32_16x16x32_bf16 v[128:131], v[56:59], v[218:221], v[128:131]
	v_mfma_f32_16x16x32_bf16 v[84:87], v[172:175], v[218:221], v[84:87]
	v_mfma_f32_16x16x32_bf16 v[104:107], v[172:175], v[180:183], v[104:107]
	v_mfma_f32_16x16x32_bf16 v[112:115], v[120:123], v[180:183], v[112:115]
	v_mfma_f32_16x16x32_bf16 v[108:111], v[120:123], v[194:197], v[108:111]
	v_mfma_f32_16x16x32_bf16 v[100:103], v[172:175], v[194:197], v[100:103]
	v_mfma_f32_16x16x32_bf16 v[92:95], v[172:175], v[210:213], v[92:95]
	v_mfma_f32_16x16x32_bf16 v[96:99], v[120:123], v[210:213], v[96:99]
	v_mfma_f32_16x16x32_bf16 v[88:91], v[120:123], v[218:221], v[88:91]
	s_barrier
	s_add_i32 s8, s84, s80
	v_lshl_add_u64 v[184:185], s[70:71], 0, v[158:159]
	s_mov_b32 m0, s8
	ds_read_b128 v[176:179], v189 offset:16384
	ds_read_b128 v[180:183], v189 offset:17408
	ds_read_b128 v[190:193], v189 offset:18432
	ds_read_b128 v[194:197], v189 offset:19456
	ds_read_b128 v[198:201], v189 offset:20480
	ds_read_b128 v[210:213], v189 offset:21504
	ds_read_b128 v[214:217], v189 offset:22528
	ds_read_b128 v[218:221], v189 offset:23552
	global_load_lds_dwordx4 v[184:185], off
	s_add_i32 m0, s8, 0x2000
	s_add_u32 s8, s70, 0x80000
	v_lshl_add_u64 v[206:207], s[70:71], 0, v[162:163]
	s_addc_u32 s9, s71, 0
	s_add_i32 s10, s10, s80
	global_load_lds_dwordx4 v[206:207], off
	v_lshl_add_u64 v[2:3], s[8:9], 0, v[158:159]
	s_mov_b32 m0, s10
	v_lshl_add_u64 v[222:223], vcc, 0, v[156:157]
	global_load_lds_dwordx4 v[2:3], off
	v_lshl_add_u64 v[2:3], s[8:9], 0, v[162:163]
	s_add_i32 m0, s10, 0x2000
	v_lshl_add_u64 v[224:225], vcc, 0, v[160:161]
	global_load_lds_dwordx4 v[2:3], off
	s_mov_b32 m0, s58
	s_nop 0
	global_load_lds_dwordx4 v[222:223], off
	s_mov_b32 m0, s12
	s_nop 0
	global_load_lds_dwordx4 v[224:225], off
	s_waitcnt vmcnt(8)
	s_waitcnt lgkmcnt(0)
	s_barrier
; #define PG8_STAGE(bufoff, gbase, voff) do { _Pragma("unroll") for (int _i = 0; _i < 2; ++_i) \
;         __builtin_amdgcn_global_load_lds((const unsigned*)((const char*)(gbase) + (voff)[_i]), (PG8_LAS unsigned*)(lds + (bufoff) + ldsw + _i * 8192), 16, 0, 0); } while (0)
; #define PG8_LDA(dst, b, h) do { _Pragma("unroll") for (int m = 0; m < 4; ++m) _Pragma("unroll") for (int k = 0; k < 2; ++k) dst[m][k] = *(const PG8_LAS bf16x8*)(lds + PG8_SA(b, h) + aoff + m * 2048 + k * 1024); } while (0)
; #define PG8_LDB(dst, b, h) do { _Pragma("unroll") for (int n = 0; n < 2; ++n) _Pragma("unroll") for (int k = 0; k < 2; ++k) dst[n][k] = *(const PG8_LAS bf16x8*)(lds + PG8_SB(b, h) + boff + n * 2048 + k * 1024); } while (0)
; #define PG8_MMA(ai, bj, At, Bt) do { __builtin_amdgcn_s_setprio(1); _Pragma("unroll") for (int m = 0; m < 4; ++m) _Pragma("unroll") for (int n = 0; n < 2; ++n) _Pragma("unroll") for (int k = 0; k < 2; ++k) \
;         acc[ai][bj][m][n] = mma16<Epi::I8>(Bt[n][k], At[m][k], acc[ai][bj][m][n]); __builtin_amdgcn_s_setprio(0); } while (0)
; #define PG8_WAIT_V(n) asm volatile("s_waitcnt vmcnt(" #n ")" ::: "memory")
; template <class Epi, class Sched, bool ALIGN_EPI = false, bool SP2 = false>
; __device__ __forceinline__ void gemm_phase(PG8_LAS unsigned char* lds, const Gemm g, const Sched& S, const Epi& E) {
;     ...
;             PG8_LDB(B0, 0, 0); PG8_LDB(B1, 0, 1); PG8_SCHED; PG8_LDA(At, 0, 0); PG8_STAGE(PG8_SA(1, 1), a1 + hstep, voffA);
;             PG8_WAIT_V(8); PG8_WAIT_L(0); PG8_BAR; PG8_MMA(0, 0, At, B0); PG8_MMA(0, 1, At, B1); PG8_BAR; PG8_SCHED;
;             PG8_LDA(At, 0, 1); PG8_STAGE(PG8_SB(0, 0), b2, voffB); PG8_STAGE(PG8_SB(0, 1), b2 + hstep, voffB); PG8_STAGE(PG8_SA(0, 0), a2, voffA);
;             PG8_WAIT_V(8); PG8_WAIT_L(0); PG8_BAR; PG8_MMA(1, 0, At, B0); PG8_MMA(1, 1, At, B1); PG8_BAR; PG8_SCHED;
;             PG8_LDB(B0, 1, 0); PG8_LDB(B1, 1, 1); PG8_SCHED; PG8_LDA(At, 1, 0); PG8_STAGE(PG8_SA(0, 1), a2 + hstep, voffA);
;             PG8_WAIT_V(8); PG8_WAIT_L(0); PG8_BAR; PG8_MMA(0, 0, At, B0); PG8_MMA(0, 1, At, B1); PG8_BAR; PG8_SCHED;
;             PG8_LDA(At, 1, 1); PG8_STAGE(PG8_SB(1, 0), b3, voffB); PG8_STAGE(PG8_SB(1, 1), b3 + hstep, voffB); PG8_STAGE(PG8_SA(1, 0), a3, voffA);
;             PG8_WAIT_V(8); PG8_WAIT_L(0); PG8_BAR; PG8_MMA(1, 0, At, B0); PG8_MMA(1, 1, At, B1); PG8_BAR; PG8_SCHED;
	s_waitcnt lgkmcnt(0)
	v_mfma_f32_16x16x32_bf16 v[72:75], v[52:55], v[176:179], v[72:75]
	v_mfma_f32_16x16x32_bf16 v[64:67], v[76:79], v[176:179], v[64:67]
	v_mfma_f32_16x16x32_bf16 v[60:63], v[76:79], v[190:193], v[60:63]
	v_mfma_f32_16x16x32_bf16 v[68:71], v[52:55], v[190:193], v[68:71]
	v_mfma_f32_16x16x32_bf16 v[48:51], v[52:55], v[198:201], v[48:51]
	v_mfma_f32_16x16x32_bf16 v[44:47], v[76:79], v[198:201], v[44:47]
	v_mfma_f32_16x16x32_bf16 v[36:39], v[76:79], v[214:217], v[36:39]
	v_mfma_f32_16x16x32_bf16 v[40:43], v[52:55], v[214:217], v[40:43]
	v_mfma_f32_16x16x32_bf16 v[2:5], v[168:171], v[214:217], v[4:7]
	v_mfma_f32_16x16x32_bf16 v[24:27], v[168:171], v[176:179], v[24:27]
	v_mfma_f32_16x16x32_bf16 v[32:35], v[116:119], v[176:179], v[32:35]
	v_mfma_f32_16x16x32_bf16 v[28:31], v[116:119], v[190:193], v[28:31]
	v_mfma_f32_16x16x32_bf16 v[20:23], v[168:171], v[190:193], v[20:23]
	v_mfma_f32_16x16x32_bf16 v[12:15], v[168:171], v[198:201], v[12:15]
	v_mfma_f32_16x16x32_bf16 v[16:19], v[116:119], v[198:201], v[16:19]
	v_mfma_f32_16x16x32_bf16 v[8:11], v[116:119], v[214:217], v[8:11]
	v_mfma_f32_16x16x32_bf16 v[72:75], v[56:59], v[180:183], v[72:75]
	v_mfma_f32_16x16x32_bf16 v[64:67], v[80:83], v[180:183], v[64:67]
	v_mfma_f32_16x16x32_bf16 v[60:63], v[80:83], v[194:197], v[60:63]
	v_mfma_f32_16x16x32_bf16 v[68:71], v[56:59], v[194:197], v[68:71]
	v_mfma_f32_16x16x32_bf16 v[48:51], v[56:59], v[210:213], v[48:51]
	v_mfma_f32_16x16x32_bf16 v[44:47], v[80:83], v[210:213], v[44:47]
	v_mfma_f32_16x16x32_bf16 v[36:39], v[80:83], v[218:221], v[36:39]
	v_mfma_f32_16x16x32_bf16 v[40:43], v[56:59], v[218:221], v[40:43]
	v_mfma_f32_16x16x32_bf16 v[2:5], v[172:175], v[218:221], v[2:5]
	v_mfma_f32_16x16x32_bf16 v[24:27], v[172:175], v[180:183], v[24:27]
	v_mfma_f32_16x16x32_bf16 v[32:35], v[120:123], v[180:183], v[32:35]
	v_mfma_f32_16x16x32_bf16 v[28:31], v[120:123], v[194:197], v[28:31]
	v_mfma_f32_16x16x32_bf16 v[20:23], v[172:175], v[194:197], v[20:23]
	v_mfma_f32_16x16x32_bf16 v[12:15], v[172:175], v[210:213], v[12:15]
	v_mfma_f32_16x16x32_bf16 v[16:19], v[120:123], v[210:213], v[16:19]
	v_mfma_f32_16x16x32_bf16 v[8:11], v[120:123], v[218:221], v[8:11]
	s_barrier
	s_add_i32 s10, 0, 0x18000
	v_add_u32_e32 v0, s10, v188
	s_add_i32 s11, 0, 0x1c000
	ds_read_b128 v[52:55], v0
	ds_read_b128 v[56:59], v0 offset:1024
	ds_read_b128 v[76:79], v0 offset:2048
	ds_read_b128 v[80:83], v0 offset:3072
	v_add_u32_e32 v0, s11, v188
	ds_read_b128 v[116:119], v0
	ds_read_b128 v[120:123], v0 offset:1024
	ds_read_b128 v[168:171], v0 offset:2048
	ds_read_b128 v[172:175], v0 offset:3072
	s_add_u32 s8, vcc_lo, 0x80000
	s_addc_u32 s9, vcc_hi, 0
	s_mov_b32 m0, s13
	v_lshl_add_u64 v[6:7], s[8:9], 0, v[156:157]
	ds_read_b128 v[176:179], v189 offset:32768
	ds_read_b128 v[180:183], v189 offset:33792
	ds_read_b128 v[190:193], v189 offset:34816
	ds_read_b128 v[194:197], v189 offset:35840
	ds_read_b128 v[198:201], v189 offset:36864
	ds_read_b128 v[210:213], v189 offset:37888
	ds_read_b128 v[214:217], v189 offset:38912
	ds_read_b128 v[218:221], v189 offset:39936
	global_load_lds_dwordx4 v[6:7], off
	v_lshl_add_u64 v[6:7], s[8:9], 0, v[160:161]
	s_mov_b32 m0, s66
	s_nop 0
	global_load_lds_dwordx4 v[6:7], off
	s_waitcnt vmcnt(8)
	s_waitcnt lgkmcnt(0)
	s_barrier
	s_waitcnt lgkmcnt(0)
	v_mfma_f32_16x16x32_bf16 v[152:155], v[52:55], v[176:179], v[152:155]
	v_mfma_f32_16x16x32_bf16 v[144:147], v[76:79], v[176:179], v[144:147]
	v_mfma_f32_16x16x32_bf16 v[140:143], v[76:79], v[190:193], v[140:143]
	v_mfma_f32_16x16x32_bf16 v[148:151], v[52:55], v[190:193], v[148:151]
	v_mfma_f32_16x16x32_bf16 v[136:139], v[52:55], v[198:201], v[136:139]
	v_mfma_f32_16x16x32_bf16 v[132:135], v[76:79], v[198:201], v[132:135]
	v_mfma_f32_16x16x32_bf16 v[124:127], v[76:79], v[214:217], v[124:127]
	v_mfma_f32_16x16x32_bf16 v[128:131], v[52:55], v[214:217], v[128:131]
	v_mfma_f32_16x16x32_bf16 v[84:87], v[168:171], v[214:217], v[84:87]
	v_mfma_f32_16x16x32_bf16 v[104:107], v[168:171], v[176:179], v[104:107]
	v_mfma_f32_16x16x32_bf16 v[112:115], v[116:119], v[176:179], v[112:115]
	v_mfma_f32_16x16x32_bf16 v[108:111], v[116:119], v[190:193], v[108:111]
	v_mfma_f32_16x16x32_bf16 v[100:103], v[168:171], v[190:193], v[100:103]
	v_mfma_f32_16x16x32_bf16 v[92:95], v[168:171], v[198:201], v[92:95]
	v_mfma_f32_16x16x32_bf16 v[96:99], v[116:119], v[198:201], v[96:99]
	v_mfma_f32_16x16x32_bf16 v[88:91], v[116:119], v[214:217], v[88:91]
	v_mfma_f32_16x16x32_bf16 v[152:155], v[56:59], v[180:183], v[152:155]
	v_mfma_f32_16x16x32_bf16 v[144:147], v[80:83], v[180:183], v[144:147]
	v_mfma_f32_16x16x32_bf16 v[140:143], v[80:83], v[194:197], v[140:143]
	v_mfma_f32_16x16x32_bf16 v[148:151], v[56:59], v[194:197], v[148:151]
	v_mfma_f32_16x16x32_bf16 v[136:139], v[56:59], v[210:213], v[136:139]
	v_mfma_f32_16x16x32_bf16 v[132:135], v[80:83], v[210:213], v[132:135]
	v_mfma_f32_16x16x32_bf16 v[124:127], v[80:83], v[218:221], v[124:127]
	v_mfma_f32_16x16x32_bf16 v[128:131], v[56:59], v[218:221], v[128:131]
	v_mfma_f32_16x16x32_bf16 v[84:87], v[172:175], v[218:221], v[84:87]
	v_mfma_f32_16x16x32_bf16 v[104:107], v[172:175], v[180:183], v[104:107]
	v_mfma_f32_16x16x32_bf16 v[112:115], v[120:123], v[180:183], v[112:115]
	v_mfma_f32_16x16x32_bf16 v[108:111], v[120:123], v[194:197], v[108:111]
	v_mfma_f32_16x16x32_bf16 v[100:103], v[172:175], v[194:197], v[100:103]
	v_mfma_f32_16x16x32_bf16 v[92:95], v[172:175], v[210:213], v[92:95]
	v_mfma_f32_16x16x32_bf16 v[96:99], v[120:123], v[210:213], v[96:99]
	v_mfma_f32_16x16x32_bf16 v[88:91], v[120:123], v[218:221], v[88:91]
	s_barrier
; #define PG8_STAGE(bufoff, gbase, voff) do { _Pragma("unroll") for (int _i = 0; _i < 2; ++_i) \
;         __builtin_amdgcn_global_load_lds((const unsigned*)((const char*)(gbase) + (voff)[_i]), (PG8_LAS unsigned*)(lds + (bufoff) + ldsw + _i * 8192), 16, 0, 0); } while (0)
; #define PG8_LDA(dst, b, h) do { _Pragma("unroll") for (int m = 0; m < 4; ++m) _Pragma("unroll") for (int k = 0; k < 2; ++k) dst[m][k] = *(const PG8_LAS bf16x8*)(lds + PG8_SA(b, h) + aoff + m * 2048 + k * 1024); } while (0)
; #define PG8_MMA(ai, bj, At, Bt) do { __builtin_amdgcn_s_setprio(1); _Pragma("unroll") for (int m = 0; m < 4; ++m) _Pragma("unroll") for (int n = 0; n < 2; ++n) _Pragma("unroll") for (int k = 0; k < 2; ++k) \
;         acc[ai][bj][m][n] = mma16<Epi::I8>(Bt[n][k], At[m][k], acc[ai][bj][m][n]); __builtin_amdgcn_s_setprio(0); } while (0)
; #define PG8_WAIT_V(n) asm volatile("s_waitcnt vmcnt(" #n ")" ::: "memory")
; #define PG8_WAIT_L(n) asm volatile("s_waitcnt lgkmcnt(" #n ")" ::: "memory")
; #define PG8_BAR __builtin_amdgcn_s_barrier()
; #define PG8_SCHED __builtin_amdgcn_sched_barrier(0)
; template <class Epi, class Sched, bool ALIGN_EPI = false, bool SP2 = false>
; __device__ __forceinline__ void gemm_phase(PG8_LAS unsigned char* lds, const Gemm g, const Sched& S, const Epi& E) {
;     ...
;             PG8_LDA(At, 1, 1); PG8_STAGE(PG8_SB(1, 0), b3, voffB); PG8_STAGE(PG8_SB(1, 1), b3 + hstep, voffB); PG8_STAGE(PG8_SA(1, 0), a3, voffA);
;             PG8_WAIT_V(8); PG8_WAIT_L(0); PG8_BAR; PG8_MMA(1, 0, At, B0); PG8_MMA(1, 1, At, B1); PG8_BAR; PG8_SCHED;
	s_add_i32 s8, s10, s80
	v_lshl_add_u64 v[6:7], v[184:185], 0, s[92:93]
	s_mov_b32 m0, s8
	ds_read_b128 v[176:179], v189 offset:49152
	ds_read_b128 v[180:183], v189 offset:50176
	ds_read_b128 v[190:193], v189 offset:51200
	ds_read_b128 v[194:197], v189 offset:52224
	ds_read_b128 v[198:201], v189 offset:53248
	ds_read_b128 v[210:213], v189 offset:54272
	ds_read_b128 v[214:217], v189 offset:55296
	ds_read_b128 v[218:221], v189 offset:56320
	global_load_lds_dwordx4 v[6:7], off
	s_add_i32 m0, s8, 0x2000
	s_add_u32 s8, s70, 0x80080
	v_lshl_add_u64 v[6:7], v[206:207], 0, s[92:93]
	s_addc_u32 s9, s71, 0
	s_add_i32 s10, s11, s80
	global_load_lds_dwordx4 v[6:7], off
	v_lshl_add_u64 v[6:7], s[8:9], 0, v[158:159]
	s_mov_b32 m0, s10
	s_nop 0
	global_load_lds_dwordx4 v[6:7], off
	v_lshl_add_u64 v[6:7], s[8:9], 0, v[162:163]
	s_add_i32 m0, s10, 0x2000
	s_nop 0
	global_load_lds_dwordx4 v[6:7], off
	v_lshl_add_u64 v[6:7], v[222:223], 0, s[92:93]
	s_mov_b32 m0, s67
	s_nop 0
	global_load_lds_dwordx4 v[6:7], off
	v_lshl_add_u64 v[6:7], v[224:225], 0, s[92:93]
	s_mov_b32 m0, s81
	s_nop 0
	global_load_lds_dwordx4 v[6:7], off
	s_waitcnt vmcnt(8)
	s_waitcnt lgkmcnt(0)
	s_barrier
	s_waitcnt lgkmcnt(0)
	v_mfma_f32_16x16x32_bf16 v[72:75], v[52:55], v[176:179], v[72:75]
	v_mfma_f32_16x16x32_bf16 v[64:67], v[76:79], v[176:179], v[64:67]
	v_mfma_f32_16x16x32_bf16 v[60:63], v[76:79], v[190:193], v[60:63]
	v_mfma_f32_16x16x32_bf16 v[68:71], v[52:55], v[190:193], v[68:71]
	v_mfma_f32_16x16x32_bf16 v[48:51], v[52:55], v[198:201], v[48:51]
	v_mfma_f32_16x16x32_bf16 v[44:47], v[76:79], v[198:201], v[44:47]
	v_mfma_f32_16x16x32_bf16 v[36:39], v[76:79], v[214:217], v[36:39]
	v_mfma_f32_16x16x32_bf16 v[40:43], v[52:55], v[214:217], v[40:43]
	v_mfma_f32_16x16x32_bf16 v[2:5], v[168:171], v[214:217], v[2:5]
	v_mfma_f32_16x16x32_bf16 v[24:27], v[168:171], v[176:179], v[24:27]
	v_mfma_f32_16x16x32_bf16 v[32:35], v[116:119], v[176:179], v[32:35]
	v_mfma_f32_16x16x32_bf16 v[28:31], v[116:119], v[190:193], v[28:31]
	v_mfma_f32_16x16x32_bf16 v[20:23], v[168:171], v[190:193], v[20:23]
	v_mfma_f32_16x16x32_bf16 v[12:15], v[168:171], v[198:201], v[12:15]
	v_mfma_f32_16x16x32_bf16 v[16:19], v[116:119], v[198:201], v[16:19]
	v_mfma_f32_16x16x32_bf16 v[6:9], v[116:119], v[214:217], v[8:11]
	v_mfma_f32_16x16x32_bf16 v[72:75], v[56:59], v[180:183], v[72:75]
	v_mfma_f32_16x16x32_bf16 v[64:67], v[80:83], v[180:183], v[64:67]
	v_mfma_f32_16x16x32_bf16 v[60:63], v[80:83], v[194:197], v[60:63]
	v_mfma_f32_16x16x32_bf16 v[68:71], v[56:59], v[194:197], v[68:71]
	v_mfma_f32_16x16x32_bf16 v[48:51], v[56:59], v[210:213], v[48:51]
	v_mfma_f32_16x16x32_bf16 v[44:47], v[80:83], v[210:213], v[44:47]
	v_mfma_f32_16x16x32_bf16 v[36:39], v[80:83], v[218:221], v[36:39]
	v_mfma_f32_16x16x32_bf16 v[40:43], v[56:59], v[218:221], v[40:43]
	v_mfma_f32_16x16x32_bf16 v[8:11], v[120:123], v[218:221], v[6:9]
	v_mfma_f32_16x16x32_bf16 v[32:35], v[120:123], v[180:183], v[32:35]
	v_mfma_f32_16x16x32_bf16 v[24:27], v[172:175], v[180:183], v[24:27]
	v_mfma_f32_16x16x32_bf16 v[20:23], v[172:175], v[194:197], v[20:23]
	v_mfma_f32_16x16x32_bf16 v[28:31], v[120:123], v[194:197], v[28:31]
	v_mfma_f32_16x16x32_bf16 v[16:19], v[120:123], v[210:213], v[16:19]
	v_mfma_f32_16x16x32_bf16 v[12:15], v[172:175], v[210:213], v[12:15]
	v_mfma_f32_16x16x32_bf16 v[4:7], v[172:175], v[218:221], v[2:5]
	s_barrier
	s_add_i32 s4, s4, 2
	s_add_u32 s97, s97, 0x100
	s_addc_u32 s96, s96, 0
	s_cmp_gt_u32 s4, 29
	s_mov_b64 s[8:9], s[68:69]
	s_cbranch_scc0 .LBB0_327

; #define PG8_STAGE(bufoff, gbase, voff) do { _Pragma("unroll") for (int _i = 0; _i < 2; ++_i) \
;         __builtin_amdgcn_global_load_lds((const unsigned*)((const char*)(gbase) + (voff)[_i]), (PG8_LAS unsigned*)(lds + (bufoff) + ldsw + _i * 8192), 16, 0, 0); } while (0)
; #define PG8_LDA(dst, b, h) do { _Pragma("unroll") for (int m = 0; m < 4; ++m) _Pragma("unroll") for (int k = 0; k < 2; ++k) dst[m][k] = *(const PG8_LAS bf16x8*)(lds + PG8_SA(b, h) + aoff + m * 2048 + k * 1024); } while (0)
; #define PG8_LDB(dst, b, h) do { _Pragma("unroll") for (int n = 0; n < 2; ++n) _Pragma("unroll") for (int k = 0; k < 2; ++k) dst[n][k] = *(const PG8_LAS bf16x8*)(lds + PG8_SB(b, h) + boff + n * 2048 + k * 1024); } while (0)
; #define PG8_MMA(ai, bj, At, Bt) do { __builtin_amdgcn_s_setprio(1); _Pragma("unroll") for (int m = 0; m < 4; ++m) _Pragma("unroll") for (int n = 0; n < 2; ++n) _Pragma("unroll") for (int k = 0; k < 2; ++k) \
;         acc[ai][bj][m][n] = mma16<Epi::I8>(Bt[n][k], At[m][k], acc[ai][bj][m][n]); __builtin_amdgcn_s_setprio(0); } while (0)
; #define PG8_WAIT_V(n) asm volatile("s_waitcnt vmcnt(" #n ")" ::: "memory")
; #define PG8_WAIT_L(n) asm volatile("s_waitcnt lgkmcnt(" #n ")" ::: "memory")
; #define PG8_BAR __builtin_amdgcn_s_barrier()
; template <class Epi, class Sched, bool ALIGN_EPI = false, bool SP2 = false>
; __device__ __forceinline__ void gemm_phase(PG8_LAS unsigned char* lds, const Gemm g, const Sched& S, const Epi& E) {
;     ...
;             const bool last = (t == nt - 2);
;             const char* a1 = cA + (size_t)(t + 1) * kstep;
;             const char* a2 = last ? nA : cA + (size_t)(t + 2) * kstep; const char* b2 = last ? nB : cB + (size_t)(t + 2) * kstep;
;             const char* a3 = a2 + kstep; const char* b3 = b2 + kstep;
;             if (last && has_next) S.a_ready(nxt);
;             if constexpr (SP2) {
;             PG8_LDB(B0, 0, 0); PG8_LDB(B1, 0, 1); PG8_SCHED; PG8_LDA(At, 0, 0); PG8_STAGE(PG8_SA(1, 1), a1 + hstep, voffA);
;             PG8_WAIT_V(8); PG8_WAIT_L(0); PG8_BAR; PG8_MMA(0, 0, At, B0); PG8_MMA(0, 1, At, B1); PG8_BAR; PG8_SCHED;
;             PG8_LDA(At, 0, 1); PG8_STAGE(PG8_SB(0, 0), b2, voffB); PG8_STAGE(PG8_SB(0, 1), b2 + hstep, voffB); PG8_STAGE(PG8_SA(0, 0), a2, voffA);
;             PG8_WAIT_V(8); PG8_WAIT_L(0); PG8_BAR; PG8_MMA(1, 0, At, B0); PG8_MMA(1, 1, At, B1); PG8_BAR; PG8_SCHED;
.Lpeel385:
	s_add_u32 s70, s8, 0x100
	s_addc_u32 s71, s9, 0
	s_add_i32 s84, 0, 0x10000
	s_cmp_eq_u32 s5, 12
	s_cselect_b32 vcc_hi, s1, s71
	s_cselect_b32 vcc_lo, s7, s70
	v_add_u32_e32 v0, s84, v214
	s_cselect_b32 s83, s69, s68
	s_cselect_b32 s82, s81, s85
	s_add_i32 s10, 0, 0x14000
	ds_read_b128 v[44:47], v0
	ds_read_b128 v[52:55], v0 offset:1024
	ds_read_b128 v[60:63], v0 offset:2048
	ds_read_b128 v[64:67], v0 offset:3072
	v_add_u32_e32 v0, s10, v214
	ds_read_b128 v[84:87], v0
	ds_read_b128 v[88:91], v0 offset:1024
	ds_read_b128 v[92:95], v0 offset:2048
	ds_read_b128 v[100:103], v0 offset:3072
	v_lshl_add_u64 v[2:3], s[8:9], 0, v[184:185]
	s_add_i32 m0, s13, 0xc000
	ds_read_b128 v[124:127], v215
	ds_read_b128 v[128:131], v215 offset:1024
	ds_read_b128 v[140:143], v215 offset:2048
	ds_read_b128 v[188:191], v215 offset:3072
	ds_read_b128 v[192:195], v215 offset:4096
	ds_read_b128 v[196:199], v215 offset:5120
	ds_read_b128 v[216:219], v215 offset:6144
	ds_read_b128 v[220:223], v215 offset:7168
	global_load_lds_dwordx4 v[2:3], off
	v_lshl_add_u64 v[2:3], s[8:9], 0, v[186:187]
	s_add_i32 m0, s13, 0xe000
	s_nop 0
	global_load_lds_dwordx4 v[2:3], off
	s_waitcnt vmcnt(8)
	s_waitcnt lgkmcnt(0)
	s_barrier
	s_waitcnt lgkmcnt(0)
	v_mfma_i32_16x16x64_i8 v[172:175], v[44:47], v[124:127], 0
	v_mfma_i32_16x16x64_i8 v[164:167], v[60:63], v[124:127], 0
	v_mfma_i32_16x16x64_i8 v[160:163], v[60:63], v[140:143], 0
	v_mfma_i32_16x16x64_i8 v[168:171], v[44:47], v[140:143], 0
	v_mfma_i32_16x16x64_i8 v[156:159], v[44:47], v[192:195], 0
	v_mfma_i32_16x16x64_i8 v[152:155], v[60:63], v[192:195], 0
	v_mfma_i32_16x16x64_i8 v[144:147], v[60:63], v[216:219], 0
	v_mfma_i32_16x16x64_i8 v[148:151], v[44:47], v[216:219], 0
	v_mfma_i32_16x16x64_i8 v[104:107], v[84:87], v[216:219], 0
	v_mfma_i32_16x16x64_i8 v[136:139], v[84:87], v[124:127], 0
	v_mfma_i32_16x16x64_i8 v[120:123], v[92:95], v[124:127], 0
	v_mfma_i32_16x16x64_i8 v[116:119], v[92:95], v[140:143], 0
	v_mfma_i32_16x16x64_i8 v[108:111], v[92:95], v[192:195], 0
	v_mfma_i32_16x16x64_i8 v[112:115], v[84:87], v[192:195], 0
	v_mfma_i32_16x16x64_i8 v[124:127], v[84:87], v[140:143], 0
	v_mfma_i32_16x16x64_i8 v[172:175], v[52:55], v[128:131], v[172:175]
	v_mfma_i32_16x16x64_i8 v[164:167], v[64:67], v[128:131], v[164:167]
	v_mfma_i32_16x16x64_i8 v[160:163], v[64:67], v[188:191], v[160:163]
	v_mfma_i32_16x16x64_i8 v[168:171], v[52:55], v[188:191], v[168:171]
	v_mfma_i32_16x16x64_i8 v[156:159], v[52:55], v[196:199], v[156:159]
	v_mfma_i32_16x16x64_i8 v[152:155], v[64:67], v[196:199], v[152:155]
	v_mfma_i32_16x16x64_i8 v[144:147], v[64:67], v[220:223], v[144:147]
	v_mfma_i32_16x16x64_i8 v[148:151], v[52:55], v[220:223], v[148:151]
	v_mfma_i32_16x16x64_i8 v[104:107], v[88:91], v[220:223], v[104:107]
	v_mfma_i32_16x16x64_i8 v[136:139], v[88:91], v[128:131], v[136:139]
	v_mfma_i32_16x16x64_i8 v[120:123], v[100:103], v[128:131], v[120:123]
	v_mfma_i32_16x16x64_i8 v[116:119], v[100:103], v[188:191], v[116:119]
	v_mfma_i32_16x16x64_i8 v[108:111], v[100:103], v[196:199], v[108:111]
	v_mfma_i32_16x16x64_i8 v[112:115], v[88:91], v[196:199], v[112:115]
	v_mfma_i32_16x16x64_i8 v[124:127], v[88:91], v[188:191], v[124:127]
	v_mfma_i32_16x16x64_i8 v[96:99], v[92:95], v[216:219], 0
	v_mfma_i32_16x16x64_i8 v[96:99], v[100:103], v[220:223], v[96:99]
	s_barrier
	s_add_i32 s8, s84, s12
	v_lshl_add_u64 v[200:201], s[82:83], 0, v[178:179]
	s_mov_b32 m0, s8
	ds_read_b128 v[128:131], v215 offset:16384
	ds_read_b128 v[132:135], v215 offset:17408
	ds_read_b128 v[140:143], v215 offset:18432
	ds_read_b128 v[188:191], v215 offset:19456
	ds_read_b128 v[192:195], v215 offset:20480
	ds_read_b128 v[196:199], v215 offset:21504
	ds_read_b128 v[216:219], v215 offset:22528
	ds_read_b128 v[220:223], v215 offset:23552
	global_load_lds_dwordx4 v[200:201], off
	s_add_i32 m0, s8, 0x2000
	s_add_u32 s8, s82, 0x40000
	v_lshl_add_u64 v[206:207], s[82:83], 0, v[182:183]
	s_addc_u32 s9, s83, 0
	s_add_i32 s10, s10, s12
	global_load_lds_dwordx4 v[206:207], off
	v_lshl_add_u64 v[2:3], s[8:9], 0, v[178:179]
	s_mov_b32 m0, s10
	v_lshl_add_u64 v[210:211], vcc, 0, v[176:177]
	global_load_lds_dwordx4 v[2:3], off
	v_lshl_add_u64 v[2:3], s[8:9], 0, v[182:183]
	s_add_i32 m0, s10, 0x2000
	v_lshl_add_u64 v[224:225], vcc, 0, v[180:181]
	global_load_lds_dwordx4 v[2:3], off
	s_mov_b32 m0, s13
	s_nop 0
	global_load_lds_dwordx4 v[210:211], off
	s_mov_b32 m0, s66
	s_nop 0
	global_load_lds_dwordx4 v[224:225], off
	s_waitcnt vmcnt(8)
	s_waitcnt lgkmcnt(0)
	s_barrier
	s_waitcnt lgkmcnt(0)
	v_mfma_i32_16x16x64_i8 v[80:83], v[44:47], v[128:131], 0
	v_mfma_i32_16x16x64_i8 v[72:75], v[60:63], v[128:131], 0
	v_mfma_i32_16x16x64_i8 v[68:71], v[60:63], v[140:143], 0
	v_mfma_i32_16x16x64_i8 v[76:79], v[44:47], v[140:143], 0
	v_mfma_i32_16x16x64_i8 v[56:59], v[44:47], v[192:195], 0
	v_mfma_i32_16x16x64_i8 v[48:51], v[60:63], v[192:195], 0
	v_mfma_i32_16x16x64_i8 v[36:39], v[60:63], v[216:219], 0
	v_mfma_i32_16x16x64_i8 v[40:43], v[44:47], v[216:219], 0
	v_mfma_i32_16x16x64_i8 v[2:5], v[92:95], v[216:219], 0
	v_mfma_i32_16x16x64_i8 v[24:27], v[92:95], v[128:131], 0
	v_mfma_i32_16x16x64_i8 v[32:35], v[84:87], v[128:131], 0
	v_mfma_i32_16x16x64_i8 v[28:31], v[84:87], v[140:143], 0
	v_mfma_i32_16x16x64_i8 v[20:23], v[92:95], v[140:143], 0
	v_mfma_i32_16x16x64_i8 v[12:15], v[92:95], v[192:195], 0
	v_mfma_i32_16x16x64_i8 v[16:19], v[84:87], v[192:195], 0
	v_mfma_i32_16x16x64_i8 v[8:11], v[84:87], v[216:219], 0
	v_mfma_i32_16x16x64_i8 v[80:83], v[52:55], v[132:135], v[80:83]
	v_mfma_i32_16x16x64_i8 v[72:75], v[64:67], v[132:135], v[72:75]
	v_mfma_i32_16x16x64_i8 v[68:71], v[64:67], v[188:191], v[68:71]
	v_mfma_i32_16x16x64_i8 v[76:79], v[52:55], v[188:191], v[76:79]
	v_mfma_i32_16x16x64_i8 v[56:59], v[52:55], v[196:199], v[56:59]
	v_mfma_i32_16x16x64_i8 v[48:51], v[64:67], v[196:199], v[48:51]
	v_mfma_i32_16x16x64_i8 v[36:39], v[64:67], v[220:223], v[36:39]
	v_mfma_i32_16x16x64_i8 v[40:43], v[52:55], v[220:223], v[40:43]
	v_mfma_i32_16x16x64_i8 v[2:5], v[100:103], v[220:223], v[2:5]
	v_mfma_i32_16x16x64_i8 v[24:27], v[100:103], v[132:135], v[24:27]
	v_mfma_i32_16x16x64_i8 v[32:35], v[88:91], v[132:135], v[32:35]
	v_mfma_i32_16x16x64_i8 v[28:31], v[88:91], v[188:191], v[28:31]
	v_mfma_i32_16x16x64_i8 v[20:23], v[100:103], v[188:191], v[20:23]
	v_mfma_i32_16x16x64_i8 v[12:15], v[100:103], v[196:199], v[12:15]
	v_mfma_i32_16x16x64_i8 v[16:19], v[88:91], v[196:199], v[16:19]
	v_mfma_i32_16x16x64_i8 v[8:11], v[88:91], v[220:223], v[8:11]
	s_barrier
; #define PG8_STAGE(bufoff, gbase, voff) do { _Pragma("unroll") for (int _i = 0; _i < 2; ++_i) \
;         __builtin_amdgcn_global_load_lds((const unsigned*)((const char*)(gbase) + (voff)[_i]), (PG8_LAS unsigned*)(lds + (bufoff) + ldsw + _i * 8192), 16, 0, 0); } while (0)
; #define PG8_LDA(dst, b, h) do { _Pragma("unroll") for (int m = 0; m < 4; ++m) _Pragma("unroll") for (int k = 0; k < 2; ++k) dst[m][k] = *(const PG8_LAS bf16x8*)(lds + PG8_SA(b, h) + aoff + m * 2048 + k * 1024); } while (0)
; #define PG8_LDB(dst, b, h) do { _Pragma("unroll") for (int n = 0; n < 2; ++n) _Pragma("unroll") for (int k = 0; k < 2; ++k) dst[n][k] = *(const PG8_LAS bf16x8*)(lds + PG8_SB(b, h) + boff + n * 2048 + k * 1024); } while (0)
; #define PG8_MMA(ai, bj, At, Bt) do { __builtin_amdgcn_s_setprio(1); _Pragma("unroll") for (int m = 0; m < 4; ++m) _Pragma("unroll") for (int n = 0; n < 2; ++n) _Pragma("unroll") for (int k = 0; k < 2; ++k) \
;         acc[ai][bj][m][n] = mma16<Epi::I8>(Bt[n][k], At[m][k], acc[ai][bj][m][n]); __builtin_amdgcn_s_setprio(0); } while (0)
; #define PG8_WAIT_V(n) asm volatile("s_waitcnt vmcnt(" #n ")" ::: "memory")
; #define PG8_WAIT_L(n) asm volatile("s_waitcnt lgkmcnt(" #n ")" ::: "memory")
; #define PG8_BAR __builtin_amdgcn_s_barrier()
; #define PG8_SCHED __builtin_amdgcn_sched_barrier(0)
; template <class Epi, class Sched, bool ALIGN_EPI = false, bool SP2 = false>
; __device__ __forceinline__ void gemm_phase(PG8_LAS unsigned char* lds, const Gemm g, const Sched& S, const Epi& E) {
;     ...
;             PG8_LDB(B0, 1, 0); PG8_LDB(B1, 1, 1); PG8_SCHED; PG8_LDA(At, 1, 0); PG8_STAGE(PG8_SA(0, 1), a2 + hstep, voffA);
;             PG8_WAIT_V(8); PG8_WAIT_L(0); PG8_BAR; PG8_MMA(0, 0, At, B0); PG8_MMA(0, 1, At, B1); PG8_BAR; PG8_SCHED;
;             PG8_LDA(At, 1, 1); PG8_STAGE(PG8_SB(1, 0), b3, voffB); PG8_STAGE(PG8_SB(1, 1), b3 + hstep, voffB); PG8_STAGE(PG8_SA(1, 0), a3, voffA);
;             PG8_WAIT_V(8); PG8_WAIT_L(0); PG8_BAR; PG8_MMA(1, 0, At, B0); PG8_MMA(1, 1, At, B1); PG8_BAR; PG8_SCHED;
	s_add_i32 s10, 0, 0x18000
	v_add_u32_e32 v0, s10, v214
	s_add_i32 s11, 0, 0x1c000
	ds_read_b128 v[44:47], v0
	ds_read_b128 v[52:55], v0 offset:1024
	ds_read_b128 v[60:63], v0 offset:2048
	ds_read_b128 v[64:67], v0 offset:3072
	v_add_u32_e32 v0, s11, v214
	ds_read_b128 v[84:87], v0
	ds_read_b128 v[88:91], v0 offset:1024
	ds_read_b128 v[92:95], v0 offset:2048
	ds_read_b128 v[100:103], v0 offset:3072
	s_add_u32 s8, vcc_lo, 0x40000
	s_addc_u32 s9, vcc_hi, 0
	s_mov_b32 m0, s67
	v_lshl_add_u64 v[6:7], s[8:9], 0, v[176:177]
	ds_read_b128 v[128:131], v215 offset:32768
	ds_read_b128 v[132:135], v215 offset:33792
	ds_read_b128 v[140:143], v215 offset:34816
	ds_read_b128 v[188:191], v215 offset:35840
	ds_read_b128 v[192:195], v215 offset:36864
	ds_read_b128 v[196:199], v215 offset:37888
	ds_read_b128 v[216:219], v215 offset:38912
	ds_read_b128 v[220:223], v215 offset:39936
	global_load_lds_dwordx4 v[6:7], off
	v_lshl_add_u64 v[6:7], s[8:9], 0, v[180:181]
	s_mov_b32 m0, s80
	s_nop 0
	global_load_lds_dwordx4 v[6:7], off
	s_waitcnt vmcnt(8)
	s_waitcnt lgkmcnt(0)
	s_barrier
	s_waitcnt lgkmcnt(0)
	v_mfma_i32_16x16x64_i8 v[172:175], v[44:47], v[128:131], v[172:175]
	v_mfma_i32_16x16x64_i8 v[164:167], v[60:63], v[128:131], v[164:167]
	v_mfma_i32_16x16x64_i8 v[160:163], v[60:63], v[140:143], v[160:163]
	v_mfma_i32_16x16x64_i8 v[168:171], v[44:47], v[140:143], v[168:171]
	v_mfma_i32_16x16x64_i8 v[156:159], v[44:47], v[192:195], v[156:159]
	v_mfma_i32_16x16x64_i8 v[152:155], v[60:63], v[192:195], v[152:155]
	v_mfma_i32_16x16x64_i8 v[144:147], v[60:63], v[216:219], v[144:147]
	v_mfma_i32_16x16x64_i8 v[148:151], v[44:47], v[216:219], v[148:151]
	v_mfma_i32_16x16x64_i8 v[96:99], v[92:95], v[216:219], v[96:99]
	v_mfma_i32_16x16x64_i8 v[120:123], v[92:95], v[128:131], v[120:123]
	v_mfma_i32_16x16x64_i8 v[136:139], v[84:87], v[128:131], v[136:139]
	v_mfma_i32_16x16x64_i8 v[124:127], v[84:87], v[140:143], v[124:127]
	v_mfma_i32_16x16x64_i8 v[116:119], v[92:95], v[140:143], v[116:119]
	v_mfma_i32_16x16x64_i8 v[108:111], v[92:95], v[192:195], v[108:111]
	v_mfma_i32_16x16x64_i8 v[112:115], v[84:87], v[192:195], v[112:115]
	v_mfma_i32_16x16x64_i8 v[104:107], v[84:87], v[216:219], v[104:107]
	v_mfma_i32_16x16x64_i8 v[172:175], v[52:55], v[132:135], v[172:175]
	v_mfma_i32_16x16x64_i8 v[164:167], v[64:67], v[132:135], v[164:167]
	v_mfma_i32_16x16x64_i8 v[160:163], v[64:67], v[188:191], v[160:163]
	v_mfma_i32_16x16x64_i8 v[168:171], v[52:55], v[188:191], v[168:171]
	v_mfma_i32_16x16x64_i8 v[156:159], v[52:55], v[196:199], v[156:159]
	v_mfma_i32_16x16x64_i8 v[152:155], v[64:67], v[196:199], v[152:155]
	v_mfma_i32_16x16x64_i8 v[144:147], v[64:67], v[220:223], v[144:147]
	v_mfma_i32_16x16x64_i8 v[148:151], v[52:55], v[220:223], v[148:151]
	v_mfma_i32_16x16x64_i8 v[96:99], v[100:103], v[220:223], v[96:99]
	v_mfma_i32_16x16x64_i8 v[120:123], v[100:103], v[132:135], v[120:123]
	v_mfma_i32_16x16x64_i8 v[136:139], v[88:91], v[132:135], v[136:139]
	v_mfma_i32_16x16x64_i8 v[132:135], v[88:91], v[188:191], v[124:127]
	v_mfma_i32_16x16x64_i8 v[116:119], v[100:103], v[188:191], v[116:119]
	v_mfma_i32_16x16x64_i8 v[108:111], v[100:103], v[196:199], v[108:111]
	v_mfma_i32_16x16x64_i8 v[112:115], v[88:91], v[196:199], v[112:115]
	v_mfma_i32_16x16x64_i8 v[104:107], v[88:91], v[220:223], v[104:107]
	s_barrier
	s_add_i32 s8, s10, s12
	v_lshl_add_u64 v[6:7], v[200:201], 0, s[92:93]
	s_mov_b32 m0, s8
	ds_read_b128 v[124:127], v215 offset:49152
	ds_read_b128 v[128:131], v215 offset:50176
	ds_read_b128 v[140:143], v215 offset:51200
	ds_read_b128 v[188:191], v215 offset:52224
	ds_read_b128 v[192:195], v215 offset:53248
	ds_read_b128 v[196:199], v215 offset:54272
	ds_read_b128 v[216:219], v215 offset:55296
	ds_read_b128 v[220:223], v215 offset:56320
	global_load_lds_dwordx4 v[6:7], off
	s_add_i32 m0, s8, 0x2000
	s_add_u32 s8, s82, 0x40080
	v_lshl_add_u64 v[6:7], v[206:207], 0, s[92:93]
	s_addc_u32 s9, s83, 0
	s_add_i32 s10, s11, s12
	global_load_lds_dwordx4 v[6:7], off
	v_lshl_add_u64 v[6:7], s[8:9], 0, v[178:179]
	s_mov_b32 m0, s10
	s_nop 0
	global_load_lds_dwordx4 v[6:7], off
	v_lshl_add_u64 v[6:7], s[8:9], 0, v[182:183]
	s_add_i32 m0, s10, 0x2000
	s_nop 0
	global_load_lds_dwordx4 v[6:7], off
	v_lshl_add_u64 v[6:7], v[210:211], 0, s[92:93]
	s_mov_b32 m0, s58
	s_nop 0
	global_load_lds_dwordx4 v[6:7], off
	v_lshl_add_u64 v[6:7], v[224:225], 0, s[92:93]
	s_mov_b32 m0, s4
	s_nop 0
	global_load_lds_dwordx4 v[6:7], off
	s_waitcnt vmcnt(8)
	s_waitcnt lgkmcnt(0)
	s_barrier
	s_waitcnt lgkmcnt(0)
	v_mfma_i32_16x16x64_i8 v[80:83], v[44:47], v[124:127], v[80:83]
	v_mfma_i32_16x16x64_i8 v[72:75], v[60:63], v[124:127], v[72:75]
	v_mfma_i32_16x16x64_i8 v[68:71], v[60:63], v[140:143], v[68:71]
	v_mfma_i32_16x16x64_i8 v[76:79], v[44:47], v[140:143], v[76:79]
	v_mfma_i32_16x16x64_i8 v[56:59], v[44:47], v[192:195], v[56:59]
	v_mfma_i32_16x16x64_i8 v[48:51], v[60:63], v[192:195], v[48:51]
	v_mfma_i32_16x16x64_i8 v[36:39], v[60:63], v[216:219], v[36:39]
	v_mfma_i32_16x16x64_i8 v[40:43], v[44:47], v[216:219], v[40:43]
	v_mfma_i32_16x16x64_i8 v[2:5], v[92:95], v[216:219], v[2:5]
	v_mfma_i32_16x16x64_i8 v[24:27], v[92:95], v[124:127], v[24:27]
	v_mfma_i32_16x16x64_i8 v[32:35], v[84:87], v[124:127], v[32:35]
	v_mfma_i32_16x16x64_i8 v[28:31], v[84:87], v[140:143], v[28:31]
	v_mfma_i32_16x16x64_i8 v[20:23], v[92:95], v[140:143], v[20:23]
	v_mfma_i32_16x16x64_i8 v[12:15], v[92:95], v[192:195], v[12:15]
	v_mfma_i32_16x16x64_i8 v[16:19], v[84:87], v[192:195], v[16:19]
	v_mfma_i32_16x16x64_i8 v[6:9], v[84:87], v[216:219], v[8:11]
	v_mfma_i32_16x16x64_i8 v[80:83], v[52:55], v[128:131], v[80:83]
	v_mfma_i32_16x16x64_i8 v[72:75], v[64:67], v[128:131], v[72:75]
	v_mfma_i32_16x16x64_i8 v[68:71], v[64:67], v[188:191], v[68:71]
	v_mfma_i32_16x16x64_i8 v[76:79], v[52:55], v[188:191], v[76:79]
	v_mfma_i32_16x16x64_i8 v[56:59], v[52:55], v[196:199], v[56:59]
	v_mfma_i32_16x16x64_i8 v[48:51], v[64:67], v[196:199], v[48:51]
	v_mfma_i32_16x16x64_i8 v[36:39], v[64:67], v[220:223], v[36:39]
	v_mfma_i32_16x16x64_i8 v[40:43], v[52:55], v[220:223], v[40:43]
	v_mfma_i32_16x16x64_i8 v[8:11], v[88:91], v[220:223], v[6:9]
	v_mfma_i32_16x16x64_i8 v[32:35], v[88:91], v[128:131], v[32:35]
	v_mfma_i32_16x16x64_i8 v[24:27], v[100:103], v[128:131], v[24:27]
	v_mfma_i32_16x16x64_i8 v[20:23], v[100:103], v[188:191], v[20:23]
	v_mfma_i32_16x16x64_i8 v[28:31], v[88:91], v[188:191], v[28:31]
	v_mfma_i32_16x16x64_i8 v[16:19], v[88:91], v[196:199], v[16:19]
	v_mfma_i32_16x16x64_i8 v[12:15], v[100:103], v[196:199], v[12:15]
	v_mfma_i32_16x16x64_i8 v[4:7], v[100:103], v[220:223], v[2:5]
	s_barrier
	s_add_i32 s5, s5, 2
	s_add_u32 s85, s85, 0x100
	s_addc_u32 s68, s68, 0
	s_cmp_gt_u32 s5, 13
	s_mov_b64 s[8:9], s[70:71]
	s_cbranch_scc0 .LBB0_385
	s_branch .Lpeelx385
; #define PG8_STAGE(bufoff, gbase, voff) do { _Pragma("unroll") for (int _i = 0; _i < 2; ++_i) \
;         __builtin_amdgcn_global_load_lds((const unsigned*)((const char*)(gbase) + (voff)[_i]), (PG8_LAS unsigned*)(lds + (bufoff) + ldsw + _i * 8192), 16, 0, 0); } while (0)
; #define PG8_LDA(dst, b, h) do { _Pragma("unroll") for (int m = 0; m < 4; ++m) _Pragma("unroll") for (int k = 0; k < 2; ++k) dst[m][k] = *(const PG8_LAS bf16x8*)(lds + PG8_SA(b, h) + aoff + m * 2048 + k * 1024); } while (0)
; #define PG8_LDB(dst, b, h) do { _Pragma("unroll") for (int n = 0; n < 2; ++n) _Pragma("unroll") for (int k = 0; k < 2; ++k) dst[n][k] = *(const PG8_LAS bf16x8*)(lds + PG8_SB(b, h) + boff + n * 2048 + k * 1024); } while (0)
; #define PG8_MMA(ai, bj, At, Bt) do { __builtin_amdgcn_s_setprio(1); _Pragma("unroll") for (int m = 0; m < 4; ++m) _Pragma("unroll") for (int n = 0; n < 2; ++n) _Pragma("unroll") for (int k = 0; k < 2; ++k) \
;         acc[ai][bj][m][n] = mma16<Epi::I8>(Bt[n][k], At[m][k], acc[ai][bj][m][n]); __builtin_amdgcn_s_setprio(0); } while (0)
; #define PG8_WAIT_V(n) asm volatile("s_waitcnt vmcnt(" #n ")" ::: "memory")
; #define PG8_WAIT_L(n) asm volatile("s_waitcnt lgkmcnt(" #n ")" ::: "memory")
; #define PG8_BAR __builtin_amdgcn_s_barrier()
; template <class Epi, class Sched, bool ALIGN_EPI = false, bool SP2 = false>
; __device__ __forceinline__ void gemm_phase(PG8_LAS unsigned char* lds, const Gemm g, const Sched& S, const Epi& E) {
;     ...
;             const bool last = (t == nt - 2);
;             const char* a1 = cA + (size_t)(t + 1) * kstep;
;             const char* a2 = last ? nA : cA + (size_t)(t + 2) * kstep; const char* b2 = last ? nB : cB + (size_t)(t + 2) * kstep;
;             const char* a3 = a2 + kstep; const char* b3 = b2 + kstep;
;             if (last && has_next) S.a_ready(nxt);
;             if constexpr (SP2) {
;             PG8_LDB(B0, 0, 0); PG8_LDB(B1, 0, 1); PG8_SCHED; PG8_LDA(At, 0, 0); PG8_STAGE(PG8_SA(1, 1), a1 + hstep, voffA);
;             PG8_WAIT_V(8); PG8_WAIT_L(0); PG8_BAR; PG8_MMA(0, 0, At, B0); PG8_MMA(0, 1, At, B1); PG8_BAR; PG8_SCHED;
;             PG8_LDA(At, 0, 1); PG8_STAGE(PG8_SB(0, 0), b2, voffB); PG8_STAGE(PG8_SB(0, 1), b2 + hstep, voffB); PG8_STAGE(PG8_SA(0, 0), a2, voffA);
;             PG8_WAIT_V(8); PG8_WAIT_L(0); PG8_BAR; PG8_MMA(1, 0, At, B0); PG8_MMA(1, 1, At, B1); PG8_BAR; PG8_SCHED;
.LBB0_385:
	s_add_u32 s70, s8, 0x100
	s_addc_u32 s71, s9, 0
	s_add_i32 s84, 0, 0x10000
	s_cmp_eq_u32 s5, 12
	s_cselect_b32 vcc_hi, s1, s71
	s_cselect_b32 vcc_lo, s7, s70
	v_add_u32_e32 v0, s84, v214
	s_cselect_b32 s83, s69, s68
	s_cselect_b32 s82, s81, s85
	s_add_i32 s10, 0, 0x14000
	ds_read_b128 v[44:47], v0
	ds_read_b128 v[52:55], v0 offset:1024
	ds_read_b128 v[60:63], v0 offset:2048
	ds_read_b128 v[64:67], v0 offset:3072
	v_add_u32_e32 v0, s10, v214
	ds_read_b128 v[84:87], v0
	ds_read_b128 v[88:91], v0 offset:1024
	ds_read_b128 v[92:95], v0 offset:2048
	ds_read_b128 v[100:103], v0 offset:3072
	v_lshl_add_u64 v[2:3], s[8:9], 0, v[184:185]
	s_add_i32 m0, s13, 0xc000
	ds_read_b128 v[124:127], v215
	ds_read_b128 v[128:131], v215 offset:1024
	ds_read_b128 v[140:143], v215 offset:2048
	ds_read_b128 v[188:191], v215 offset:3072
	ds_read_b128 v[192:195], v215 offset:4096
	ds_read_b128 v[196:199], v215 offset:5120
	ds_read_b128 v[216:219], v215 offset:6144
	ds_read_b128 v[220:223], v215 offset:7168
	global_load_lds_dwordx4 v[2:3], off
	v_lshl_add_u64 v[2:3], s[8:9], 0, v[186:187]
	s_add_i32 m0, s13, 0xe000
	s_nop 0
	global_load_lds_dwordx4 v[2:3], off
	s_waitcnt vmcnt(8)
	s_waitcnt lgkmcnt(0)
	s_barrier
	s_waitcnt lgkmcnt(0)
	v_mfma_i32_16x16x64_i8 v[172:175], v[44:47], v[124:127], v[172:175]
	v_mfma_i32_16x16x64_i8 v[164:167], v[60:63], v[124:127], v[164:167]
	v_mfma_i32_16x16x64_i8 v[160:163], v[60:63], v[140:143], v[160:163]
	v_mfma_i32_16x16x64_i8 v[168:171], v[44:47], v[140:143], v[168:171]
	v_mfma_i32_16x16x64_i8 v[156:159], v[44:47], v[192:195], v[156:159]
	v_mfma_i32_16x16x64_i8 v[152:155], v[60:63], v[192:195], v[152:155]
	v_mfma_i32_16x16x64_i8 v[144:147], v[60:63], v[216:219], v[144:147]
	v_mfma_i32_16x16x64_i8 v[148:151], v[44:47], v[216:219], v[148:151]
	v_mfma_i32_16x16x64_i8 v[104:107], v[84:87], v[216:219], v[104:107]
	v_mfma_i32_16x16x64_i8 v[136:139], v[84:87], v[124:127], v[136:139]
	v_mfma_i32_16x16x64_i8 v[120:123], v[92:95], v[124:127], v[120:123]
	v_mfma_i32_16x16x64_i8 v[116:119], v[92:95], v[140:143], v[116:119]
	v_mfma_i32_16x16x64_i8 v[108:111], v[92:95], v[192:195], v[108:111]
	v_mfma_i32_16x16x64_i8 v[112:115], v[84:87], v[192:195], v[112:115]
	v_mfma_i32_16x16x64_i8 v[124:127], v[84:87], v[140:143], v[132:135]
	v_mfma_i32_16x16x64_i8 v[172:175], v[52:55], v[128:131], v[172:175]
	v_mfma_i32_16x16x64_i8 v[164:167], v[64:67], v[128:131], v[164:167]
	v_mfma_i32_16x16x64_i8 v[160:163], v[64:67], v[188:191], v[160:163]
	v_mfma_i32_16x16x64_i8 v[168:171], v[52:55], v[188:191], v[168:171]
	v_mfma_i32_16x16x64_i8 v[156:159], v[52:55], v[196:199], v[156:159]
	v_mfma_i32_16x16x64_i8 v[152:155], v[64:67], v[196:199], v[152:155]
	v_mfma_i32_16x16x64_i8 v[144:147], v[64:67], v[220:223], v[144:147]
	v_mfma_i32_16x16x64_i8 v[148:151], v[52:55], v[220:223], v[148:151]
	v_mfma_i32_16x16x64_i8 v[104:107], v[88:91], v[220:223], v[104:107]
	v_mfma_i32_16x16x64_i8 v[136:139], v[88:91], v[128:131], v[136:139]
	v_mfma_i32_16x16x64_i8 v[120:123], v[100:103], v[128:131], v[120:123]
	v_mfma_i32_16x16x64_i8 v[116:119], v[100:103], v[188:191], v[116:119]
	v_mfma_i32_16x16x64_i8 v[108:111], v[100:103], v[196:199], v[108:111]
	v_mfma_i32_16x16x64_i8 v[112:115], v[88:91], v[196:199], v[112:115]
	v_mfma_i32_16x16x64_i8 v[124:127], v[88:91], v[188:191], v[124:127]
	v_mfma_i32_16x16x64_i8 v[96:99], v[92:95], v[216:219], v[96:99]
	v_mfma_i32_16x16x64_i8 v[96:99], v[100:103], v[220:223], v[96:99]
	s_barrier
	s_add_i32 s8, s84, s12
	v_lshl_add_u64 v[200:201], s[82:83], 0, v[178:179]
	s_mov_b32 m0, s8
	ds_read_b128 v[128:131], v215 offset:16384
	ds_read_b128 v[132:135], v215 offset:17408
	ds_read_b128 v[140:143], v215 offset:18432
	ds_read_b128 v[188:191], v215 offset:19456
	ds_read_b128 v[192:195], v215 offset:20480
	ds_read_b128 v[196:199], v215 offset:21504
	ds_read_b128 v[216:219], v215 offset:22528
	ds_read_b128 v[220:223], v215 offset:23552
	global_load_lds_dwordx4 v[200:201], off
	s_add_i32 m0, s8, 0x2000
	s_add_u32 s8, s82, 0x40000
	v_lshl_add_u64 v[206:207], s[82:83], 0, v[182:183]
	s_addc_u32 s9, s83, 0
	s_add_i32 s10, s10, s12
	global_load_lds_dwordx4 v[206:207], off
	v_lshl_add_u64 v[2:3], s[8:9], 0, v[178:179]
	s_mov_b32 m0, s10
	v_lshl_add_u64 v[210:211], vcc, 0, v[176:177]
	global_load_lds_dwordx4 v[2:3], off
	v_lshl_add_u64 v[2:3], s[8:9], 0, v[182:183]
	s_add_i32 m0, s10, 0x2000
	v_lshl_add_u64 v[224:225], vcc, 0, v[180:181]
	global_load_lds_dwordx4 v[2:3], off
	s_mov_b32 m0, s13
	s_nop 0
	global_load_lds_dwordx4 v[210:211], off
	s_mov_b32 m0, s66
	s_nop 0
	global_load_lds_dwordx4 v[224:225], off
	s_waitcnt vmcnt(8)
	s_waitcnt lgkmcnt(0)
	s_barrier
; #define PG8_STAGE(bufoff, gbase, voff) do { _Pragma("unroll") for (int _i = 0; _i < 2; ++_i) \
;         __builtin_amdgcn_global_load_lds((const unsigned*)((const char*)(gbase) + (voff)[_i]), (PG8_LAS unsigned*)(lds + (bufoff) + ldsw + _i * 8192), 16, 0, 0); } while (0)
; #define PG8_LDA(dst, b, h) do { _Pragma("unroll") for (int m = 0; m < 4; ++m) _Pragma("unroll") for (int k = 0; k < 2; ++k) dst[m][k] = *(const PG8_LAS bf16x8*)(lds + PG8_SA(b, h) + aoff + m * 2048 + k * 1024); } while (0)
; #define PG8_LDB(dst, b, h) do { _Pragma("unroll") for (int n = 0; n < 2; ++n) _Pragma("unroll") for (int k = 0; k < 2; ++k) dst[n][k] = *(const PG8_LAS bf16x8*)(lds + PG8_SB(b, h) + boff + n * 2048 + k * 1024); } while (0)
; #define PG8_MMA(ai, bj, At, Bt) do { __builtin_amdgcn_s_setprio(1); _Pragma("unroll") for (int m = 0; m < 4; ++m) _Pragma("unroll") for (int n = 0; n < 2; ++n) _Pragma("unroll") for (int k = 0; k < 2; ++k) \
;         acc[ai][bj][m][n] = mma16<Epi::I8>(Bt[n][k], At[m][k], acc[ai][bj][m][n]); __builtin_amdgcn_s_setprio(0); } while (0)
; #define PG8_WAIT_V(n) asm volatile("s_waitcnt vmcnt(" #n ")" ::: "memory")
; #define PG8_WAIT_L(n) asm volatile("s_waitcnt lgkmcnt(" #n ")" ::: "memory")
; #define PG8_BAR __builtin_amdgcn_s_barrier()
; #define PG8_SCHED __builtin_amdgcn_sched_barrier(0)
; template <class Epi, class Sched, bool ALIGN_EPI = false, bool SP2 = false>
; __device__ __forceinline__ void gemm_phase(PG8_LAS unsigned char* lds, const Gemm g, const Sched& S, const Epi& E) {
;     ...
;             PG8_WAIT_V(8); PG8_WAIT_L(0); PG8_BAR; PG8_MMA(1, 0, At, B0); PG8_MMA(1, 1, At, B1); PG8_BAR; PG8_SCHED;
;             PG8_LDB(B0, 1, 0); PG8_LDB(B1, 1, 1); PG8_SCHED; PG8_LDA(At, 1, 0); PG8_STAGE(PG8_SA(0, 1), a2 + hstep, voffA);
;             PG8_WAIT_V(8); PG8_WAIT_L(0); PG8_BAR; PG8_MMA(0, 0, At, B0); PG8_MMA(0, 1, At, B1); PG8_BAR; PG8_SCHED;
	s_waitcnt lgkmcnt(0)
	v_mfma_i32_16x16x64_i8 v[80:83], v[44:47], v[128:131], v[80:83]
	v_mfma_i32_16x16x64_i8 v[72:75], v[60:63], v[128:131], v[72:75]
	v_mfma_i32_16x16x64_i8 v[68:71], v[60:63], v[140:143], v[68:71]
	v_mfma_i32_16x16x64_i8 v[76:79], v[44:47], v[140:143], v[76:79]
	v_mfma_i32_16x16x64_i8 v[56:59], v[44:47], v[192:195], v[56:59]
	v_mfma_i32_16x16x64_i8 v[48:51], v[60:63], v[192:195], v[48:51]
	v_mfma_i32_16x16x64_i8 v[36:39], v[60:63], v[216:219], v[36:39]
	v_mfma_i32_16x16x64_i8 v[40:43], v[44:47], v[216:219], v[40:43]
	v_mfma_i32_16x16x64_i8 v[2:5], v[92:95], v[216:219], v[4:7]
	v_mfma_i32_16x16x64_i8 v[24:27], v[92:95], v[128:131], v[24:27]
	v_mfma_i32_16x16x64_i8 v[32:35], v[84:87], v[128:131], v[32:35]
	v_mfma_i32_16x16x64_i8 v[28:31], v[84:87], v[140:143], v[28:31]
	v_mfma_i32_16x16x64_i8 v[20:23], v[92:95], v[140:143], v[20:23]
	v_mfma_i32_16x16x64_i8 v[12:15], v[92:95], v[192:195], v[12:15]
	v_mfma_i32_16x16x64_i8 v[16:19], v[84:87], v[192:195], v[16:19]
	v_mfma_i32_16x16x64_i8 v[8:11], v[84:87], v[216:219], v[8:11]
	v_mfma_i32_16x16x64_i8 v[80:83], v[52:55], v[132:135], v[80:83]
	v_mfma_i32_16x16x64_i8 v[72:75], v[64:67], v[132:135], v[72:75]
	v_mfma_i32_16x16x64_i8 v[68:71], v[64:67], v[188:191], v[68:71]
	v_mfma_i32_16x16x64_i8 v[76:79], v[52:55], v[188:191], v[76:79]
	v_mfma_i32_16x16x64_i8 v[56:59], v[52:55], v[196:199], v[56:59]
	v_mfma_i32_16x16x64_i8 v[48:51], v[64:67], v[196:199], v[48:51]
	v_mfma_i32_16x16x64_i8 v[36:39], v[64:67], v[220:223], v[36:39]
	v_mfma_i32_16x16x64_i8 v[40:43], v[52:55], v[220:223], v[40:43]
	v_mfma_i32_16x16x64_i8 v[2:5], v[100:103], v[220:223], v[2:5]
	v_mfma_i32_16x16x64_i8 v[24:27], v[100:103], v[132:135], v[24:27]
	v_mfma_i32_16x16x64_i8 v[32:35], v[88:91], v[132:135], v[32:35]
	v_mfma_i32_16x16x64_i8 v[28:31], v[88:91], v[188:191], v[28:31]
	v_mfma_i32_16x16x64_i8 v[20:23], v[100:103], v[188:191], v[20:23]
	v_mfma_i32_16x16x64_i8 v[12:15], v[100:103], v[196:199], v[12:15]
	v_mfma_i32_16x16x64_i8 v[16:19], v[88:91], v[196:199], v[16:19]
	v_mfma_i32_16x16x64_i8 v[8:11], v[88:91], v[220:223], v[8:11]
	s_barrier
	s_add_i32 s10, 0, 0x18000
	v_add_u32_e32 v0, s10, v214
	s_add_i32 s11, 0, 0x1c000
	ds_read_b128 v[44:47], v0
	ds_read_b128 v[52:55], v0 offset:1024
	ds_read_b128 v[60:63], v0 offset:2048
	ds_read_b128 v[64:67], v0 offset:3072
	v_add_u32_e32 v0, s11, v214
	ds_read_b128 v[84:87], v0
	ds_read_b128 v[88:91], v0 offset:1024
	ds_read_b128 v[92:95], v0 offset:2048
	ds_read_b128 v[100:103], v0 offset:3072
	s_add_u32 s8, vcc_lo, 0x40000
	s_addc_u32 s9, vcc_hi, 0
	s_mov_b32 m0, s67
	v_lshl_add_u64 v[6:7], s[8:9], 0, v[176:177]
	ds_read_b128 v[128:131], v215 offset:32768
	ds_read_b128 v[132:135], v215 offset:33792
	ds_read_b128 v[140:143], v215 offset:34816
	ds_read_b128 v[188:191], v215 offset:35840
	ds_read_b128 v[192:195], v215 offset:36864
	ds_read_b128 v[196:199], v215 offset:37888
	ds_read_b128 v[216:219], v215 offset:38912
	ds_read_b128 v[220:223], v215 offset:39936
	global_load_lds_dwordx4 v[6:7], off
	v_lshl_add_u64 v[6:7], s[8:9], 0, v[180:181]
	s_mov_b32 m0, s80
	s_nop 0
	global_load_lds_dwordx4 v[6:7], off
	s_waitcnt vmcnt(8)
	s_waitcnt lgkmcnt(0)
	s_barrier
	s_waitcnt lgkmcnt(0)
	v_mfma_i32_16x16x64_i8 v[172:175], v[44:47], v[128:131], v[172:175]
	v_mfma_i32_16x16x64_i8 v[164:167], v[60:63], v[128:131], v[164:167]
	v_mfma_i32_16x16x64_i8 v[160:163], v[60:63], v[140:143], v[160:163]
	v_mfma_i32_16x16x64_i8 v[168:171], v[44:47], v[140:143], v[168:171]
	v_mfma_i32_16x16x64_i8 v[156:159], v[44:47], v[192:195], v[156:159]
	v_mfma_i32_16x16x64_i8 v[152:155], v[60:63], v[192:195], v[152:155]
	v_mfma_i32_16x16x64_i8 v[144:147], v[60:63], v[216:219], v[144:147]
	v_mfma_i32_16x16x64_i8 v[148:151], v[44:47], v[216:219], v[148:151]
	v_mfma_i32_16x16x64_i8 v[96:99], v[92:95], v[216:219], v[96:99]
	v_mfma_i32_16x16x64_i8 v[120:123], v[92:95], v[128:131], v[120:123]
	v_mfma_i32_16x16x64_i8 v[136:139], v[84:87], v[128:131], v[136:139]
	v_mfma_i32_16x16x64_i8 v[124:127], v[84:87], v[140:143], v[124:127]
	v_mfma_i32_16x16x64_i8 v[116:119], v[92:95], v[140:143], v[116:119]
	v_mfma_i32_16x16x64_i8 v[108:111], v[92:95], v[192:195], v[108:111]
	v_mfma_i32_16x16x64_i8 v[112:115], v[84:87], v[192:195], v[112:115]
	v_mfma_i32_16x16x64_i8 v[104:107], v[84:87], v[216:219], v[104:107]
	v_mfma_i32_16x16x64_i8 v[172:175], v[52:55], v[132:135], v[172:175]
	v_mfma_i32_16x16x64_i8 v[164:167], v[64:67], v[132:135], v[164:167]
	v_mfma_i32_16x16x64_i8 v[160:163], v[64:67], v[188:191], v[160:163]
	v_mfma_i32_16x16x64_i8 v[168:171], v[52:55], v[188:191], v[168:171]
	v_mfma_i32_16x16x64_i8 v[156:159], v[52:55], v[196:199], v[156:159]
	v_mfma_i32_16x16x64_i8 v[152:155], v[64:67], v[196:199], v[152:155]
	v_mfma_i32_16x16x64_i8 v[144:147], v[64:67], v[220:223], v[144:147]
	v_mfma_i32_16x16x64_i8 v[148:151], v[52:55], v[220:223], v[148:151]
	v_mfma_i32_16x16x64_i8 v[96:99], v[100:103], v[220:223], v[96:99]
	v_mfma_i32_16x16x64_i8 v[120:123], v[100:103], v[132:135], v[120:123]
	v_mfma_i32_16x16x64_i8 v[136:139], v[88:91], v[132:135], v[136:139]
	v_mfma_i32_16x16x64_i8 v[132:135], v[88:91], v[188:191], v[124:127]
	v_mfma_i32_16x16x64_i8 v[116:119], v[100:103], v[188:191], v[116:119]
	v_mfma_i32_16x16x64_i8 v[108:111], v[100:103], v[196:199], v[108:111]
	v_mfma_i32_16x16x64_i8 v[112:115], v[88:91], v[196:199], v[112:115]
	v_mfma_i32_16x16x64_i8 v[104:107], v[88:91], v[220:223], v[104:107]
	s_barrier
; #define PG8_STAGE(bufoff, gbase, voff) do { _Pragma("unroll") for (int _i = 0; _i < 2; ++_i) \
;         __builtin_amdgcn_global_load_lds((const unsigned*)((const char*)(gbase) + (voff)[_i]), (PG8_LAS unsigned*)(lds + (bufoff) + ldsw + _i * 8192), 16, 0, 0); } while (0)
; #define PG8_LDA(dst, b, h) do { _Pragma("unroll") for (int m = 0; m < 4; ++m) _Pragma("unroll") for (int k = 0; k < 2; ++k) dst[m][k] = *(const PG8_LAS bf16x8*)(lds + PG8_SA(b, h) + aoff + m * 2048 + k * 1024); } while (0)
; #define PG8_MMA(ai, bj, At, Bt) do { __builtin_amdgcn_s_setprio(1); _Pragma("unroll") for (int m = 0; m < 4; ++m) _Pragma("unroll") for (int n = 0; n < 2; ++n) _Pragma("unroll") for (int k = 0; k < 2; ++k) \
;         acc[ai][bj][m][n] = mma16<Epi::I8>(Bt[n][k], At[m][k], acc[ai][bj][m][n]); __builtin_amdgcn_s_setprio(0); } while (0)
; #define PG8_WAIT_V(n) asm volatile("s_waitcnt vmcnt(" #n ")" ::: "memory")
; #define PG8_WAIT_L(n) asm volatile("s_waitcnt lgkmcnt(" #n ")" ::: "memory")
; #define PG8_BAR __builtin_amdgcn_s_barrier()
; #define PG8_SCHED __builtin_amdgcn_sched_barrier(0)
; template <class Epi, class Sched, bool ALIGN_EPI = false, bool SP2 = false>
; __device__ __forceinline__ void gemm_phase(PG8_LAS unsigned char* lds, const Gemm g, const Sched& S, const Epi& E) {
;     ...
;             PG8_LDA(At, 1, 1); PG8_STAGE(PG8_SB(1, 0), b3, voffB); PG8_STAGE(PG8_SB(1, 1), b3 + hstep, voffB); PG8_STAGE(PG8_SA(1, 0), a3, voffA);
;             PG8_WAIT_V(8); PG8_WAIT_L(0); PG8_BAR; PG8_MMA(1, 0, At, B0); PG8_MMA(1, 1, At, B1); PG8_BAR; PG8_SCHED;
	s_add_i32 s8, s10, s12
	v_lshl_add_u64 v[6:7], v[200:201], 0, s[92:93]
	s_mov_b32 m0, s8
	ds_read_b128 v[124:127], v215 offset:49152
	ds_read_b128 v[128:131], v215 offset:50176
	ds_read_b128 v[140:143], v215 offset:51200
	ds_read_b128 v[188:191], v215 offset:52224
	ds_read_b128 v[192:195], v215 offset:53248
	ds_read_b128 v[196:199], v215 offset:54272
	ds_read_b128 v[216:219], v215 offset:55296
	ds_read_b128 v[220:223], v215 offset:56320
	global_load_lds_dwordx4 v[6:7], off
	s_add_i32 m0, s8, 0x2000
	s_add_u32 s8, s82, 0x40080
	v_lshl_add_u64 v[6:7], v[206:207], 0, s[92:93]
	s_addc_u32 s9, s83, 0
	s_add_i32 s10, s11, s12
	global_load_lds_dwordx4 v[6:7], off
	v_lshl_add_u64 v[6:7], s[8:9], 0, v[178:179]
	s_mov_b32 m0, s10
	s_nop 0
	global_load_lds_dwordx4 v[6:7], off
	v_lshl_add_u64 v[6:7], s[8:9], 0, v[182:183]
	s_add_i32 m0, s10, 0x2000
	s_nop 0
	global_load_lds_dwordx4 v[6:7], off
	v_lshl_add_u64 v[6:7], v[210:211], 0, s[92:93]
	s_mov_b32 m0, s58
	s_nop 0
	global_load_lds_dwordx4 v[6:7], off
	v_lshl_add_u64 v[6:7], v[224:225], 0, s[92:93]
	s_mov_b32 m0, s4
	s_nop 0
	global_load_lds_dwordx4 v[6:7], off
	s_waitcnt vmcnt(8)
	s_waitcnt lgkmcnt(0)
	s_barrier
	s_waitcnt lgkmcnt(0)
	v_mfma_i32_16x16x64_i8 v[80:83], v[44:47], v[124:127], v[80:83]
	v_mfma_i32_16x16x64_i8 v[72:75], v[60:63], v[124:127], v[72:75]
	v_mfma_i32_16x16x64_i8 v[68:71], v[60:63], v[140:143], v[68:71]
	v_mfma_i32_16x16x64_i8 v[76:79], v[44:47], v[140:143], v[76:79]
	v_mfma_i32_16x16x64_i8 v[56:59], v[44:47], v[192:195], v[56:59]
	v_mfma_i32_16x16x64_i8 v[48:51], v[60:63], v[192:195], v[48:51]
	v_mfma_i32_16x16x64_i8 v[36:39], v[60:63], v[216:219], v[36:39]
	v_mfma_i32_16x16x64_i8 v[40:43], v[44:47], v[216:219], v[40:43]
	v_mfma_i32_16x16x64_i8 v[2:5], v[92:95], v[216:219], v[2:5]
	v_mfma_i32_16x16x64_i8 v[24:27], v[92:95], v[124:127], v[24:27]
	v_mfma_i32_16x16x64_i8 v[32:35], v[84:87], v[124:127], v[32:35]
	v_mfma_i32_16x16x64_i8 v[28:31], v[84:87], v[140:143], v[28:31]
	v_mfma_i32_16x16x64_i8 v[20:23], v[92:95], v[140:143], v[20:23]
	v_mfma_i32_16x16x64_i8 v[12:15], v[92:95], v[192:195], v[12:15]
	v_mfma_i32_16x16x64_i8 v[16:19], v[84:87], v[192:195], v[16:19]
	v_mfma_i32_16x16x64_i8 v[6:9], v[84:87], v[216:219], v[8:11]
	v_mfma_i32_16x16x64_i8 v[80:83], v[52:55], v[128:131], v[80:83]
	v_mfma_i32_16x16x64_i8 v[72:75], v[64:67], v[128:131], v[72:75]
	v_mfma_i32_16x16x64_i8 v[68:71], v[64:67], v[188:191], v[68:71]
	v_mfma_i32_16x16x64_i8 v[76:79], v[52:55], v[188:191], v[76:79]
	v_mfma_i32_16x16x64_i8 v[56:59], v[52:55], v[196:199], v[56:59]
	v_mfma_i32_16x16x64_i8 v[48:51], v[64:67], v[196:199], v[48:51]
	v_mfma_i32_16x16x64_i8 v[36:39], v[64:67], v[220:223], v[36:39]
	v_mfma_i32_16x16x64_i8 v[40:43], v[52:55], v[220:223], v[40:43]
	v_mfma_i32_16x16x64_i8 v[8:11], v[88:91], v[220:223], v[6:9]
	v_mfma_i32_16x16x64_i8 v[32:35], v[88:91], v[128:131], v[32:35]
	v_mfma_i32_16x16x64_i8 v[24:27], v[100:103], v[128:131], v[24:27]
	v_mfma_i32_16x16x64_i8 v[20:23], v[100:103], v[188:191], v[20:23]
	v_mfma_i32_16x16x64_i8 v[28:31], v[88:91], v[188:191], v[28:31]
	v_mfma_i32_16x16x64_i8 v[16:19], v[88:91], v[196:199], v[16:19]
	v_mfma_i32_16x16x64_i8 v[12:15], v[100:103], v[196:199], v[12:15]
	v_mfma_i32_16x16x64_i8 v[4:7], v[100:103], v[220:223], v[2:5]
	s_barrier
	s_add_i32 s5, s5, 2
	s_add_u32 s85, s85, 0x100
	s_addc_u32 s68, s68, 0
	s_cmp_gt_u32 s5, 13
	s_mov_b64 s[8:9], s[70:71]
	s_cbranch_scc0 .LBB0_385
